# O3 L1 + E3 L2: swapped-MFMA layout, coalesced bf16 residual loads/stores, DPP row-sum reduction (on top of v25)
# speedup vs baseline: 1.0098x; 1.0098x over previous
; #define PG8_STAGE(bufoff, gbase, voff) do { _Pragma("unroll") for (int _i = 0; _i < 2; ++_i) \
;         __builtin_amdgcn_global_load_lds((const unsigned*)((const char*)(gbase) + (voff)[_i]), (LAS unsigned*)(lds + (bufoff) + ldsw + _i * 8192), 16, 0, 0); } while (0)
; #define PG8_WAIT_V(n) asm volatile("s_waitcnt vmcnt(" #n ")" ::: "memory")
; #define PG8_BAR __builtin_amdgcn_s_barrier()
; template <class Epi, class Sched>
; __device__ __forceinline__ void gemm_phase(LAS unsigned char* lds, const int K, const int lda, const int ldb, const Sched& S, const Epi& E) {
;     ...
;     const int wid = __builtin_amdgcn_readfirstlane(tid >> 6), lane = tid & 63, wr = wid >> 2, wc = wid & 3, fr = lane & 15, fq = lane >> 4;
;     const int nt = K / BK;
;     unsigned voffA[2], voffB[2];
; #pragma unroll
;     for (int i = 0; i < 2; ++i) { int R, C; stage_rc(tid * 16 + i * 8192, R, C); const int Rb = (R & ~31) + perm32(R & 31);
;         voffA[i] = (unsigned)(R * lda + C) * 2u; voffB[i] = (unsigned)(Rb * ldb + C) * 2u; }
;     const size_t kstep = (size_t)(BK * 2);
;     const size_t hA = (size_t)HALF * lda * 2, hB = (size_t)HALF * ldb * 2;
;     const unsigned ldsw = (unsigned)wid * 1024u;
;     const int aoff = lds_byte(wr * 64 + fr, fq * 8), boff = lds_byte(wc * 32 + fr, fq * 8);
;     ...
;     Unit cur, nxt; int ui = 0;
;     if (!S.next(0, cur)) return;
;     f32x4 acc[2][2][4][2];
; #pragma unroll
;     for (int a = 0; a < 2; ++a)
; #pragma unroll
;         for (int b = 0; b < 2; ++b)
; #pragma unroll
;             for (int m = 0; m < 4; ++m)
; #pragma unroll
;                 for (int n = 0; n < 2; ++n) acc[a][b][m][n] = (f32x4){0.f, 0.f, 0.f, 0.f};
;     bf16x8 At[4][2], B0[2][2], B1[2][2];
;     const char* cA = S.aptr(cur); const char* cB = S.bptr(cur);
;     PG8_STAGE(PG8_SB(0, 0), cB, voffB); PG8_STAGE(PG8_SB(0, 1), cB + hB, voffB); PG8_STAGE(PG8_SA(0, 0), cA, voffA); PG8_STAGE(PG8_SA(0, 1), cA + hA, voffA);
;     if (wr == 1) PG8_BAR;
;     PG8_WAIT_V(2); PG8_BAR;
;     PG8_STAGE(PG8_SB(1, 0), cB + kstep, voffB); PG8_STAGE(PG8_SA(1, 0), cA + kstep, voffA); PG8_STAGE(PG8_SB(1, 1), cB + hB + kstep, voffB);
;     PG8_WAIT_V(6); PG8_BAR;
.LBB0_876:
	v_readlane_b32 s4, v255, 24
	v_readlane_b32 s5, v255, 25
	s_and_b64 vcc, exec, s[4:5]
	s_cbranch_vccnz .LBB0_914
	v_ashrrev_i32_e32 v1, 31, v8
	v_lshrrev_b32_e32 v1, 26, v1
	v_add_u32_e32 v1, v8, v1
	v_ashrrev_i32_e32 v9, 6, v1
	v_bfe_i32 v1, v8, 27, 1
	v_lshlrev_b32_e32 v0, 4, v8
	v_lshrrev_b32_e32 v1, 22, v1
	v_add_u32_e32 v1, v0, v1
	v_and_b32_e32 v1, 0xfffffc00, v1
	v_sub_u32_e32 v1, v0, v1
	v_lshrrev_b32_e32 v2, 4, v1
	v_bitop3_b32 v1, v2, v1, 32 bitop3:0x6c
	v_ashrrev_i32_e32 v3, 31, v1
	v_lshrrev_b32_e32 v3, 26, v3
	v_add_u32_e32 v3, v1, v3
	v_lshlrev_b32_e32 v2, 3, v9
	v_ashrrev_i32_e32 v10, 6, v3
	v_and_b32_e32 v3, 0xc0, v3
	v_and_b32_e32 v2, -16, v2
	v_sub_u32_e32 v1, v1, v3
	v_mov_b32_e32 v3, 1
	v_add_u32_e32 v2, v10, v2
	v_ashrrev_i16_sdwa v1, v3, sext(v1) dst_sel:DWORD dst_unused:UNUSED_PAD src0_sel:DWORD src1_sel:BYTE_0
	v_lshlrev_b32_e32 v4, 5, v9
	v_bfe_i32 v11, v1, 0, 16
	v_lshlrev_b32_e32 v1, 1, v2
	v_lshrrev_b32_e32 v5, 2, v2
	v_and_b32_e32 v6, 3, v10
	s_mov_b32 s1, 0xfffe0
	v_and_b32_e32 v4, 32, v4
	v_and_b32_e32 v1, 24, v1
	v_and_b32_e32 v5, 4, v5
	v_and_or_b32 v6, v2, s1, v6
	v_or3_b32 v1, v6, v5, v1
	v_add_lshl_u32 v4, v4, v11, 1
	v_add_u32_e32 v0, 0x2000, v0
	v_and_b32_e32 v106, 63, v254
	v_lshrrev_b32_e32 v107, 6, v254
	v_lshrrev_b32_e32 v108, 3, v106
	v_lshl_add_u32 v109, v107, 3, v108
	v_and_b32_e32 v110, 1, v107
	v_bfe_u32 v111, v106, 4, 2
	v_lshl_add_u32 v111, v110, 2, v111
	v_and_b32_e32 v101, 7, v106
	v_xor_b32_e32 v111, v101, v111
	v_lshlrev_b32_e32 v111, 4, v111
	v_lshl_add_u32 v100, v109, 12, v111
	v_add_u32_e32 v101, 0x40000, v100
	v_lshrrev_b32_e32 v109, 5, v106
	v_lshlrev_b32_e32 v109, 3, v109
	v_lshl_add_u32 v109, v110, 4, v109
	v_bfe_u32 v110, v107, 1, 1
	v_lshl_add_u32 v109, v110, 2, v109
	v_and_b32_e32 v110, 3, v108
	v_add_u32_e32 v109, v109, v110
	v_lshrrev_b32_e32 v110, 2, v107
	v_lshl_add_u32 v109, v110, 5, v109
	v_lshl_add_u32 v102, v109, 12, v111
	v_add_u32_e32 v103, 0x40000, v102
	v_and_b32_e32 v106, 15, v254
	v_bfe_u32 v108, v254, 4, 2
	v_bfe_u32 v109, v254, 1, 3
	v_xor_b32_e32 v108, v108, v109
	v_lshlrev_b32_e32 v108, 4, v108
	v_lshl_add_u32 v108, v106, 7, v108
	v_lshrrev_b32_e32 v109, 8, v254
	v_lshl_add_u32 v104, v109, 13, v108
	v_and_b32_e32 v109, 3, v107
	v_lshl_add_u32 v105, v109, 13, v108
	v_and_b32_e32 v106, 63, v254
	v_lshrrev_b32_e32 v107, 6, v254
	v_lshrrev_b32_e32 v108, 3, v106
	v_and_b32_e32 v110, 1, v107
	v_bfe_u32 v111, v106, 4, 2
	v_lshl_add_u32 v111, v110, 2, v111
	v_and_b32_e32 v109, 7, v106
	v_xor_b32_e32 v111, v109, v111
	v_lshlrev_b32_e32 v111, 4, v111
	v_lshlrev_b32_e32 v109, 5, v110
	v_lshl_add_u32 v109, v108, 2, v109
	v_bfe_u32 v110, v107, 1, 2
	v_add_u32_e32 v109, v109, v110
	v_lshl_add_u32 v102, v109, 12, v111
	v_add_u32_e32 v103, 0x40000, v102
	v_mov_b32_e32 v186, v102
	v_ashrrev_i32_e32 v1, 31, v0
	v_lshrrev_b32_e32 v1, 22, v1
	v_add_u32_e32 v1, v0, v1
	v_ashrrev_i32_e32 v12, 10, v1
	v_mul_i32_i24_e32 v1, 0x400, v12
	v_sub_u32_e32 v0, v0, v1
	v_lshrrev_b32_e32 v1, 4, v0
	v_bitop3_b32 v0, v1, v0, 32 bitop3:0x6c
	v_mov_b32_e32 v184, v100
	v_ashrrev_i32_e32 v2, 31, v0
	v_lshrrev_b32_e32 v2, 26, v2
	v_add_u32_e32 v2, v0, v2
	v_lshlrev_b32_e32 v1, 3, v12
	v_ashrrev_i32_e32 v13, 6, v2
	v_and_b32_e32 v2, 0xc0, v2
	v_and_b32_e32 v1, -16, v1
	v_sub_u32_e32 v0, v0, v2
	s_ashr_i32 s8, s0, 6
	v_add_u32_e32 v1, v13, v1
	v_ashrrev_i16_sdwa v0, v3, sext(v0) dst_sel:DWORD dst_unused:UNUSED_PAD src0_sel:DWORD src1_sel:BYTE_0
	v_and_b32_e32 v3, 3, v13
	s_ashr_i32 s65, s64, 31
	s_ashr_i32 s49, s48, 31
	v_and_or_b32 v3, v1, s1, v3
	s_ashr_i32 s9, s0, 8
	s_lshl_b32 s1, s8, 10
	s_lshl_b64 s[4:5], s[64:65], 20
	s_lshl_b64 s[6:7], s[48:49], 20
	s_add_u32 s66, s36, s6
	v_lshlrev_b32_e32 v4, 5, v12
	v_bfe_i32 v14, v0, 0, 16
	v_lshlrev_b32_e32 v0, 1, v1
	v_lshrrev_b32_e32 v2, 2, v1
	s_addc_u32 s67, s37, s7
	s_add_i32 s2, s1, 0
	v_and_b32_e32 v4, 32, v4
	v_and_b32_e32 v0, 24, v0
	v_and_b32_e32 v2, 4, v2
	s_add_i32 m0, s2, 0x10000
	v_or3_b32 v0, v3, v2, v0
	v_add_lshl_u32 v2, v4, v14, 1
	global_load_lds_dwordx4 v186, s[66:67]
	s_add_i32 m0, s2, 0x12000
	v_mov_b32_e32 v190, v103
	s_add_u32 s6, s66, 0x80000
	global_load_lds_dwordx4 v190, s[66:67]
	s_addc_u32 s7, s67, 0
	s_add_i32 m0, s2, 0x14000
	v_mov_b32_e32 v188, v101
	global_load_lds_dwordx4 v186, s[6:7]
	s_add_i32 m0, s2, 0x16000
	s_add_u32 s68, s46, s4
	s_addc_u32 s69, s47, s5
	s_add_i32 s4, s2, 0x2000
	global_load_lds_dwordx4 v190, s[6:7]
	s_mov_b32 m0, s2
	s_add_u32 s10, s68, 0x80000
	global_load_lds_dwordx4 v184, s[68:69]
	s_mov_b32 m0, s4
	s_addc_u32 s11, s69, 0
	s_add_i32 s5, s2, 0x4000
	global_load_lds_dwordx4 v188, s[68:69]
	s_mov_b32 m0, s5
	s_add_i32 s6, s2, 0x6000
	global_load_lds_dwordx4 v184, s[10:11]
	s_mov_b32 m0, s6
	v_mov_b32_e32 v187, 0
	global_load_lds_dwordx4 v188, s[10:11]
	v_mov_b32_e32 v191, v187
	v_mov_b32_e32 v185, v187
	v_mov_b32_e32 v189, v187
	s_cmp_eq_u32 s9, 1
	s_mov_b32 s7, 0
	v_lshl_add_u64 v[6:7], s[66:67], 0, v[186:187]
	v_lshl_add_u64 v[4:5], s[66:67], 0, v[190:191]
	v_lshl_add_u64 v[0:1], s[68:69], 0, v[184:185]
	s_cselect_b64 s[50:51], -1, 0
	s_cmp_lg_u32 s9, 1
	v_lshl_add_u64 v[2:3], s[68:69], 0, v[188:189]
	s_cbranch_scc1 .LBB0_879
	s_barrier
; #define LAS __attribute__((address_space(3)))
; #define LDS_WAIT() asm volatile("s_waitcnt lgkmcnt(0)" ::: "memory")
; #define PG8_STAGE(bufoff, gbase, voff) do { _Pragma("unroll") for (int _i = 0; _i < 2; ++_i) \
;         __builtin_amdgcn_global_load_lds((const unsigned*)((const char*)(gbase) + (voff)[_i]), (LAS unsigned*)(lds + (bufoff) + ldsw + _i * 8192), 16, 0, 0); } while (0)
; #define PG8_WAIT_V(n) asm volatile("s_waitcnt vmcnt(" #n ")" ::: "memory")
; #define PG8_BAR __builtin_amdgcn_s_barrier()
; template <class Epi, class Sched>
; __device__ __forceinline__ void gemm_phase(LAS unsigned char* lds, const int K, const int lda, const int ldb, const Sched& S, const Epi& E) {
;     ...
;     PG8_STAGE(PG8_SB(0, 0), cB, voffB); PG8_STAGE(PG8_SB(0, 1), cB + hB, voffB); PG8_STAGE(PG8_SA(0, 0), cA, voffA); PG8_STAGE(PG8_SA(0, 1), cA + hA, voffA);
;     if (wr == 1) PG8_BAR;
;     PG8_WAIT_V(2); PG8_BAR;
;     PG8_STAGE(PG8_SB(1, 0), cB + kstep, voffB); PG8_STAGE(PG8_SA(1, 0), cA + kstep, voffA); PG8_STAGE(PG8_SB(1, 1), cB + hB + kstep, voffB);
;     PG8_WAIT_V(6); PG8_BAR;
;     for (;;) {
;     __device__ __forceinline__ void operator()(const f32x4 (&acc)[2][2][4][2], const Unit& u, int wr, int wc, int fr, int fq, LAS unsigned char* xs, int wid, int lane) const {
;     ...
;         if (!LAST) {
;             LDS_WAIT();
;             __builtin_amdgcn_s_barrier();
;             const int tid = wid * 64 + lane;
;             if (tid < 256) { const f32x4 v = *(const LAS f32x4*)(P + tid * 4); rss[(size_t)(u.pm * 256 + tid) * 8 + u.pn] = (v[0] + v[1]) + (v[2] + v[3]); }
;             LDS_WAIT();
.LBB0_879:
	s_mov_b64 s[52:53], 0x80
	s_and_b32 s8, s8, 3
	s_add_i32 m0, s2, 0x18000
	v_lshl_add_u64 v[6:7], v[6:7], 0, s[52:53]
	s_lshl_b32 s12, s9, 13
	s_lshl_b32 s13, s8, 12
	s_waitcnt vmcnt(2)
	s_barrier
	global_load_lds_dwordx4 v[6:7], off
	v_lshl_add_u64 v[4:5], v[4:5], 0, s[52:53]
	s_add_i32 m0, s2, 0x1a000
	s_add_i32 s14, s2, 0x8000
	s_add_i32 s15, s2, 0xa000
	global_load_lds_dwordx4 v[4:5], off
	v_lshl_add_u64 v[0:1], v[0:1], 0, s[52:53]
	s_mov_b32 m0, s14
	s_add_u32 s10, s66, 0x80080
	global_load_lds_dwordx4 v[0:1], off
	v_lshl_add_u64 v[0:1], v[2:3], 0, s[52:53]
	s_mov_b32 m0, s15
	s_addc_u32 s11, s67, 0
	global_load_lds_dwordx4 v[0:1], off
	s_add_i32 m0, s2, 0x1c000
	v_lshl_add_u64 v[0:1], s[10:11], 0, v[186:187]
	global_load_lds_dwordx4 v[0:1], off
	v_lshl_add_u64 v[0:1], s[10:11], 0, v[190:191]
	s_add_i32 m0, s2, 0x1e000
	v_lshrrev_b32_e32 v2, 1, v8
	global_load_lds_dwordx4 v[0:1], off
	v_and_b32_e32 v1, 15, v8
	v_and_b32_e32 v2, 24, v2
	v_and_b32_e32 v3, 48, v8
	v_lshl_or_b32 v216, s9, 6, v1
	v_lshl_or_b32 v1, v1, 6, v3
	v_lshlrev_b32_e32 v3, 2, v8
	v_lshl_or_b32 v218, s8, 5, v2
	v_lshlrev_b32_e32 v2, 15, v12
	v_and_b32_e32 v3, 32, v3
	v_and_b32_e32 v2, 0xffff0000, v2
	v_bitop3_b32 v4, v1, s12, v3 bitop3:0xde
	v_mov_b32_e32 v217, v105
	v_lshl_add_u32 v2, v13, 12, v2
	v_and_b32_e32 v3, 1, v12
	v_lshl_or_b32 v2, v3, 6, v2
	v_mov_b32_e32 v192, v101
	v_lshlrev_b32_e32 v2, 15, v9
	s_cmpk_lt_u32 s0, 0x100
	s_movk_i32 s11, 0xffc0
	v_mov_b32_e32 v1, s0
	v_and_b32_e32 v2, 0xffff0000, v2
	s_cselect_b64 s[54:55], -1, 0
	s_lshl_b32 s8, s8, 2
	v_bfi_b32 v219, s11, v1, v8
	v_lshl_add_u32 v2, v10, 12, v2
	v_and_b32_e32 v3, 1, v9
	v_and_b32_e32 v0, 63, v8
	s_waitcnt vmcnt(6)
	s_add_i32 s8, s8, 0
	v_lshlrev_b32_e32 v1, 4, v219
	v_lshl_or_b32 v2, v3, 6, v2
	s_movk_i32 s10, 0x100
	s_add_i32 s12, s8, 0x20000
	v_cmp_gt_u32_e64 s[8:9], 16, v0
	v_lshlrev_b32_e32 v0, 4, v216
	v_mov_b32_e32 v194, v100
	s_add_i32 s0, 0, 0x10000
	s_add_i32 s23, 0, 0x14000
	v_mbcnt_lo_u32_b32 v2, -1, 0
	v_add_u32_e32 v1, 0, v1
	v_cmp_gt_i32_e64 s[10:11], s10, v219
	s_ashr_i32 s17, s3, 31
	s_ashr_i32 s21, s33, 31
	v_mov_b32_e32 v193, v187
	v_mov_b32_e32 v195, v187
	v_mov_b64_e32 v[196:197], 0x400
	v_mov_b64_e32 v[198:199], 0x3ff
	v_add_u32_e32 v220, s0, v217
	v_add_u32_e32 v221, 0x11000, v217
	v_mov_b32_e32 v222, v104
	v_xor_b32_e32 v246, 64, v222
	v_xor_b32_e32 v247, 64, v220
	v_xor_b32_e32 v248, 64, v221
	v_xor_b32_e32 v249, 64, v217
	v_mbcnt_hi_u32_b32 v223, -1, v2
	v_add_u32_e32 v224, 0x20000, v1
	v_add_u32_e32 v225, s12, v0
	s_barrier
	s_branch .LBB0_882

; #define PG8_STAGE(bufoff, gbase, voff) do { _Pragma("unroll") for (int _i = 0; _i < 2; ++_i) \
;         __builtin_amdgcn_global_load_lds((const unsigned*)((const char*)(gbase) + (voff)[_i]), (LAS unsigned*)(lds + (bufoff) + ldsw + _i * 8192), 16, 0, 0); } while (0)
; #define PG8_LDA(dst, b, h) do { _Pragma("unroll") for (int m = 0; m < 4; ++m) _Pragma("unroll") for (int k = 0; k < 2; ++k) dst[m][k] = *(const LAS bf16x8*)(lds + PG8_SA(b, h) + aoff + m * 2048 + k * 1024); } while (0)
; #define PG8_LDB(dst, b, h) do { _Pragma("unroll") for (int n = 0; n < 2; ++n) _Pragma("unroll") for (int k = 0; k < 2; ++k) dst[n][k] = *(const LAS bf16x8*)(lds + PG8_SB(b, h) + boff + n * 2048 + k * 1024); } while (0)
; #define PG8_MMA(ai, bj, At, Bt) do { __builtin_amdgcn_s_setprio(1); _Pragma("unroll") for (int m = 0; m < 4; ++m) _Pragma("unroll") for (int n = 0; n < 2; ++n) _Pragma("unroll") for (int k = 0; k < 2; ++k) \
;         acc[ai][bj][m][n] = __builtin_amdgcn_mfma_f32_16x16x32_bf16(Bt[n][k], At[m][k], acc[ai][bj][m][n], 0, 0, 0); __builtin_amdgcn_s_setprio(0); } while (0)
; #define PG8_WAIT_V(n) asm volatile("s_waitcnt vmcnt(" #n ")" ::: "memory")
; #define PG8_WAIT_L(n) asm volatile("s_waitcnt lgkmcnt(" #n ")" ::: "memory")
; #define PG8_BAR __builtin_amdgcn_s_barrier()
; #define PG8_SCHED __builtin_amdgcn_sched_barrier(0)
; template <class Epi, class Sched>
; __device__ __forceinline__ void gemm_phase(LAS unsigned char* lds, const int K, const int lda, const int ldb, const Sched& S, const Epi& E) {
;     ...
;             PG8_LDB(B0, 0, 0); PG8_LDB(B1, 0, 1); PG8_SCHED; PG8_LDA(At, 0, 0); PG8_STAGE(PG8_SA(1, 1), a1 + hA, voffA);
;             PG8_WAIT_V(8); PG8_WAIT_L(0); PG8_BAR; PG8_MMA(0, 0, At, B0); PG8_MMA(0, 1, At, B1); PG8_BAR; PG8_SCHED;
;             PG8_LDA(At, 0, 1); PG8_STAGE(PG8_SB(0, 0), b2, voffB); PG8_STAGE(PG8_SB(0, 1), b2 + hB, voffB); PG8_STAGE(PG8_SA(0, 0), a2, voffA);
;             PG8_WAIT_V(8); PG8_WAIT_L(0); PG8_BAR; PG8_MMA(1, 0, At, B0); PG8_MMA(1, 1, At, B1); PG8_BAR; PG8_SCHED;
.LBB0_889:
	ds_read_b128 v[104:107], v220
	ds_read_b128 v[112:115], v247
	ds_read_b128 v[124:127], v220 offset:2048
	ds_read_b128 v[140:143], v247 offset:2048
	ds_read_b128 v[144:147], v221
	ds_read_b128 v[148:151], v248
	ds_read_b128 v[152:155], v221 offset:2048
	ds_read_b128 v[156:159], v248 offset:2048
	s_add_u32 s29, s66, 0xfff80080
	s_addc_u32 s30, s67, -1
	s_cmp_eq_u32 s28, 28
	s_cselect_b32 s71, s18, s30
	s_cselect_b32 s70, s19, s29
	s_cselect_b32 s69, s24, s27
	s_cselect_b32 s68, s25, s26
	v_lshl_add_u64 v[208:209], s[66:67], 0, v[194:195]
	s_add_i32 m0, s2, 0xc000
	ds_read_b128 v[160:163], v222
	ds_read_b128 v[164:167], v246
	ds_read_b128 v[168:171], v222 offset:2048
	ds_read_b128 v[172:175], v246 offset:2048
	ds_read_b128 v[176:179], v222 offset:4096
	ds_read_b128 v[180:183], v246 offset:4096
	ds_read_b128 v[200:203], v222 offset:6144
	ds_read_b128 v[204:207], v246 offset:6144
	global_load_lds_dwordx4 v[208:209], off
	v_lshl_add_u64 v[208:209], s[66:67], 0, v[192:193]
	s_add_i32 m0, s2, 0xe000
	s_nop 0
	global_load_lds_dwordx4 v[208:209], off
	s_waitcnt vmcnt(8)
	s_waitcnt lgkmcnt(0)
	s_barrier
	s_setprio 1
	s_waitcnt lgkmcnt(0)
	v_mfma_f32_16x16x32_bf16 v[136:139], v[160:163], v[104:107], v[136:139]
	v_mfma_f32_16x16x32_bf16 v[132:135], v[160:163], v[124:127], v[132:135]
	v_mfma_f32_16x16x32_bf16 v[116:119], v[168:171], v[104:107], v[116:119]
	v_mfma_f32_16x16x32_bf16 v[108:111], v[168:171], v[124:127], v[108:111]
	v_mfma_f32_16x16x32_bf16 v[92:95], v[176:179], v[104:107], v[92:95]
	v_mfma_f32_16x16x32_bf16 v[88:91], v[176:179], v[124:127], v[88:91]
	v_mfma_f32_16x16x32_bf16 v[76:79], v[200:203], v[104:107], v[76:79]
	v_mfma_f32_16x16x32_bf16 v[72:75], v[200:203], v[124:127], v[72:75]
	v_mfma_f32_16x16x32_bf16 v[136:139], v[164:167], v[112:115], v[136:139]
	v_mfma_f32_16x16x32_bf16 v[132:135], v[164:167], v[140:143], v[132:135]
	v_mfma_f32_16x16x32_bf16 v[116:119], v[172:175], v[112:115], v[116:119]
	v_mfma_f32_16x16x32_bf16 v[108:111], v[172:175], v[140:143], v[108:111]
	v_mfma_f32_16x16x32_bf16 v[92:95], v[180:183], v[112:115], v[92:95]
	v_mfma_f32_16x16x32_bf16 v[88:91], v[180:183], v[140:143], v[88:91]
	v_mfma_f32_16x16x32_bf16 v[76:79], v[204:207], v[112:115], v[76:79]
	v_mfma_f32_16x16x32_bf16 v[72:75], v[204:207], v[140:143], v[72:75]
	s_setprio 0
	s_setprio 1
	v_mfma_f32_16x16x32_bf16 v[128:131], v[160:163], v[144:147], v[128:131]
	v_mfma_f32_16x16x32_bf16 v[120:123], v[160:163], v[152:155], v[120:123]
	v_mfma_f32_16x16x32_bf16 v[100:103], v[168:171], v[144:147], v[100:103]
	v_mfma_f32_16x16x32_bf16 v[96:99], v[168:171], v[152:155], v[96:99]
	v_mfma_f32_16x16x32_bf16 v[84:87], v[176:179], v[144:147], v[84:87]
	v_mfma_f32_16x16x32_bf16 v[80:83], v[176:179], v[152:155], v[80:83]
	v_mfma_f32_16x16x32_bf16 v[68:71], v[200:203], v[144:147], v[68:71]
	v_mfma_f32_16x16x32_bf16 v[64:67], v[200:203], v[152:155], v[64:67]
	v_mfma_f32_16x16x32_bf16 v[128:131], v[164:167], v[148:151], v[128:131]
	v_mfma_f32_16x16x32_bf16 v[120:123], v[164:167], v[156:159], v[120:123]
	v_mfma_f32_16x16x32_bf16 v[100:103], v[172:175], v[148:151], v[100:103]
	v_mfma_f32_16x16x32_bf16 v[96:99], v[172:175], v[156:159], v[96:99]
	v_mfma_f32_16x16x32_bf16 v[84:87], v[180:183], v[148:151], v[84:87]
	v_mfma_f32_16x16x32_bf16 v[80:83], v[180:183], v[156:159], v[80:83]
	v_mfma_f32_16x16x32_bf16 v[68:71], v[204:207], v[148:151], v[68:71]
	v_mfma_f32_16x16x32_bf16 v[64:67], v[204:207], v[156:159], v[64:67]
	s_setprio 0
	s_barrier
	s_add_i32 s29, s0, s1
	v_lshl_add_u64 v[208:209], s[68:69], 0, v[186:187]
	s_mov_b32 m0, s29
	ds_read_b128 v[160:163], v222 offset:16384
	ds_read_b128 v[164:167], v246 offset:16384
	ds_read_b128 v[168:171], v222 offset:18432
	ds_read_b128 v[172:175], v246 offset:18432
	ds_read_b128 v[176:179], v222 offset:20480
	ds_read_b128 v[180:183], v246 offset:20480
	ds_read_b128 v[200:203], v222 offset:22528
	ds_read_b128 v[204:207], v246 offset:22528
	global_load_lds_dwordx4 v[208:209], off
	s_add_i32 m0, s29, 0x2000
	s_add_u32 s30, s68, 0x80000
	v_lshl_add_u64 v[210:211], s[68:69], 0, v[190:191]
	s_addc_u32 s31, s69, 0
	s_add_i32 s29, s23, s1
	global_load_lds_dwordx4 v[210:211], off
	v_lshl_add_u64 v[212:213], s[30:31], 0, v[186:187]
	s_mov_b32 m0, s29
	v_lshl_add_u64 v[214:215], s[70:71], 0, v[188:189]
	global_load_lds_dwordx4 v[212:213], off
	v_lshl_add_u64 v[212:213], s[30:31], 0, v[190:191]
	s_add_i32 m0, s29, 0x2000
	s_nop 0
	global_load_lds_dwordx4 v[212:213], off
	v_lshl_add_u64 v[212:213], s[70:71], 0, v[184:185]
	s_mov_b32 m0, s2
	s_nop 0
	global_load_lds_dwordx4 v[212:213], off
	s_mov_b32 m0, s4
	s_nop 0
	global_load_lds_dwordx4 v[214:215], off
	s_waitcnt vmcnt(8)
	s_waitcnt lgkmcnt(0)
	s_barrier
; #define PG8_STAGE(bufoff, gbase, voff) do { _Pragma("unroll") for (int _i = 0; _i < 2; ++_i) \
;         __builtin_amdgcn_global_load_lds((const unsigned*)((const char*)(gbase) + (voff)[_i]), (LAS unsigned*)(lds + (bufoff) + ldsw + _i * 8192), 16, 0, 0); } while (0)
; #define PG8_LDA(dst, b, h) do { _Pragma("unroll") for (int m = 0; m < 4; ++m) _Pragma("unroll") for (int k = 0; k < 2; ++k) dst[m][k] = *(const LAS bf16x8*)(lds + PG8_SA(b, h) + aoff + m * 2048 + k * 1024); } while (0)
; #define PG8_LDB(dst, b, h) do { _Pragma("unroll") for (int n = 0; n < 2; ++n) _Pragma("unroll") for (int k = 0; k < 2; ++k) dst[n][k] = *(const LAS bf16x8*)(lds + PG8_SB(b, h) + boff + n * 2048 + k * 1024); } while (0)
; #define PG8_MMA(ai, bj, At, Bt) do { __builtin_amdgcn_s_setprio(1); _Pragma("unroll") for (int m = 0; m < 4; ++m) _Pragma("unroll") for (int n = 0; n < 2; ++n) _Pragma("unroll") for (int k = 0; k < 2; ++k) \
;         acc[ai][bj][m][n] = __builtin_amdgcn_mfma_f32_16x16x32_bf16(Bt[n][k], At[m][k], acc[ai][bj][m][n], 0, 0, 0); __builtin_amdgcn_s_setprio(0); } while (0)
; #define PG8_WAIT_V(n) asm volatile("s_waitcnt vmcnt(" #n ")" ::: "memory")
; #define PG8_WAIT_L(n) asm volatile("s_waitcnt lgkmcnt(" #n ")" ::: "memory")
; #define PG8_BAR __builtin_amdgcn_s_barrier()
; #define PG8_SCHED __builtin_amdgcn_sched_barrier(0)
; template <class Epi, class Sched>
; __device__ __forceinline__ void gemm_phase(LAS unsigned char* lds, const int K, const int lda, const int ldb, const Sched& S, const Epi& E) {
;     ...
;             PG8_WAIT_V(8); PG8_WAIT_L(0); PG8_BAR; PG8_MMA(1, 0, At, B0); PG8_MMA(1, 1, At, B1); PG8_BAR; PG8_SCHED;
;             PG8_LDB(B0, 1, 0); PG8_LDB(B1, 1, 1); PG8_SCHED; PG8_LDA(At, 1, 0); PG8_STAGE(PG8_SA(0, 1), a2 + hA, voffA);
;             PG8_WAIT_V(8); PG8_WAIT_L(0); PG8_BAR; PG8_MMA(0, 0, At, B0); PG8_MMA(0, 1, At, B1); PG8_BAR; PG8_SCHED;
	s_setprio 1
	s_waitcnt lgkmcnt(0)
	v_mfma_f32_16x16x32_bf16 v[60:63], v[160:163], v[104:107], v[60:63]
	v_mfma_f32_16x16x32_bf16 v[56:59], v[160:163], v[124:127], v[56:59]
	v_mfma_f32_16x16x32_bf16 v[44:47], v[168:171], v[104:107], v[44:47]
	v_mfma_f32_16x16x32_bf16 v[40:43], v[168:171], v[124:127], v[40:43]
	v_mfma_f32_16x16x32_bf16 v[28:31], v[176:179], v[104:107], v[28:31]
	v_mfma_f32_16x16x32_bf16 v[24:27], v[176:179], v[124:127], v[24:27]
	v_mfma_f32_16x16x32_bf16 v[12:15], v[200:203], v[104:107], v[12:15]
	v_mfma_f32_16x16x32_bf16 v[8:11], v[200:203], v[124:127], v[8:11]
	v_mfma_f32_16x16x32_bf16 v[60:63], v[164:167], v[112:115], v[60:63]
	v_mfma_f32_16x16x32_bf16 v[56:59], v[164:167], v[140:143], v[56:59]
	v_mfma_f32_16x16x32_bf16 v[44:47], v[172:175], v[112:115], v[44:47]
	v_mfma_f32_16x16x32_bf16 v[40:43], v[172:175], v[140:143], v[40:43]
	v_mfma_f32_16x16x32_bf16 v[28:31], v[180:183], v[112:115], v[28:31]
	v_mfma_f32_16x16x32_bf16 v[24:27], v[180:183], v[140:143], v[24:27]
	v_mfma_f32_16x16x32_bf16 v[12:15], v[204:207], v[112:115], v[12:15]
	v_mfma_f32_16x16x32_bf16 v[8:11], v[204:207], v[140:143], v[8:11]
	s_setprio 0
	s_setprio 1
	v_mfma_f32_16x16x32_bf16 v[52:55], v[160:163], v[144:147], v[52:55]
	v_mfma_f32_16x16x32_bf16 v[48:51], v[160:163], v[152:155], v[48:51]
	v_mfma_f32_16x16x32_bf16 v[36:39], v[168:171], v[144:147], v[36:39]
	v_mfma_f32_16x16x32_bf16 v[32:35], v[168:171], v[152:155], v[32:35]
	v_mfma_f32_16x16x32_bf16 v[20:23], v[176:179], v[144:147], v[20:23]
	v_mfma_f32_16x16x32_bf16 v[16:19], v[176:179], v[152:155], v[16:19]
	v_mfma_f32_16x16x32_bf16 v[4:7], v[200:203], v[144:147], v[4:7]
	v_mfma_f32_16x16x32_bf16 v[0:3], v[200:203], v[152:155], v[0:3]
	v_mfma_f32_16x16x32_bf16 v[52:55], v[164:167], v[148:151], v[52:55]
	v_mfma_f32_16x16x32_bf16 v[48:51], v[164:167], v[156:159], v[48:51]
	v_mfma_f32_16x16x32_bf16 v[36:39], v[172:175], v[148:151], v[36:39]
	v_mfma_f32_16x16x32_bf16 v[32:35], v[172:175], v[156:159], v[32:35]
	v_mfma_f32_16x16x32_bf16 v[20:23], v[180:183], v[148:151], v[20:23]
	v_mfma_f32_16x16x32_bf16 v[16:19], v[180:183], v[156:159], v[16:19]
	v_mfma_f32_16x16x32_bf16 v[4:7], v[204:207], v[148:151], v[4:7]
	v_mfma_f32_16x16x32_bf16 v[0:3], v[204:207], v[156:159], v[0:3]
	s_setprio 0
	s_barrier
	s_add_i32 s29, 0, 0x18000
	s_add_i32 s34, 0, 0x1c000
	v_add_u32_e32 v140, s29, v217
	v_add_u32_e32 v250, s29, v249
	v_add_u32_e32 v156, 0x19000, v217
	v_add_u32_e32 v251, 0x19000, v249
	ds_read_b128 v[104:107], v140
	ds_read_b128 v[112:115], v250
	ds_read_b128 v[124:127], v140 offset:2048
	ds_read_b128 v[140:143], v250 offset:2048
	ds_read_b128 v[144:147], v156
	ds_read_b128 v[148:151], v251
	ds_read_b128 v[152:155], v156 offset:2048
	ds_read_b128 v[156:159], v251 offset:2048
	s_add_u32 s30, s70, 0x80000
	s_addc_u32 s31, s71, 0
	s_mov_b32 m0, s5
	v_lshl_add_u64 v[226:227], s[30:31], 0, v[184:185]
	ds_read_b128 v[160:163], v222 offset:32768
	ds_read_b128 v[164:167], v246 offset:32768
	ds_read_b128 v[168:171], v222 offset:34816
	ds_read_b128 v[172:175], v246 offset:34816
	ds_read_b128 v[176:179], v222 offset:36864
	ds_read_b128 v[180:183], v246 offset:36864
	ds_read_b128 v[200:203], v222 offset:38912
	ds_read_b128 v[204:207], v246 offset:38912
	global_load_lds_dwordx4 v[226:227], off
	v_lshl_add_u64 v[226:227], s[30:31], 0, v[188:189]
	s_mov_b32 m0, s6
	s_nop 0
	global_load_lds_dwordx4 v[226:227], off
	s_waitcnt vmcnt(8)
	s_waitcnt lgkmcnt(0)
	s_barrier
	s_setprio 1
	s_waitcnt lgkmcnt(0)
	v_mfma_f32_16x16x32_bf16 v[136:139], v[160:163], v[104:107], v[136:139]
	v_mfma_f32_16x16x32_bf16 v[132:135], v[160:163], v[124:127], v[132:135]
	v_mfma_f32_16x16x32_bf16 v[116:119], v[168:171], v[104:107], v[116:119]
	v_mfma_f32_16x16x32_bf16 v[108:111], v[168:171], v[124:127], v[108:111]
	v_mfma_f32_16x16x32_bf16 v[92:95], v[176:179], v[104:107], v[92:95]
	v_mfma_f32_16x16x32_bf16 v[88:91], v[176:179], v[124:127], v[88:91]
	v_mfma_f32_16x16x32_bf16 v[76:79], v[200:203], v[104:107], v[76:79]
	v_mfma_f32_16x16x32_bf16 v[72:75], v[200:203], v[124:127], v[72:75]
	v_mfma_f32_16x16x32_bf16 v[136:139], v[164:167], v[112:115], v[136:139]
	v_mfma_f32_16x16x32_bf16 v[132:135], v[164:167], v[140:143], v[132:135]
	v_mfma_f32_16x16x32_bf16 v[116:119], v[172:175], v[112:115], v[116:119]
	v_mfma_f32_16x16x32_bf16 v[108:111], v[172:175], v[140:143], v[108:111]
	v_mfma_f32_16x16x32_bf16 v[92:95], v[180:183], v[112:115], v[92:95]
	v_mfma_f32_16x16x32_bf16 v[88:91], v[180:183], v[140:143], v[88:91]
	v_mfma_f32_16x16x32_bf16 v[76:79], v[204:207], v[112:115], v[76:79]
	v_mfma_f32_16x16x32_bf16 v[72:75], v[204:207], v[140:143], v[72:75]
	s_setprio 0
	s_setprio 1
	v_mfma_f32_16x16x32_bf16 v[128:131], v[160:163], v[144:147], v[128:131]
	v_mfma_f32_16x16x32_bf16 v[120:123], v[160:163], v[152:155], v[120:123]
	v_mfma_f32_16x16x32_bf16 v[100:103], v[168:171], v[144:147], v[100:103]
	v_mfma_f32_16x16x32_bf16 v[96:99], v[168:171], v[152:155], v[96:99]
	v_mfma_f32_16x16x32_bf16 v[84:87], v[176:179], v[144:147], v[84:87]
	v_mfma_f32_16x16x32_bf16 v[80:83], v[176:179], v[152:155], v[80:83]
	v_mfma_f32_16x16x32_bf16 v[68:71], v[200:203], v[144:147], v[68:71]
	v_mfma_f32_16x16x32_bf16 v[64:67], v[200:203], v[152:155], v[64:67]
	v_mfma_f32_16x16x32_bf16 v[128:131], v[164:167], v[148:151], v[128:131]
	v_mfma_f32_16x16x32_bf16 v[120:123], v[164:167], v[156:159], v[120:123]
	v_mfma_f32_16x16x32_bf16 v[100:103], v[172:175], v[148:151], v[100:103]
	v_mfma_f32_16x16x32_bf16 v[96:99], v[172:175], v[156:159], v[96:99]
	v_mfma_f32_16x16x32_bf16 v[84:87], v[180:183], v[148:151], v[84:87]
	v_mfma_f32_16x16x32_bf16 v[80:83], v[180:183], v[156:159], v[80:83]
	v_mfma_f32_16x16x32_bf16 v[68:71], v[204:207], v[148:151], v[68:71]
	v_mfma_f32_16x16x32_bf16 v[64:67], v[204:207], v[156:159], v[64:67]
	s_setprio 0
	s_barrier
; #define LAS __attribute__((address_space(3)))
; #define PG8_STAGE(bufoff, gbase, voff) do { _Pragma("unroll") for (int _i = 0; _i < 2; ++_i) \
;         __builtin_amdgcn_global_load_lds((const unsigned*)((const char*)(gbase) + (voff)[_i]), (LAS unsigned*)(lds + (bufoff) + ldsw + _i * 8192), 16, 0, 0); } while (0)
; #define PG8_LDA(dst, b, h) do { _Pragma("unroll") for (int m = 0; m < 4; ++m) _Pragma("unroll") for (int k = 0; k < 2; ++k) dst[m][k] = *(const LAS bf16x8*)(lds + PG8_SA(b, h) + aoff + m * 2048 + k * 1024); } while (0)
; #define PG8_MMA(ai, bj, At, Bt) do { __builtin_amdgcn_s_setprio(1); _Pragma("unroll") for (int m = 0; m < 4; ++m) _Pragma("unroll") for (int n = 0; n < 2; ++n) _Pragma("unroll") for (int k = 0; k < 2; ++k) \
;         acc[ai][bj][m][n] = __builtin_amdgcn_mfma_f32_16x16x32_bf16(Bt[n][k], At[m][k], acc[ai][bj][m][n], 0, 0, 0); __builtin_amdgcn_s_setprio(0); } while (0)
; #define PG8_WAIT_V(n) asm volatile("s_waitcnt vmcnt(" #n ")" ::: "memory")
; #define PG8_WAIT_L(n) asm volatile("s_waitcnt lgkmcnt(" #n ")" ::: "memory")
; #define PG8_BAR __builtin_amdgcn_s_barrier()
; #define PG8_SCHED __builtin_amdgcn_sched_barrier(0)
; template <class Epi, class Sched>
; __device__ __forceinline__ void gemm_phase(LAS unsigned char* lds, const int K, const int lda, const int ldb, const Sched& S, const Epi& E) {
;     ...
;             PG8_LDA(At, 1, 1); PG8_STAGE(PG8_SB(1, 0), b3, voffB); PG8_STAGE(PG8_SB(1, 1), b3 + hB, voffB); PG8_STAGE(PG8_SA(1, 0), a3, voffA);
;             PG8_WAIT_V(8); PG8_WAIT_L(0); PG8_BAR; PG8_MMA(1, 0, At, B0); PG8_MMA(1, 1, At, B1); PG8_BAR; PG8_SCHED;
;         }
;     __device__ __forceinline__ void operator()(const f32x4 (&acc)[2][2][4][2], const Unit& u, int wr, int wc, int fr, int fq, LAS unsigned char* xs, int wid, int lane) const {
;         const int row0 = u.pm * 256 + wr * 64, col0 = u.pn * 256 + wc * 32 + 8 * fq;
;         const float* xo = (row0 < TP) ? xo_p : xo_s - (size_t)TP * D;
;         LAS float* P = (LAS float*)xs;
;         u32x4 raw[2][4][2];
;         if (!SRCF32) {
; #pragma unroll
;             for (int ai = 0; ai < 2; ++ai)
; #pragma unroll
;                 for (int m = 0; m < 4; ++m)
; #pragma unroll
;                     for (int bj = 0; bj < 2; ++bj) raw[ai][m][bj] = *(const u32x4*)(xb + (size_t)(row0 + ai * 128 + m * 16 + fr) * D + col0 + bj * 128);
;         }
	s_add_i32 s29, s29, s1
	v_lshl_add_u64 v[208:209], v[208:209], 0, s[52:53]
	s_mov_b32 m0, s29
	ds_read_b128 v[160:163], v222 offset:49152
	ds_read_b128 v[164:167], v246 offset:49152
	ds_read_b128 v[168:171], v222 offset:51200
	ds_read_b128 v[172:175], v246 offset:51200
	ds_read_b128 v[176:179], v222 offset:53248
	ds_read_b128 v[180:183], v246 offset:53248
	ds_read_b128 v[200:203], v222 offset:55296
	ds_read_b128 v[204:207], v246 offset:55296
	global_load_lds_dwordx4 v[208:209], off
	s_add_i32 m0, s29, 0x2000
	s_add_u32 s30, s68, 0x80080
	v_lshl_add_u64 v[208:209], v[210:211], 0, s[52:53]
	s_addc_u32 s31, s69, 0
	s_add_i32 s29, s34, s1
	global_load_lds_dwordx4 v[208:209], off
	v_lshl_add_u64 v[208:209], s[30:31], 0, v[186:187]
	s_mov_b32 m0, s29
	s_nop 0
	global_load_lds_dwordx4 v[208:209], off
	v_lshl_add_u64 v[208:209], s[30:31], 0, v[190:191]
	s_add_i32 m0, s29, 0x2000
	s_nop 0
	global_load_lds_dwordx4 v[208:209], off
	v_lshl_add_u64 v[208:209], v[212:213], 0, s[52:53]
	s_mov_b32 m0, s14
	s_nop 0
	global_load_lds_dwordx4 v[208:209], off
	v_lshl_add_u64 v[208:209], v[214:215], 0, s[52:53]
	s_mov_b32 m0, s15
	s_nop 0
	global_load_lds_dwordx4 v[208:209], off
	s_waitcnt vmcnt(8)
	s_waitcnt lgkmcnt(0)
	s_barrier
	s_setprio 1
	s_waitcnt lgkmcnt(0)
	v_mfma_f32_16x16x32_bf16 v[60:63], v[160:163], v[104:107], v[60:63]
	v_mfma_f32_16x16x32_bf16 v[56:59], v[160:163], v[124:127], v[56:59]
	v_mfma_f32_16x16x32_bf16 v[44:47], v[168:171], v[104:107], v[44:47]
	v_mfma_f32_16x16x32_bf16 v[40:43], v[168:171], v[124:127], v[40:43]
	v_mfma_f32_16x16x32_bf16 v[28:31], v[176:179], v[104:107], v[28:31]
	v_mfma_f32_16x16x32_bf16 v[24:27], v[176:179], v[124:127], v[24:27]
	v_mfma_f32_16x16x32_bf16 v[12:15], v[200:203], v[104:107], v[12:15]
	v_mfma_f32_16x16x32_bf16 v[8:11], v[200:203], v[124:127], v[8:11]
	v_mfma_f32_16x16x32_bf16 v[60:63], v[164:167], v[112:115], v[60:63]
	v_mfma_f32_16x16x32_bf16 v[56:59], v[164:167], v[140:143], v[56:59]
	v_mfma_f32_16x16x32_bf16 v[44:47], v[172:175], v[112:115], v[44:47]
	v_mfma_f32_16x16x32_bf16 v[40:43], v[172:175], v[140:143], v[40:43]
	v_mfma_f32_16x16x32_bf16 v[28:31], v[180:183], v[112:115], v[28:31]
	v_mfma_f32_16x16x32_bf16 v[24:27], v[180:183], v[140:143], v[24:27]
	v_mfma_f32_16x16x32_bf16 v[12:15], v[204:207], v[112:115], v[12:15]
	v_mfma_f32_16x16x32_bf16 v[8:11], v[204:207], v[140:143], v[8:11]
	s_setprio 0
	s_setprio 1
	v_mfma_f32_16x16x32_bf16 v[52:55], v[160:163], v[144:147], v[52:55]
	v_mfma_f32_16x16x32_bf16 v[48:51], v[160:163], v[152:155], v[48:51]
	v_mfma_f32_16x16x32_bf16 v[36:39], v[168:171], v[144:147], v[36:39]
	v_mfma_f32_16x16x32_bf16 v[32:35], v[168:171], v[152:155], v[32:35]
	v_mfma_f32_16x16x32_bf16 v[20:23], v[176:179], v[144:147], v[20:23]
	v_mfma_f32_16x16x32_bf16 v[16:19], v[176:179], v[152:155], v[16:19]
	v_mfma_f32_16x16x32_bf16 v[4:7], v[200:203], v[144:147], v[4:7]
	v_mfma_f32_16x16x32_bf16 v[0:3], v[200:203], v[152:155], v[0:3]
	v_mfma_f32_16x16x32_bf16 v[52:55], v[164:167], v[148:151], v[52:55]
	v_mfma_f32_16x16x32_bf16 v[48:51], v[164:167], v[156:159], v[48:51]
	v_mfma_f32_16x16x32_bf16 v[36:39], v[172:175], v[148:151], v[36:39]
	v_mfma_f32_16x16x32_bf16 v[32:35], v[172:175], v[156:159], v[32:35]
	v_mfma_f32_16x16x32_bf16 v[20:23], v[180:183], v[148:151], v[20:23]
	v_mfma_f32_16x16x32_bf16 v[16:19], v[180:183], v[156:159], v[16:19]
	v_mfma_f32_16x16x32_bf16 v[4:7], v[204:207], v[148:151], v[4:7]
	v_mfma_f32_16x16x32_bf16 v[0:3], v[204:207], v[156:159], v[0:3]
	s_setprio 0
	s_barrier
	s_add_i32 s28, s28, 2
	s_add_u32 s26, s26, 0x100
	s_addc_u32 s27, s27, 0
	s_add_u32 s66, s66, 0x100
	s_addc_u32 s67, s67, 0
	s_cmp_gt_u32 s28, 29
	s_cbranch_scc0 .LBB0_889
	s_and_b64 vcc, exec, s[54:55]
	s_cbranch_vccz .LBB0_892
	s_barrier
.LBB0_892:
	v_readfirstlane_b32 s18, v254
	s_nop 1
	s_lshr_b32 s18, s18, 6
	s_lshr_b32 s19, s18, 2
	s_and_b32 s34, s18, 3
	s_lshl_b32 s32, s64, 8
	s_lshl_b32 s19, s19, 6
	s_add_i32 s30, s32, s19
	s_lshl_b32 s31, s48, 8
	s_lshl_b32 s18, s34, 6
	s_add_i32 s31, s31, s18
	s_lshl_b32 s30, s30, 11
	s_add_i32 s30, s30, s31
	s_lshl_b32 s31, s30, 1
	s_add_u32 s24, s42, s31
	s_addc_u32 s25, s43, 0
	v_and_b32_e32 v114, 15, v254
	v_bfe_u32 v124, v254, 4, 2
	v_lshlrev_b32_e32 v112, 13, v124
	v_lshl_add_u32 v112, v114, 2, v112
	v_lshlrev_b32_e32 v112, 1, v112
	v_lshlrev_b32_e32 v227, 6, v124
	v_add_u32_e32 v227, 0x20000, v227
	s_lshl_b32 s19, s19, 4
	s_lshl_b32 s18, s34, 2
	s_add_i32 s19, s19, s18
	v_add_u32_e32 v227, s19, v227
	s_add_u32 s26, s24, 0x0
	s_addc_u32 s27, s25, 0
	global_load_dwordx2 v[104:105], v112, s[26:27]
	s_add_u32 s28, s24, 0x1000
	s_addc_u32 s29, s25, 0
	global_load_dwordx2 v[106:107], v112, s[28:29]
	s_add_u32 s26, s24, 0x2000
	s_addc_u32 s27, s25, 0
	global_load_dwordx2 v[140:141], v112, s[26:27]
	s_add_u32 s28, s24, 0x3000
	s_addc_u32 s29, s25, 0
	global_load_dwordx2 v[142:143], v112, s[28:29]
	s_add_u32 s26, s24, 0x10000
	s_addc_u32 s27, s25, 0
	global_load_dwordx2 v[144:145], v112, s[26:27]
	s_add_u32 s28, s24, 0x11000
	s_addc_u32 s29, s25, 0
	global_load_dwordx2 v[146:147], v112, s[28:29]
	s_add_u32 s26, s24, 0x12000
	s_addc_u32 s27, s25, 0
	global_load_dwordx2 v[148:149], v112, s[26:27]
	s_add_u32 s28, s24, 0x13000
	s_addc_u32 s29, s25, 0
	global_load_dwordx2 v[150:151], v112, s[28:29]
	s_add_u32 s26, s24, 0x20000
	s_addc_u32 s27, s25, 0
	global_load_dwordx2 v[152:153], v112, s[26:27]
	s_add_u32 s28, s24, 0x21000
	s_addc_u32 s29, s25, 0
	global_load_dwordx2 v[154:155], v112, s[28:29]
	s_add_u32 s26, s24, 0x22000
	s_addc_u32 s27, s25, 0
	global_load_dwordx2 v[156:157], v112, s[26:27]
	s_add_u32 s28, s24, 0x23000
	s_addc_u32 s29, s25, 0
; __device__ __forceinline__ unsigned cvt_pk_bf16(float lo, float hi) { unsigned r; asm("v_cvt_pk_bf16_f32 %0, %1, %2" : "=v"(r) : "v"(lo), "v"(hi)); return r; }
;     __device__ __forceinline__ void operator()(const f32x4 (&acc)[2][2][4][2], const Unit& u, int wr, int wc, int fr, int fq, LAS unsigned char* xs, int wid, int lane) const {
;     ...
;                     for (int bj = 0; bj < 2; ++bj) raw[ai][m][bj] = *(const u32x4*)(xb + (size_t)(row0 + ai * 128 + m * 16 + fr) * D + col0 + bj * 128);
;         }
; #pragma unroll
;         for (int ai = 0; ai < 2; ++ai) {
;             f32x4 xf[4][2][2];
;             if (SRCF32) {
; #pragma unroll
;                 for (int m = 0; m < 4; ++m)
; #pragma unroll
;                     for (int bj = 0; bj < 2; ++bj) { const size_t o = (size_t)(row0 + ai * 128 + m * 16 + fr) * D + col0 + bj * 128; xf[m][bj][0] = *(const f32x4*)(xo + o); xf[m][bj][1] = *(const f32x4*)(xo + o + 4); }
;             }
; #pragma unroll
;             for (int m = 0; m < 4; ++m) {
;                 const size_t row = (size_t)(row0 + ai * 128 + m * 16 + fr);
;                 float ss = 0.f;
; #pragma unroll
;                 for (int bj = 0; bj < 2; ++bj) {
;                     const size_t o = row * D + col0 + bj * 128;
;                     f32x4 x0, x1;
;                     if (SRCF32) { x0 = xf[m][bj][0]; x1 = xf[m][bj][1]; }
;                     else { const u32x4 r = raw[ai][m][bj]; x0 = (f32x4){bf_lo(r.x), bf_hi(r.x), bf_lo(r.y), bf_hi(r.y)}; x1 = (f32x4){bf_lo(r.z), bf_hi(r.z), bf_lo(r.w), bf_hi(r.w)}; }
;                     const f32x4 v0 = x0 + acc[ai][bj][m][0], v1 = x1 + acc[ai][bj][m][1];
;                     if (LAST) { *(f32x4*)(out + o) = v0; *(f32x4*)(out + o + 4) = v1; }
;                     else {
;                         ss += (v0[0] * v0[0] + v0[1] * v0[1]) + (v0[2] * v0[2] + v0[3] * v0[3]) + (v1[0] * v1[0] + v1[1] * v1[1]) + (v1[2] * v1[2] + v1[3] * v1[3]);
;                         u32x4 w; w.x = cvt_pk_bf16(v0[0], v0[1]); w.y = cvt_pk_bf16(v0[2], v0[3]); w.z = cvt_pk_bf16(v1[0], v1[1]); w.w = cvt_pk_bf16(v1[2], v1[3]); *(u32x4*)(xb + o) = w;
;                     }
	global_load_dwordx2 v[158:159], v112, s[28:29]
	s_add_u32 s26, s24, 0x30000
	s_addc_u32 s27, s25, 0
	global_load_dwordx2 v[160:161], v112, s[26:27]
	s_add_u32 s28, s24, 0x31000
	s_addc_u32 s29, s25, 0
	global_load_dwordx2 v[162:163], v112, s[28:29]
	s_add_u32 s26, s24, 0x32000
	s_addc_u32 s27, s25, 0
	global_load_dwordx2 v[164:165], v112, s[26:27]
	s_add_u32 s28, s24, 0x33000
	s_addc_u32 s29, s25, 0
	global_load_dwordx2 v[166:167], v112, s[28:29]
	s_add_u32 s26, s24, 0x80000
	s_addc_u32 s27, s25, 0
	global_load_dwordx2 v[168:169], v112, s[26:27]
	s_add_u32 s28, s24, 0x81000
	s_addc_u32 s29, s25, 0
	global_load_dwordx2 v[170:171], v112, s[28:29]
	s_add_u32 s26, s24, 0x82000
	s_addc_u32 s27, s25, 0
	global_load_dwordx2 v[172:173], v112, s[26:27]
	s_add_u32 s28, s24, 0x83000
	s_addc_u32 s29, s25, 0
	global_load_dwordx2 v[174:175], v112, s[28:29]
	s_add_u32 s26, s24, 0x90000
	s_addc_u32 s27, s25, 0
	global_load_dwordx2 v[176:177], v112, s[26:27]
	s_add_u32 s28, s24, 0x91000
	s_addc_u32 s29, s25, 0
	global_load_dwordx2 v[178:179], v112, s[28:29]
	s_add_u32 s26, s24, 0x92000
	s_addc_u32 s27, s25, 0
	global_load_dwordx2 v[180:181], v112, s[26:27]
	s_add_u32 s28, s24, 0x93000
	s_addc_u32 s29, s25, 0
	global_load_dwordx2 v[182:183], v112, s[28:29]
	s_add_u32 s26, s24, 0xa0000
	s_addc_u32 s27, s25, 0
	global_load_dwordx2 v[200:201], v112, s[26:27]
	s_add_u32 s28, s24, 0xa1000
	s_addc_u32 s29, s25, 0
	global_load_dwordx2 v[202:203], v112, s[28:29]
	s_add_u32 s26, s24, 0xa2000
	s_addc_u32 s27, s25, 0
	global_load_dwordx2 v[204:205], v112, s[26:27]
	s_add_u32 s28, s24, 0xa3000
	s_addc_u32 s29, s25, 0
	global_load_dwordx2 v[206:207], v112, s[28:29]
	s_add_u32 s26, s24, 0xb0000
	s_addc_u32 s27, s25, 0
	global_load_dwordx2 v[208:209], v112, s[26:27]
	s_add_u32 s28, s24, 0xb1000
	s_addc_u32 s29, s25, 0
	global_load_dwordx2 v[210:211], v112, s[28:29]
	s_add_u32 s26, s24, 0xb2000
	s_addc_u32 s27, s25, 0
	global_load_dwordx2 v[212:213], v112, s[26:27]
	s_add_u32 s28, s24, 0xb3000
	s_addc_u32 s29, s25, 0
	global_load_dwordx2 v[214:215], v112, s[28:29]
	s_waitcnt vmcnt(31)
	v_lshlrev_b32_e32 v126, 16, v104
	v_and_b32_e32 v226, 0xffff0000, v104
	v_add_f32_e32 v136, v136, v126
	v_add_f32_e32 v132, v132, v226
	v_lshlrev_b32_e32 v126, 16, v105
	v_and_b32_e32 v226, 0xffff0000, v105
	v_add_f32_e32 v128, v128, v126
	v_add_f32_e32 v120, v120, v226
	v_cvt_pk_bf16_f32 v236, v136, v132
	v_cvt_pk_bf16_f32 v237, v128, v120
	v_mul_f32_e32 v136, v136, v136
	v_fmac_f32_e32 v136, v132, v132
	v_fmac_f32_e32 v136, v128, v128
	v_fmac_f32_e32 v136, v120, v120
	s_add_u32 s26, s24, 0x0
	s_addc_u32 s27, s25, 0
	global_store_dwordx2 v112, v[236:237], s[26:27]
	s_waitcnt vmcnt(31)
	v_lshlrev_b32_e32 v126, 16, v106
	v_and_b32_e32 v226, 0xffff0000, v106
	v_add_f32_e32 v137, v137, v126
	v_add_f32_e32 v133, v133, v226
	v_lshlrev_b32_e32 v126, 16, v107
	v_and_b32_e32 v226, 0xffff0000, v107
	v_add_f32_e32 v129, v129, v126
	v_add_f32_e32 v121, v121, v226
	v_cvt_pk_bf16_f32 v238, v137, v133
	v_cvt_pk_bf16_f32 v239, v129, v121
	v_mul_f32_e32 v137, v137, v137
	v_fmac_f32_e32 v137, v133, v133
	v_fmac_f32_e32 v137, v129, v129
	v_fmac_f32_e32 v137, v121, v121
	s_add_u32 s28, s24, 0x1000
	s_addc_u32 s29, s25, 0
	global_store_dwordx2 v112, v[238:239], s[28:29]
	s_waitcnt vmcnt(31)
	v_lshlrev_b32_e32 v126, 16, v140
	v_and_b32_e32 v226, 0xffff0000, v140
	v_add_f32_e32 v138, v138, v126
	v_add_f32_e32 v134, v134, v226
	v_lshlrev_b32_e32 v126, 16, v141
	v_and_b32_e32 v226, 0xffff0000, v141
	v_add_f32_e32 v130, v130, v126
	v_add_f32_e32 v122, v122, v226
	v_cvt_pk_bf16_f32 v240, v138, v134
	v_cvt_pk_bf16_f32 v241, v130, v122
	v_mul_f32_e32 v138, v138, v138
	v_fmac_f32_e32 v138, v134, v134
	v_fmac_f32_e32 v138, v130, v130
	v_fmac_f32_e32 v138, v122, v122
	s_add_u32 s26, s24, 0x2000
	s_addc_u32 s27, s25, 0
	global_store_dwordx2 v112, v[240:241], s[26:27]
	s_waitcnt vmcnt(31)
	v_lshlrev_b32_e32 v126, 16, v142
	v_and_b32_e32 v226, 0xffff0000, v142
	v_add_f32_e32 v139, v139, v126
	v_add_f32_e32 v135, v135, v226
	v_lshlrev_b32_e32 v126, 16, v143
	v_and_b32_e32 v226, 0xffff0000, v143
	v_add_f32_e32 v131, v131, v126
	v_add_f32_e32 v123, v123, v226
	v_cvt_pk_bf16_f32 v242, v139, v135
	v_cvt_pk_bf16_f32 v243, v131, v123
	v_mul_f32_e32 v139, v139, v139
	v_fmac_f32_e32 v139, v135, v135
	v_fmac_f32_e32 v139, v131, v131
	v_fmac_f32_e32 v139, v123, v123
	s_add_u32 s28, s24, 0x3000
	s_addc_u32 s29, s25, 0
	global_store_dwordx2 v112, v[242:243], s[28:29]
	s_waitcnt vmcnt(31)
	v_lshlrev_b32_e32 v126, 16, v144
	v_and_b32_e32 v226, 0xffff0000, v144
	v_add_f32_e32 v116, v116, v126
	v_add_f32_e32 v108, v108, v226
	v_lshlrev_b32_e32 v126, 16, v145
	v_and_b32_e32 v226, 0xffff0000, v145
	v_add_f32_e32 v100, v100, v126
	v_add_f32_e32 v96, v96, v226
	v_cvt_pk_bf16_f32 v236, v116, v108
	v_cvt_pk_bf16_f32 v237, v100, v96
	v_mul_f32_e32 v116, v116, v116
	v_fmac_f32_e32 v116, v108, v108
	v_fmac_f32_e32 v116, v100, v100
	v_fmac_f32_e32 v116, v96, v96
	s_add_u32 s26, s24, 0x10000
	s_addc_u32 s27, s25, 0
	global_store_dwordx2 v112, v[236:237], s[26:27]
	s_waitcnt vmcnt(31)
	v_lshlrev_b32_e32 v126, 16, v146
	v_and_b32_e32 v226, 0xffff0000, v146
	v_add_f32_e32 v117, v117, v126
	v_add_f32_e32 v109, v109, v226
	v_lshlrev_b32_e32 v126, 16, v147
	v_and_b32_e32 v226, 0xffff0000, v147
	v_add_f32_e32 v101, v101, v126
	v_add_f32_e32 v97, v97, v226
	v_cvt_pk_bf16_f32 v238, v117, v109
	v_cvt_pk_bf16_f32 v239, v101, v97
	v_mul_f32_e32 v117, v117, v117
	v_fmac_f32_e32 v117, v109, v109
	v_fmac_f32_e32 v117, v101, v101
	v_fmac_f32_e32 v117, v97, v97
	s_add_u32 s28, s24, 0x11000
	s_addc_u32 s29, s25, 0
	global_store_dwordx2 v112, v[238:239], s[28:29]
	s_waitcnt vmcnt(31)
; __device__ __forceinline__ unsigned cvt_pk_bf16(float lo, float hi) { unsigned r; asm("v_cvt_pk_bf16_f32 %0, %1, %2" : "=v"(r) : "v"(lo), "v"(hi)); return r; }
;     __device__ __forceinline__ void operator()(const f32x4 (&acc)[2][2][4][2], const Unit& u, int wr, int wc, int fr, int fq, LAS unsigned char* xs, int wid, int lane) const {
;     ...
; #pragma unroll
;             for (int m = 0; m < 4; ++m) {
;                 const size_t row = (size_t)(row0 + ai * 128 + m * 16 + fr);
;                 float ss = 0.f;
; #pragma unroll
;                 for (int bj = 0; bj < 2; ++bj) {
;                     const size_t o = row * D + col0 + bj * 128;
;                     f32x4 x0, x1;
;                     if (SRCF32) { x0 = xf[m][bj][0]; x1 = xf[m][bj][1]; }
;                     else { const u32x4 r = raw[ai][m][bj]; x0 = (f32x4){bf_lo(r.x), bf_hi(r.x), bf_lo(r.y), bf_hi(r.y)}; x1 = (f32x4){bf_lo(r.z), bf_hi(r.z), bf_lo(r.w), bf_hi(r.w)}; }
;                     const f32x4 v0 = x0 + acc[ai][bj][m][0], v1 = x1 + acc[ai][bj][m][1];
;                     if (LAST) { *(f32x4*)(out + o) = v0; *(f32x4*)(out + o + 4) = v1; }
;                     else {
;                         ss += (v0[0] * v0[0] + v0[1] * v0[1]) + (v0[2] * v0[2] + v0[3] * v0[3]) + (v1[0] * v1[0] + v1[1] * v1[1]) + (v1[2] * v1[2] + v1[3] * v1[3]);
;                         u32x4 w; w.x = cvt_pk_bf16(v0[0], v0[1]); w.y = cvt_pk_bf16(v0[2], v0[3]); w.z = cvt_pk_bf16(v1[0], v1[1]); w.w = cvt_pk_bf16(v1[2], v1[3]); *(u32x4*)(xb + o) = w;
;                     }
	v_lshlrev_b32_e32 v126, 16, v148
	v_and_b32_e32 v226, 0xffff0000, v148
	v_add_f32_e32 v118, v118, v126
	v_add_f32_e32 v110, v110, v226
	v_lshlrev_b32_e32 v126, 16, v149
	v_and_b32_e32 v226, 0xffff0000, v149
	v_add_f32_e32 v102, v102, v126
	v_add_f32_e32 v98, v98, v226
	v_cvt_pk_bf16_f32 v240, v118, v110
	v_cvt_pk_bf16_f32 v241, v102, v98
	v_mul_f32_e32 v118, v118, v118
	v_fmac_f32_e32 v118, v110, v110
	v_fmac_f32_e32 v118, v102, v102
	v_fmac_f32_e32 v118, v98, v98
	s_add_u32 s26, s24, 0x12000
	s_addc_u32 s27, s25, 0
	global_store_dwordx2 v112, v[240:241], s[26:27]
	s_waitcnt vmcnt(31)
	v_lshlrev_b32_e32 v126, 16, v150
	v_and_b32_e32 v226, 0xffff0000, v150
	v_add_f32_e32 v119, v119, v126
	v_add_f32_e32 v111, v111, v226
	v_lshlrev_b32_e32 v126, 16, v151
	v_and_b32_e32 v226, 0xffff0000, v151
	v_add_f32_e32 v103, v103, v126
	v_add_f32_e32 v99, v99, v226
	v_cvt_pk_bf16_f32 v242, v119, v111
	v_cvt_pk_bf16_f32 v243, v103, v99
	v_mul_f32_e32 v119, v119, v119
	v_fmac_f32_e32 v119, v111, v111
	v_fmac_f32_e32 v119, v103, v103
	v_fmac_f32_e32 v119, v99, v99
	s_add_u32 s28, s24, 0x13000
	s_addc_u32 s29, s25, 0
	global_store_dwordx2 v112, v[242:243], s[28:29]
	s_waitcnt vmcnt(31)
	v_lshlrev_b32_e32 v126, 16, v152
	v_and_b32_e32 v226, 0xffff0000, v152
	v_add_f32_e32 v92, v92, v126
	v_add_f32_e32 v88, v88, v226
	v_lshlrev_b32_e32 v126, 16, v153
	v_and_b32_e32 v226, 0xffff0000, v153
	v_add_f32_e32 v84, v84, v126
	v_add_f32_e32 v80, v80, v226
	v_cvt_pk_bf16_f32 v236, v92, v88
	v_cvt_pk_bf16_f32 v237, v84, v80
	v_mul_f32_e32 v92, v92, v92
	v_fmac_f32_e32 v92, v88, v88
	v_fmac_f32_e32 v92, v84, v84
	v_fmac_f32_e32 v92, v80, v80
	s_add_u32 s26, s24, 0x20000
	s_addc_u32 s27, s25, 0
	global_store_dwordx2 v112, v[236:237], s[26:27]
	s_waitcnt vmcnt(31)
	v_lshlrev_b32_e32 v126, 16, v154
	v_and_b32_e32 v226, 0xffff0000, v154
	v_add_f32_e32 v93, v93, v126
	v_add_f32_e32 v89, v89, v226
	v_lshlrev_b32_e32 v126, 16, v155
	v_and_b32_e32 v226, 0xffff0000, v155
	v_add_f32_e32 v85, v85, v126
	v_add_f32_e32 v81, v81, v226
	v_cvt_pk_bf16_f32 v238, v93, v89
	v_cvt_pk_bf16_f32 v239, v85, v81
	v_mul_f32_e32 v93, v93, v93
	v_fmac_f32_e32 v93, v89, v89
	v_fmac_f32_e32 v93, v85, v85
	v_fmac_f32_e32 v93, v81, v81
	s_add_u32 s28, s24, 0x21000
	s_addc_u32 s29, s25, 0
	global_store_dwordx2 v112, v[238:239], s[28:29]
	s_waitcnt vmcnt(31)
	v_lshlrev_b32_e32 v126, 16, v156
	v_and_b32_e32 v226, 0xffff0000, v156
	v_add_f32_e32 v94, v94, v126
	v_add_f32_e32 v90, v90, v226
	v_lshlrev_b32_e32 v126, 16, v157
	v_and_b32_e32 v226, 0xffff0000, v157
	v_add_f32_e32 v86, v86, v126
	v_add_f32_e32 v82, v82, v226
	v_cvt_pk_bf16_f32 v240, v94, v90
	v_cvt_pk_bf16_f32 v241, v86, v82
	v_mul_f32_e32 v94, v94, v94
	v_fmac_f32_e32 v94, v90, v90
	v_fmac_f32_e32 v94, v86, v86
	v_fmac_f32_e32 v94, v82, v82
	s_add_u32 s26, s24, 0x22000
	s_addc_u32 s27, s25, 0
	global_store_dwordx2 v112, v[240:241], s[26:27]
	s_waitcnt vmcnt(31)
	v_lshlrev_b32_e32 v126, 16, v158
	v_and_b32_e32 v226, 0xffff0000, v158
	v_add_f32_e32 v95, v95, v126
	v_add_f32_e32 v91, v91, v226
	v_lshlrev_b32_e32 v126, 16, v159
	v_and_b32_e32 v226, 0xffff0000, v159
	v_add_f32_e32 v87, v87, v126
	v_add_f32_e32 v83, v83, v226
	v_cvt_pk_bf16_f32 v242, v95, v91
	v_cvt_pk_bf16_f32 v243, v87, v83
	v_mul_f32_e32 v95, v95, v95
	v_fmac_f32_e32 v95, v91, v91
	v_fmac_f32_e32 v95, v87, v87
	v_fmac_f32_e32 v95, v83, v83
	s_add_u32 s28, s24, 0x23000
	s_addc_u32 s29, s25, 0
	global_store_dwordx2 v112, v[242:243], s[28:29]
	s_waitcnt vmcnt(31)
	v_lshlrev_b32_e32 v126, 16, v160
	v_and_b32_e32 v226, 0xffff0000, v160
	v_add_f32_e32 v76, v76, v126
	v_add_f32_e32 v72, v72, v226
	v_lshlrev_b32_e32 v126, 16, v161
	v_and_b32_e32 v226, 0xffff0000, v161
	v_add_f32_e32 v68, v68, v126
	v_add_f32_e32 v64, v64, v226
	v_cvt_pk_bf16_f32 v236, v76, v72
	v_cvt_pk_bf16_f32 v237, v68, v64
	v_mul_f32_e32 v76, v76, v76
	v_fmac_f32_e32 v76, v72, v72
	v_fmac_f32_e32 v76, v68, v68
	v_fmac_f32_e32 v76, v64, v64
	s_add_u32 s26, s24, 0x30000
	s_addc_u32 s27, s25, 0
	global_store_dwordx2 v112, v[236:237], s[26:27]
	s_waitcnt vmcnt(31)
	v_lshlrev_b32_e32 v126, 16, v162
	v_and_b32_e32 v226, 0xffff0000, v162
	v_add_f32_e32 v77, v77, v126
	v_add_f32_e32 v73, v73, v226
	v_lshlrev_b32_e32 v126, 16, v163
	v_and_b32_e32 v226, 0xffff0000, v163
	v_add_f32_e32 v69, v69, v126
	v_add_f32_e32 v65, v65, v226
	v_cvt_pk_bf16_f32 v238, v77, v73
	v_cvt_pk_bf16_f32 v239, v69, v65
	v_mul_f32_e32 v77, v77, v77
	v_fmac_f32_e32 v77, v73, v73
	v_fmac_f32_e32 v77, v69, v69
	v_fmac_f32_e32 v77, v65, v65
	s_add_u32 s28, s24, 0x31000
	s_addc_u32 s29, s25, 0
	global_store_dwordx2 v112, v[238:239], s[28:29]
	s_waitcnt vmcnt(31)
	v_lshlrev_b32_e32 v126, 16, v164
	v_and_b32_e32 v226, 0xffff0000, v164
	v_add_f32_e32 v78, v78, v126
	v_add_f32_e32 v74, v74, v226
	v_lshlrev_b32_e32 v126, 16, v165
	v_and_b32_e32 v226, 0xffff0000, v165
	v_add_f32_e32 v70, v70, v126
	v_add_f32_e32 v66, v66, v226
	v_cvt_pk_bf16_f32 v240, v78, v74
	v_cvt_pk_bf16_f32 v241, v70, v66
	v_mul_f32_e32 v78, v78, v78
	v_fmac_f32_e32 v78, v74, v74
	v_fmac_f32_e32 v78, v70, v70
	v_fmac_f32_e32 v78, v66, v66
	s_add_u32 s26, s24, 0x32000
	s_addc_u32 s27, s25, 0
	global_store_dwordx2 v112, v[240:241], s[26:27]
	s_waitcnt vmcnt(31)
	v_lshlrev_b32_e32 v126, 16, v166
	v_and_b32_e32 v226, 0xffff0000, v166
	v_add_f32_e32 v79, v79, v126
	v_add_f32_e32 v75, v75, v226
	v_lshlrev_b32_e32 v126, 16, v167
	v_and_b32_e32 v226, 0xffff0000, v167
	v_add_f32_e32 v71, v71, v126
	v_add_f32_e32 v67, v67, v226
	v_cvt_pk_bf16_f32 v242, v79, v75
	v_cvt_pk_bf16_f32 v243, v71, v67
	v_mul_f32_e32 v79, v79, v79
	v_fmac_f32_e32 v79, v75, v75
	v_fmac_f32_e32 v79, v71, v71
	v_fmac_f32_e32 v79, v67, v67
	s_add_u32 s28, s24, 0x33000
	s_addc_u32 s29, s25, 0
	global_store_dwordx2 v112, v[242:243], s[28:29]
	s_waitcnt vmcnt(31)
; __device__ __forceinline__ unsigned cvt_pk_bf16(float lo, float hi) { unsigned r; asm("v_cvt_pk_bf16_f32 %0, %1, %2" : "=v"(r) : "v"(lo), "v"(hi)); return r; }
;     __device__ __forceinline__ void operator()(const f32x4 (&acc)[2][2][4][2], const Unit& u, int wr, int wc, int fr, int fq, LAS unsigned char* xs, int wid, int lane) const {
;     ...
; #pragma unroll
;             for (int m = 0; m < 4; ++m) {
;                 const size_t row = (size_t)(row0 + ai * 128 + m * 16 + fr);
;                 float ss = 0.f;
; #pragma unroll
;                 for (int bj = 0; bj < 2; ++bj) {
;                     const size_t o = row * D + col0 + bj * 128;
;                     f32x4 x0, x1;
;                     if (SRCF32) { x0 = xf[m][bj][0]; x1 = xf[m][bj][1]; }
;                     else { const u32x4 r = raw[ai][m][bj]; x0 = (f32x4){bf_lo(r.x), bf_hi(r.x), bf_lo(r.y), bf_hi(r.y)}; x1 = (f32x4){bf_lo(r.z), bf_hi(r.z), bf_lo(r.w), bf_hi(r.w)}; }
;                     const f32x4 v0 = x0 + acc[ai][bj][m][0], v1 = x1 + acc[ai][bj][m][1];
;                     if (LAST) { *(f32x4*)(out + o) = v0; *(f32x4*)(out + o + 4) = v1; }
;                     else {
;                         ss += (v0[0] * v0[0] + v0[1] * v0[1]) + (v0[2] * v0[2] + v0[3] * v0[3]) + (v1[0] * v1[0] + v1[1] * v1[1]) + (v1[2] * v1[2] + v1[3] * v1[3]);
;                         u32x4 w; w.x = cvt_pk_bf16(v0[0], v0[1]); w.y = cvt_pk_bf16(v0[2], v0[3]); w.z = cvt_pk_bf16(v1[0], v1[1]); w.w = cvt_pk_bf16(v1[2], v1[3]); *(u32x4*)(xb + o) = w;
;                     }
	v_lshlrev_b32_e32 v126, 16, v168
	v_and_b32_e32 v226, 0xffff0000, v168
	v_add_f32_e32 v60, v60, v126
	v_add_f32_e32 v56, v56, v226
	v_lshlrev_b32_e32 v126, 16, v169
	v_and_b32_e32 v226, 0xffff0000, v169
	v_add_f32_e32 v52, v52, v126
	v_add_f32_e32 v48, v48, v226
	v_cvt_pk_bf16_f32 v236, v60, v56
	v_cvt_pk_bf16_f32 v237, v52, v48
	v_mul_f32_e32 v60, v60, v60
	v_fmac_f32_e32 v60, v56, v56
	v_fmac_f32_e32 v60, v52, v52
	v_fmac_f32_e32 v60, v48, v48
	s_add_u32 s26, s24, 0x80000
	s_addc_u32 s27, s25, 0
	global_store_dwordx2 v112, v[236:237], s[26:27]
	s_waitcnt vmcnt(31)
	v_lshlrev_b32_e32 v126, 16, v170
	v_and_b32_e32 v226, 0xffff0000, v170
	v_add_f32_e32 v61, v61, v126
	v_add_f32_e32 v57, v57, v226
	v_lshlrev_b32_e32 v126, 16, v171
	v_and_b32_e32 v226, 0xffff0000, v171
	v_add_f32_e32 v53, v53, v126
	v_add_f32_e32 v49, v49, v226
	v_cvt_pk_bf16_f32 v238, v61, v57
	v_cvt_pk_bf16_f32 v239, v53, v49
	v_mul_f32_e32 v61, v61, v61
	v_fmac_f32_e32 v61, v57, v57
	v_fmac_f32_e32 v61, v53, v53
	v_fmac_f32_e32 v61, v49, v49
	s_add_u32 s28, s24, 0x81000
	s_addc_u32 s29, s25, 0
	global_store_dwordx2 v112, v[238:239], s[28:29]
	s_waitcnt vmcnt(31)
	v_lshlrev_b32_e32 v126, 16, v172
	v_and_b32_e32 v226, 0xffff0000, v172
	v_add_f32_e32 v62, v62, v126
	v_add_f32_e32 v58, v58, v226
	v_lshlrev_b32_e32 v126, 16, v173
	v_and_b32_e32 v226, 0xffff0000, v173
	v_add_f32_e32 v54, v54, v126
	v_add_f32_e32 v50, v50, v226
	v_cvt_pk_bf16_f32 v240, v62, v58
	v_cvt_pk_bf16_f32 v241, v54, v50
	v_mul_f32_e32 v62, v62, v62
	v_fmac_f32_e32 v62, v58, v58
	v_fmac_f32_e32 v62, v54, v54
	v_fmac_f32_e32 v62, v50, v50
	s_add_u32 s26, s24, 0x82000
	s_addc_u32 s27, s25, 0
	global_store_dwordx2 v112, v[240:241], s[26:27]
	s_waitcnt vmcnt(31)
	v_lshlrev_b32_e32 v126, 16, v174
	v_and_b32_e32 v226, 0xffff0000, v174
	v_add_f32_e32 v63, v63, v126
	v_add_f32_e32 v59, v59, v226
	v_lshlrev_b32_e32 v126, 16, v175
	v_and_b32_e32 v226, 0xffff0000, v175
	v_add_f32_e32 v55, v55, v126
	v_add_f32_e32 v51, v51, v226
	v_cvt_pk_bf16_f32 v242, v63, v59
	v_cvt_pk_bf16_f32 v243, v55, v51
	v_mul_f32_e32 v63, v63, v63
	v_fmac_f32_e32 v63, v59, v59
	v_fmac_f32_e32 v63, v55, v55
	v_fmac_f32_e32 v63, v51, v51
	s_add_u32 s28, s24, 0x83000
	s_addc_u32 s29, s25, 0
	global_store_dwordx2 v112, v[242:243], s[28:29]
	s_waitcnt vmcnt(31)
	v_lshlrev_b32_e32 v126, 16, v176
	v_and_b32_e32 v226, 0xffff0000, v176
	v_add_f32_e32 v44, v44, v126
	v_add_f32_e32 v40, v40, v226
	v_lshlrev_b32_e32 v126, 16, v177
	v_and_b32_e32 v226, 0xffff0000, v177
	v_add_f32_e32 v36, v36, v126
	v_add_f32_e32 v32, v32, v226
	v_cvt_pk_bf16_f32 v236, v44, v40
	v_cvt_pk_bf16_f32 v237, v36, v32
	v_mul_f32_e32 v44, v44, v44
	v_fmac_f32_e32 v44, v40, v40
	v_fmac_f32_e32 v44, v36, v36
	v_fmac_f32_e32 v44, v32, v32
	s_add_u32 s26, s24, 0x90000
	s_addc_u32 s27, s25, 0
	global_store_dwordx2 v112, v[236:237], s[26:27]
	s_waitcnt vmcnt(31)
	v_lshlrev_b32_e32 v126, 16, v178
	v_and_b32_e32 v226, 0xffff0000, v178
	v_add_f32_e32 v45, v45, v126
	v_add_f32_e32 v41, v41, v226
	v_lshlrev_b32_e32 v126, 16, v179
	v_and_b32_e32 v226, 0xffff0000, v179
	v_add_f32_e32 v37, v37, v126
	v_add_f32_e32 v33, v33, v226
	v_cvt_pk_bf16_f32 v238, v45, v41
	v_cvt_pk_bf16_f32 v239, v37, v33
	v_mul_f32_e32 v45, v45, v45
	v_fmac_f32_e32 v45, v41, v41
	v_fmac_f32_e32 v45, v37, v37
	v_fmac_f32_e32 v45, v33, v33
	s_add_u32 s28, s24, 0x91000
	s_addc_u32 s29, s25, 0
	global_store_dwordx2 v112, v[238:239], s[28:29]
	s_waitcnt vmcnt(31)
	v_lshlrev_b32_e32 v126, 16, v180
	v_and_b32_e32 v226, 0xffff0000, v180
	v_add_f32_e32 v46, v46, v126
	v_add_f32_e32 v42, v42, v226
	v_lshlrev_b32_e32 v126, 16, v181
	v_and_b32_e32 v226, 0xffff0000, v181
	v_add_f32_e32 v38, v38, v126
	v_add_f32_e32 v34, v34, v226
	v_cvt_pk_bf16_f32 v240, v46, v42
	v_cvt_pk_bf16_f32 v241, v38, v34
	v_mul_f32_e32 v46, v46, v46
	v_fmac_f32_e32 v46, v42, v42
	v_fmac_f32_e32 v46, v38, v38
	v_fmac_f32_e32 v46, v34, v34
	s_add_u32 s26, s24, 0x92000
	s_addc_u32 s27, s25, 0
	global_store_dwordx2 v112, v[240:241], s[26:27]
	s_waitcnt vmcnt(31)
	v_lshlrev_b32_e32 v126, 16, v182
	v_and_b32_e32 v226, 0xffff0000, v182
	v_add_f32_e32 v47, v47, v126
	v_add_f32_e32 v43, v43, v226
	v_lshlrev_b32_e32 v126, 16, v183
	v_and_b32_e32 v226, 0xffff0000, v183
	v_add_f32_e32 v39, v39, v126
	v_add_f32_e32 v35, v35, v226
	v_cvt_pk_bf16_f32 v242, v47, v43
	v_cvt_pk_bf16_f32 v243, v39, v35
	v_mul_f32_e32 v47, v47, v47
	v_fmac_f32_e32 v47, v43, v43
	v_fmac_f32_e32 v47, v39, v39
	v_fmac_f32_e32 v47, v35, v35
	s_add_u32 s28, s24, 0x93000
	s_addc_u32 s29, s25, 0
	global_store_dwordx2 v112, v[242:243], s[28:29]
	s_waitcnt vmcnt(31)
	v_lshlrev_b32_e32 v126, 16, v200
	v_and_b32_e32 v226, 0xffff0000, v200
	v_add_f32_e32 v28, v28, v126
	v_add_f32_e32 v24, v24, v226
	v_lshlrev_b32_e32 v126, 16, v201
	v_and_b32_e32 v226, 0xffff0000, v201
	v_add_f32_e32 v20, v20, v126
	v_add_f32_e32 v16, v16, v226
	v_cvt_pk_bf16_f32 v236, v28, v24
	v_cvt_pk_bf16_f32 v237, v20, v16
	v_mul_f32_e32 v28, v28, v28
	v_fmac_f32_e32 v28, v24, v24
	v_fmac_f32_e32 v28, v20, v20
	v_fmac_f32_e32 v28, v16, v16
	s_add_u32 s26, s24, 0xa0000
	s_addc_u32 s27, s25, 0
	global_store_dwordx2 v112, v[236:237], s[26:27]
	s_waitcnt vmcnt(31)
	v_lshlrev_b32_e32 v126, 16, v202
	v_and_b32_e32 v226, 0xffff0000, v202
	v_add_f32_e32 v29, v29, v126
	v_add_f32_e32 v25, v25, v226
	v_lshlrev_b32_e32 v126, 16, v203
	v_and_b32_e32 v226, 0xffff0000, v203
	v_add_f32_e32 v21, v21, v126
	v_add_f32_e32 v17, v17, v226
	v_cvt_pk_bf16_f32 v238, v29, v25
	v_cvt_pk_bf16_f32 v239, v21, v17
	v_mul_f32_e32 v29, v29, v29
	v_fmac_f32_e32 v29, v25, v25
	v_fmac_f32_e32 v29, v21, v21
	v_fmac_f32_e32 v29, v17, v17
	s_add_u32 s28, s24, 0xa1000
	s_addc_u32 s29, s25, 0
	global_store_dwordx2 v112, v[238:239], s[28:29]
	s_waitcnt vmcnt(31)
; __device__ __forceinline__ unsigned cvt_pk_bf16(float lo, float hi) { unsigned r; asm("v_cvt_pk_bf16_f32 %0, %1, %2" : "=v"(r) : "v"(lo), "v"(hi)); return r; }
;     __device__ __forceinline__ void operator()(const f32x4 (&acc)[2][2][4][2], const Unit& u, int wr, int wc, int fr, int fq, LAS unsigned char* xs, int wid, int lane) const {
;     ...
; #pragma unroll
;             for (int m = 0; m < 4; ++m) {
;                 const size_t row = (size_t)(row0 + ai * 128 + m * 16 + fr);
;                 float ss = 0.f;
; #pragma unroll
;                 for (int bj = 0; bj < 2; ++bj) {
;                     const size_t o = row * D + col0 + bj * 128;
;                     f32x4 x0, x1;
;                     if (SRCF32) { x0 = xf[m][bj][0]; x1 = xf[m][bj][1]; }
;                     else { const u32x4 r = raw[ai][m][bj]; x0 = (f32x4){bf_lo(r.x), bf_hi(r.x), bf_lo(r.y), bf_hi(r.y)}; x1 = (f32x4){bf_lo(r.z), bf_hi(r.z), bf_lo(r.w), bf_hi(r.w)}; }
;                     const f32x4 v0 = x0 + acc[ai][bj][m][0], v1 = x1 + acc[ai][bj][m][1];
;                     if (LAST) { *(f32x4*)(out + o) = v0; *(f32x4*)(out + o + 4) = v1; }
;                     else {
;                         ss += (v0[0] * v0[0] + v0[1] * v0[1]) + (v0[2] * v0[2] + v0[3] * v0[3]) + (v1[0] * v1[0] + v1[1] * v1[1]) + (v1[2] * v1[2] + v1[3] * v1[3]);
;                         u32x4 w; w.x = cvt_pk_bf16(v0[0], v0[1]); w.y = cvt_pk_bf16(v0[2], v0[3]); w.z = cvt_pk_bf16(v1[0], v1[1]); w.w = cvt_pk_bf16(v1[2], v1[3]); *(u32x4*)(xb + o) = w;
;                     }
;                 }
;                 if (!LAST) { ss += __shfl_xor(ss, 16); ss += __shfl_xor(ss, 32);
;                     if (fq == 0) P[(ai * 128 + wr * 64 + m * 16 + fr) * 4 + wc] = ss; }
	v_lshlrev_b32_e32 v126, 16, v204
	v_and_b32_e32 v226, 0xffff0000, v204
	v_add_f32_e32 v30, v30, v126
	v_add_f32_e32 v26, v26, v226
	v_lshlrev_b32_e32 v126, 16, v205
	v_and_b32_e32 v226, 0xffff0000, v205
	v_add_f32_e32 v22, v22, v126
	v_add_f32_e32 v18, v18, v226
	v_cvt_pk_bf16_f32 v240, v30, v26
	v_cvt_pk_bf16_f32 v241, v22, v18
	v_mul_f32_e32 v30, v30, v30
	v_fmac_f32_e32 v30, v26, v26
	v_fmac_f32_e32 v30, v22, v22
	v_fmac_f32_e32 v30, v18, v18
	s_add_u32 s26, s24, 0xa2000
	s_addc_u32 s27, s25, 0
	global_store_dwordx2 v112, v[240:241], s[26:27]
	s_waitcnt vmcnt(31)
	v_lshlrev_b32_e32 v126, 16, v206
	v_and_b32_e32 v226, 0xffff0000, v206
	v_add_f32_e32 v31, v31, v126
	v_add_f32_e32 v27, v27, v226
	v_lshlrev_b32_e32 v126, 16, v207
	v_and_b32_e32 v226, 0xffff0000, v207
	v_add_f32_e32 v23, v23, v126
	v_add_f32_e32 v19, v19, v226
	v_cvt_pk_bf16_f32 v242, v31, v27
	v_cvt_pk_bf16_f32 v243, v23, v19
	v_mul_f32_e32 v31, v31, v31
	v_fmac_f32_e32 v31, v27, v27
	v_fmac_f32_e32 v31, v23, v23
	v_fmac_f32_e32 v31, v19, v19
	s_add_u32 s28, s24, 0xa3000
	s_addc_u32 s29, s25, 0
	global_store_dwordx2 v112, v[242:243], s[28:29]
	s_waitcnt vmcnt(31)
	v_lshlrev_b32_e32 v126, 16, v208
	v_and_b32_e32 v226, 0xffff0000, v208
	v_add_f32_e32 v12, v12, v126
	v_add_f32_e32 v8, v8, v226
	v_lshlrev_b32_e32 v126, 16, v209
	v_and_b32_e32 v226, 0xffff0000, v209
	v_add_f32_e32 v4, v4, v126
	v_add_f32_e32 v0, v0, v226
	v_cvt_pk_bf16_f32 v236, v12, v8
	v_cvt_pk_bf16_f32 v237, v4, v0
	v_mul_f32_e32 v12, v12, v12
	v_fmac_f32_e32 v12, v8, v8
	v_fmac_f32_e32 v12, v4, v4
	v_fmac_f32_e32 v12, v0, v0
	s_add_u32 s26, s24, 0xb0000
	s_addc_u32 s27, s25, 0
	global_store_dwordx2 v112, v[236:237], s[26:27]
	s_waitcnt vmcnt(31)
	v_lshlrev_b32_e32 v126, 16, v210
	v_and_b32_e32 v226, 0xffff0000, v210
	v_add_f32_e32 v13, v13, v126
	v_add_f32_e32 v9, v9, v226
	v_lshlrev_b32_e32 v126, 16, v211
	v_and_b32_e32 v226, 0xffff0000, v211
	v_add_f32_e32 v5, v5, v126
	v_add_f32_e32 v1, v1, v226
	v_cvt_pk_bf16_f32 v238, v13, v9
	v_cvt_pk_bf16_f32 v239, v5, v1
	v_mul_f32_e32 v13, v13, v13
	v_fmac_f32_e32 v13, v9, v9
	v_fmac_f32_e32 v13, v5, v5
	v_fmac_f32_e32 v13, v1, v1
	s_add_u32 s28, s24, 0xb1000
	s_addc_u32 s29, s25, 0
	global_store_dwordx2 v112, v[238:239], s[28:29]
	s_waitcnt vmcnt(31)
	v_lshlrev_b32_e32 v126, 16, v212
	v_and_b32_e32 v226, 0xffff0000, v212
	v_add_f32_e32 v14, v14, v126
	v_add_f32_e32 v10, v10, v226
	v_lshlrev_b32_e32 v126, 16, v213
	v_and_b32_e32 v226, 0xffff0000, v213
	v_add_f32_e32 v6, v6, v126
	v_add_f32_e32 v2, v2, v226
	v_cvt_pk_bf16_f32 v240, v14, v10
	v_cvt_pk_bf16_f32 v241, v6, v2
	v_mul_f32_e32 v14, v14, v14
	v_fmac_f32_e32 v14, v10, v10
	v_fmac_f32_e32 v14, v6, v6
	v_fmac_f32_e32 v14, v2, v2
	s_add_u32 s26, s24, 0xb2000
	s_addc_u32 s27, s25, 0
	global_store_dwordx2 v112, v[240:241], s[26:27]
	s_waitcnt vmcnt(31)
	v_lshlrev_b32_e32 v126, 16, v214
	v_and_b32_e32 v226, 0xffff0000, v214
	v_add_f32_e32 v15, v15, v126
	v_add_f32_e32 v11, v11, v226
	v_lshlrev_b32_e32 v126, 16, v215
	v_and_b32_e32 v226, 0xffff0000, v215
	v_add_f32_e32 v7, v7, v126
	v_add_f32_e32 v3, v3, v226
	v_cvt_pk_bf16_f32 v242, v15, v11
	v_cvt_pk_bf16_f32 v243, v7, v3
	v_mul_f32_e32 v15, v15, v15
	v_fmac_f32_e32 v15, v11, v11
	v_fmac_f32_e32 v15, v7, v7
	v_fmac_f32_e32 v15, v3, v3
	s_add_u32 s28, s24, 0xb3000
	s_addc_u32 s29, s25, 0
	global_store_dwordx2 v112, v[242:243], s[28:29]
	v_add_f32_dpp v136, v136, v136 quad_perm:[1,0,3,2] row_mask:0xf bank_mask:0xf
	v_add_f32_dpp v137, v137, v137 quad_perm:[1,0,3,2] row_mask:0xf bank_mask:0xf
	v_add_f32_dpp v138, v138, v138 quad_perm:[1,0,3,2] row_mask:0xf bank_mask:0xf
	v_add_f32_dpp v139, v139, v139 quad_perm:[1,0,3,2] row_mask:0xf bank_mask:0xf
	v_add_f32_dpp v136, v136, v136 quad_perm:[2,3,0,1] row_mask:0xf bank_mask:0xf
	v_add_f32_dpp v137, v137, v137 quad_perm:[2,3,0,1] row_mask:0xf bank_mask:0xf
	v_add_f32_dpp v138, v138, v138 quad_perm:[2,3,0,1] row_mask:0xf bank_mask:0xf
	v_add_f32_dpp v139, v139, v139 quad_perm:[2,3,0,1] row_mask:0xf bank_mask:0xf
	v_add_f32_dpp v136, v136, v136 row_half_mirror row_mask:0xf bank_mask:0xf
	v_add_f32_dpp v137, v137, v137 row_half_mirror row_mask:0xf bank_mask:0xf
	v_add_f32_dpp v138, v138, v138 row_half_mirror row_mask:0xf bank_mask:0xf
	v_add_f32_dpp v139, v139, v139 row_half_mirror row_mask:0xf bank_mask:0xf
	v_add_f32_dpp v136, v136, v136 row_mirror row_mask:0xf bank_mask:0xf
	v_add_f32_dpp v137, v137, v137 row_mirror row_mask:0xf bank_mask:0xf
	v_add_f32_dpp v138, v138, v138 row_mirror row_mask:0xf bank_mask:0xf
	v_add_f32_dpp v139, v139, v139 row_mirror row_mask:0xf bank_mask:0xf
	v_add_f32_dpp v116, v116, v116 quad_perm:[1,0,3,2] row_mask:0xf bank_mask:0xf
	v_add_f32_dpp v117, v117, v117 quad_perm:[1,0,3,2] row_mask:0xf bank_mask:0xf
	v_add_f32_dpp v118, v118, v118 quad_perm:[1,0,3,2] row_mask:0xf bank_mask:0xf
	v_add_f32_dpp v119, v119, v119 quad_perm:[1,0,3,2] row_mask:0xf bank_mask:0xf
	v_add_f32_dpp v116, v116, v116 quad_perm:[2,3,0,1] row_mask:0xf bank_mask:0xf
	v_add_f32_dpp v117, v117, v117 quad_perm:[2,3,0,1] row_mask:0xf bank_mask:0xf
	v_add_f32_dpp v118, v118, v118 quad_perm:[2,3,0,1] row_mask:0xf bank_mask:0xf
	v_add_f32_dpp v119, v119, v119 quad_perm:[2,3,0,1] row_mask:0xf bank_mask:0xf
	v_add_f32_dpp v116, v116, v116 row_half_mirror row_mask:0xf bank_mask:0xf
	v_add_f32_dpp v117, v117, v117 row_half_mirror row_mask:0xf bank_mask:0xf
	v_add_f32_dpp v118, v118, v118 row_half_mirror row_mask:0xf bank_mask:0xf
	v_add_f32_dpp v119, v119, v119 row_half_mirror row_mask:0xf bank_mask:0xf
	v_add_f32_dpp v116, v116, v116 row_mirror row_mask:0xf bank_mask:0xf
	v_add_f32_dpp v117, v117, v117 row_mirror row_mask:0xf bank_mask:0xf
;     __device__ __forceinline__ void operator()(const f32x4 (&acc)[2][2][4][2], const Unit& u, int wr, int wc, int fr, int fq, LAS unsigned char* xs, int wid, int lane) const {
;     ...
;                 if (!LAST) { ss += __shfl_xor(ss, 16); ss += __shfl_xor(ss, 32);
;                     if (fq == 0) P[(ai * 128 + wr * 64 + m * 16 + fr) * 4 + wc] = ss; }
	v_add_f32_dpp v118, v118, v118 row_mirror row_mask:0xf bank_mask:0xf
	v_add_f32_dpp v119, v119, v119 row_mirror row_mask:0xf bank_mask:0xf
	v_add_f32_dpp v92, v92, v92 quad_perm:[1,0,3,2] row_mask:0xf bank_mask:0xf
	v_add_f32_dpp v93, v93, v93 quad_perm:[1,0,3,2] row_mask:0xf bank_mask:0xf
	v_add_f32_dpp v94, v94, v94 quad_perm:[1,0,3,2] row_mask:0xf bank_mask:0xf
	v_add_f32_dpp v95, v95, v95 quad_perm:[1,0,3,2] row_mask:0xf bank_mask:0xf
	v_add_f32_dpp v92, v92, v92 quad_perm:[2,3,0,1] row_mask:0xf bank_mask:0xf
	v_add_f32_dpp v93, v93, v93 quad_perm:[2,3,0,1] row_mask:0xf bank_mask:0xf
	v_add_f32_dpp v94, v94, v94 quad_perm:[2,3,0,1] row_mask:0xf bank_mask:0xf
	v_add_f32_dpp v95, v95, v95 quad_perm:[2,3,0,1] row_mask:0xf bank_mask:0xf
	v_add_f32_dpp v92, v92, v92 row_half_mirror row_mask:0xf bank_mask:0xf
	v_add_f32_dpp v93, v93, v93 row_half_mirror row_mask:0xf bank_mask:0xf
	v_add_f32_dpp v94, v94, v94 row_half_mirror row_mask:0xf bank_mask:0xf
	v_add_f32_dpp v95, v95, v95 row_half_mirror row_mask:0xf bank_mask:0xf
	v_add_f32_dpp v92, v92, v92 row_mirror row_mask:0xf bank_mask:0xf
	v_add_f32_dpp v93, v93, v93 row_mirror row_mask:0xf bank_mask:0xf
	v_add_f32_dpp v94, v94, v94 row_mirror row_mask:0xf bank_mask:0xf
	v_add_f32_dpp v95, v95, v95 row_mirror row_mask:0xf bank_mask:0xf
	v_add_f32_dpp v76, v76, v76 quad_perm:[1,0,3,2] row_mask:0xf bank_mask:0xf
	v_add_f32_dpp v77, v77, v77 quad_perm:[1,0,3,2] row_mask:0xf bank_mask:0xf
	v_add_f32_dpp v78, v78, v78 quad_perm:[1,0,3,2] row_mask:0xf bank_mask:0xf
	v_add_f32_dpp v79, v79, v79 quad_perm:[1,0,3,2] row_mask:0xf bank_mask:0xf
	v_add_f32_dpp v76, v76, v76 quad_perm:[2,3,0,1] row_mask:0xf bank_mask:0xf
	v_add_f32_dpp v77, v77, v77 quad_perm:[2,3,0,1] row_mask:0xf bank_mask:0xf
	v_add_f32_dpp v78, v78, v78 quad_perm:[2,3,0,1] row_mask:0xf bank_mask:0xf
	v_add_f32_dpp v79, v79, v79 quad_perm:[2,3,0,1] row_mask:0xf bank_mask:0xf
	v_add_f32_dpp v76, v76, v76 row_half_mirror row_mask:0xf bank_mask:0xf
	v_add_f32_dpp v77, v77, v77 row_half_mirror row_mask:0xf bank_mask:0xf
	v_add_f32_dpp v78, v78, v78 row_half_mirror row_mask:0xf bank_mask:0xf
	v_add_f32_dpp v79, v79, v79 row_half_mirror row_mask:0xf bank_mask:0xf
	v_add_f32_dpp v76, v76, v76 row_mirror row_mask:0xf bank_mask:0xf
	v_add_f32_dpp v77, v77, v77 row_mirror row_mask:0xf bank_mask:0xf
	v_add_f32_dpp v78, v78, v78 row_mirror row_mask:0xf bank_mask:0xf
	v_add_f32_dpp v79, v79, v79 row_mirror row_mask:0xf bank_mask:0xf
	v_add_f32_dpp v60, v60, v60 quad_perm:[1,0,3,2] row_mask:0xf bank_mask:0xf
	v_add_f32_dpp v61, v61, v61 quad_perm:[1,0,3,2] row_mask:0xf bank_mask:0xf
	v_add_f32_dpp v62, v62, v62 quad_perm:[1,0,3,2] row_mask:0xf bank_mask:0xf
	v_add_f32_dpp v63, v63, v63 quad_perm:[1,0,3,2] row_mask:0xf bank_mask:0xf
	v_add_f32_dpp v60, v60, v60 quad_perm:[2,3,0,1] row_mask:0xf bank_mask:0xf
	v_add_f32_dpp v61, v61, v61 quad_perm:[2,3,0,1] row_mask:0xf bank_mask:0xf
	v_add_f32_dpp v62, v62, v62 quad_perm:[2,3,0,1] row_mask:0xf bank_mask:0xf
	v_add_f32_dpp v63, v63, v63 quad_perm:[2,3,0,1] row_mask:0xf bank_mask:0xf
	v_add_f32_dpp v60, v60, v60 row_half_mirror row_mask:0xf bank_mask:0xf
	v_add_f32_dpp v61, v61, v61 row_half_mirror row_mask:0xf bank_mask:0xf
	v_add_f32_dpp v62, v62, v62 row_half_mirror row_mask:0xf bank_mask:0xf
	v_add_f32_dpp v63, v63, v63 row_half_mirror row_mask:0xf bank_mask:0xf
	v_add_f32_dpp v60, v60, v60 row_mirror row_mask:0xf bank_mask:0xf
	v_add_f32_dpp v61, v61, v61 row_mirror row_mask:0xf bank_mask:0xf
	v_add_f32_dpp v62, v62, v62 row_mirror row_mask:0xf bank_mask:0xf
	v_add_f32_dpp v63, v63, v63 row_mirror row_mask:0xf bank_mask:0xf
	v_add_f32_dpp v44, v44, v44 quad_perm:[1,0,3,2] row_mask:0xf bank_mask:0xf
	v_add_f32_dpp v45, v45, v45 quad_perm:[1,0,3,2] row_mask:0xf bank_mask:0xf
	v_add_f32_dpp v46, v46, v46 quad_perm:[1,0,3,2] row_mask:0xf bank_mask:0xf
	v_add_f32_dpp v47, v47, v47 quad_perm:[1,0,3,2] row_mask:0xf bank_mask:0xf
	v_add_f32_dpp v44, v44, v44 quad_perm:[2,3,0,1] row_mask:0xf bank_mask:0xf
	v_add_f32_dpp v45, v45, v45 quad_perm:[2,3,0,1] row_mask:0xf bank_mask:0xf
	v_add_f32_dpp v46, v46, v46 quad_perm:[2,3,0,1] row_mask:0xf bank_mask:0xf
	v_add_f32_dpp v47, v47, v47 quad_perm:[2,3,0,1] row_mask:0xf bank_mask:0xf
	v_add_f32_dpp v44, v44, v44 row_half_mirror row_mask:0xf bank_mask:0xf
	v_add_f32_dpp v45, v45, v45 row_half_mirror row_mask:0xf bank_mask:0xf
	v_add_f32_dpp v46, v46, v46 row_half_mirror row_mask:0xf bank_mask:0xf
	v_add_f32_dpp v47, v47, v47 row_half_mirror row_mask:0xf bank_mask:0xf
; #define LAS __attribute__((address_space(3)))
; #define LDS_WAIT() asm volatile("s_waitcnt lgkmcnt(0)" ::: "memory")
;     __device__ __forceinline__ void operator()(const f32x4 (&acc)[2][2][4][2], const Unit& u, int wr, int wc, int fr, int fq, LAS unsigned char* xs, int wid, int lane) const {
;     ...
;                 if (!LAST) { ss += __shfl_xor(ss, 16); ss += __shfl_xor(ss, 32);
;                     if (fq == 0) P[(ai * 128 + wr * 64 + m * 16 + fr) * 4 + wc] = ss; }
;             }
;             if (SRCF32) __builtin_amdgcn_sched_barrier(0);
;         }
;         if (!LAST) {
;             LDS_WAIT();
;             __builtin_amdgcn_s_barrier();
;             const int tid = wid * 64 + lane;
;             if (tid < 256) { const f32x4 v = *(const LAS f32x4*)(P + tid * 4); rss[(size_t)(u.pm * 256 + tid) * 8 + u.pn] = (v[0] + v[1]) + (v[2] + v[3]); }
;             LDS_WAIT();
	v_add_f32_dpp v44, v44, v44 row_mirror row_mask:0xf bank_mask:0xf
	v_add_f32_dpp v45, v45, v45 row_mirror row_mask:0xf bank_mask:0xf
	v_add_f32_dpp v46, v46, v46 row_mirror row_mask:0xf bank_mask:0xf
	v_add_f32_dpp v47, v47, v47 row_mirror row_mask:0xf bank_mask:0xf
	v_add_f32_dpp v28, v28, v28 quad_perm:[1,0,3,2] row_mask:0xf bank_mask:0xf
	v_add_f32_dpp v29, v29, v29 quad_perm:[1,0,3,2] row_mask:0xf bank_mask:0xf
	v_add_f32_dpp v30, v30, v30 quad_perm:[1,0,3,2] row_mask:0xf bank_mask:0xf
	v_add_f32_dpp v31, v31, v31 quad_perm:[1,0,3,2] row_mask:0xf bank_mask:0xf
	v_add_f32_dpp v28, v28, v28 quad_perm:[2,3,0,1] row_mask:0xf bank_mask:0xf
	v_add_f32_dpp v29, v29, v29 quad_perm:[2,3,0,1] row_mask:0xf bank_mask:0xf
	v_add_f32_dpp v30, v30, v30 quad_perm:[2,3,0,1] row_mask:0xf bank_mask:0xf
	v_add_f32_dpp v31, v31, v31 quad_perm:[2,3,0,1] row_mask:0xf bank_mask:0xf
	v_add_f32_dpp v28, v28, v28 row_half_mirror row_mask:0xf bank_mask:0xf
	v_add_f32_dpp v29, v29, v29 row_half_mirror row_mask:0xf bank_mask:0xf
	v_add_f32_dpp v30, v30, v30 row_half_mirror row_mask:0xf bank_mask:0xf
	v_add_f32_dpp v31, v31, v31 row_half_mirror row_mask:0xf bank_mask:0xf
	v_add_f32_dpp v28, v28, v28 row_mirror row_mask:0xf bank_mask:0xf
	v_add_f32_dpp v29, v29, v29 row_mirror row_mask:0xf bank_mask:0xf
	v_add_f32_dpp v30, v30, v30 row_mirror row_mask:0xf bank_mask:0xf
	v_add_f32_dpp v31, v31, v31 row_mirror row_mask:0xf bank_mask:0xf
	v_add_f32_dpp v12, v12, v12 quad_perm:[1,0,3,2] row_mask:0xf bank_mask:0xf
	v_add_f32_dpp v13, v13, v13 quad_perm:[1,0,3,2] row_mask:0xf bank_mask:0xf
	v_add_f32_dpp v14, v14, v14 quad_perm:[1,0,3,2] row_mask:0xf bank_mask:0xf
	v_add_f32_dpp v15, v15, v15 quad_perm:[1,0,3,2] row_mask:0xf bank_mask:0xf
	v_add_f32_dpp v12, v12, v12 quad_perm:[2,3,0,1] row_mask:0xf bank_mask:0xf
	v_add_f32_dpp v13, v13, v13 quad_perm:[2,3,0,1] row_mask:0xf bank_mask:0xf
	v_add_f32_dpp v14, v14, v14 quad_perm:[2,3,0,1] row_mask:0xf bank_mask:0xf
	v_add_f32_dpp v15, v15, v15 quad_perm:[2,3,0,1] row_mask:0xf bank_mask:0xf
	v_add_f32_dpp v12, v12, v12 row_half_mirror row_mask:0xf bank_mask:0xf
	v_add_f32_dpp v13, v13, v13 row_half_mirror row_mask:0xf bank_mask:0xf
	v_add_f32_dpp v14, v14, v14 row_half_mirror row_mask:0xf bank_mask:0xf
	v_add_f32_dpp v15, v15, v15 row_half_mirror row_mask:0xf bank_mask:0xf
	v_add_f32_dpp v12, v12, v12 row_mirror row_mask:0xf bank_mask:0xf
	v_add_f32_dpp v13, v13, v13 row_mirror row_mask:0xf bank_mask:0xf
	v_add_f32_dpp v14, v14, v14 row_mirror row_mask:0xf bank_mask:0xf
	v_add_f32_dpp v15, v15, v15 row_mirror row_mask:0xf bank_mask:0xf
	s_mov_b32 exec_lo, 0x10001
	s_mov_b32 exec_hi, 0x10001
	ds_write_b32 v227, v136 offset:0
	ds_write_b32 v227, v137 offset:16
	ds_write_b32 v227, v138 offset:32
	ds_write_b32 v227, v139 offset:48
	ds_write_b32 v227, v116 offset:256
	ds_write_b32 v227, v117 offset:272
	ds_write_b32 v227, v118 offset:288
	ds_write_b32 v227, v119 offset:304
	ds_write_b32 v227, v92 offset:512
	ds_write_b32 v227, v93 offset:528
	ds_write_b32 v227, v94 offset:544
	ds_write_b32 v227, v95 offset:560
	ds_write_b32 v227, v76 offset:768
	ds_write_b32 v227, v77 offset:784
	ds_write_b32 v227, v78 offset:800
	ds_write_b32 v227, v79 offset:816
	ds_write_b32 v227, v60 offset:2048
	ds_write_b32 v227, v61 offset:2064
	ds_write_b32 v227, v62 offset:2080
	ds_write_b32 v227, v63 offset:2096
	ds_write_b32 v227, v44 offset:2304
	ds_write_b32 v227, v45 offset:2320
	ds_write_b32 v227, v46 offset:2336
	ds_write_b32 v227, v47 offset:2352
	ds_write_b32 v227, v28 offset:2560
	ds_write_b32 v227, v29 offset:2576
	ds_write_b32 v227, v30 offset:2592
	ds_write_b32 v227, v31 offset:2608
	ds_write_b32 v227, v12 offset:2816
	ds_write_b32 v227, v13 offset:2832
	ds_write_b32 v227, v14 offset:2848
	ds_write_b32 v227, v15 offset:2864
	s_mov_b64 exec, -1
	s_waitcnt lgkmcnt(0)
	s_barrier
	v_cmp_gt_u32_e32 vcc, 0x100, v254
	s_and_saveexec_b64 s[26:27], vcc
	v_lshlrev_b32_e32 v126, 4, v254
	v_add_u32_e32 v126, 0x20000, v126
	ds_read_b128 v[236:239], v126
	v_add_u32_e32 v226, s32, v254
	v_lshlrev_b32_e32 v226, 5, v226
	s_lshl_b32 s18, s48, 2
	v_add_u32_e32 v226, s18, v226
	s_waitcnt lgkmcnt(0)
	v_add_f32_e32 v236, v236, v237
	v_add_f32_e32 v238, v238, v239
	v_add_f32_e32 v236, v236, v238
	global_store_dword v226, v236, s[44:45]
	s_or_b64 exec, exec, s[26:27]
	s_andn2_b64 vcc, exec, s[12:13]
	s_mov_b64 s[12:13], -1
	s_cbranch_vccnz .LBB0_881
	s_andn2_b64 vcc, exec, s[50:51]
	s_cbranch_vccnz .LBB0_880
	s_barrier
	s_branch .LBB0_880

; #define PG8_STAGE(bufoff, gbase, voff) do { _Pragma("unroll") for (int _i = 0; _i < 2; ++_i) \
;         __builtin_amdgcn_global_load_lds((const unsigned*)((const char*)(gbase) + (voff)[_i]), (LAS unsigned*)(lds + (bufoff) + ldsw + _i * 8192), 16, 0, 0); } while (0)
; #define PG8_WAIT_V(n) asm volatile("s_waitcnt vmcnt(" #n ")" ::: "memory")
; #define PG8_BAR __builtin_amdgcn_s_barrier()
; template <class Epi, class Sched>
; __device__ __forceinline__ void gemm_phase(LAS unsigned char* lds, const int K, const int lda, const int ldb, const Sched& S, const Epi& E) {
;     ...
;     const int wid = __builtin_amdgcn_readfirstlane(tid >> 6), lane = tid & 63, wr = wid >> 2, wc = wid & 3, fr = lane & 15, fq = lane >> 4;
;     const int nt = K / BK;
;     unsigned voffA[2], voffB[2];
; #pragma unroll
;     for (int i = 0; i < 2; ++i) { int R, C; stage_rc(tid * 16 + i * 8192, R, C); const int Rb = (R & ~31) + perm32(R & 31);
;         voffA[i] = (unsigned)(R * lda + C) * 2u; voffB[i] = (unsigned)(Rb * ldb + C) * 2u; }
;     const size_t kstep = (size_t)(BK * 2);
;     const size_t hA = (size_t)HALF * lda * 2, hB = (size_t)HALF * ldb * 2;
;     const unsigned ldsw = (unsigned)wid * 1024u;
;     const int aoff = lds_byte(wr * 64 + fr, fq * 8), boff = lds_byte(wc * 32 + fr, fq * 8);
;     ...
;     Unit cur, nxt; int ui = 0;
;     if (!S.next(0, cur)) return;
;     f32x4 acc[2][2][4][2];
; #pragma unroll
;     for (int a = 0; a < 2; ++a)
; #pragma unroll
;         for (int b = 0; b < 2; ++b)
; #pragma unroll
;             for (int m = 0; m < 4; ++m)
; #pragma unroll
;                 for (int n = 0; n < 2; ++n) acc[a][b][m][n] = (f32x4){0.f, 0.f, 0.f, 0.f};
;     bf16x8 At[4][2], B0[2][2], B1[2][2];
;     const char* cA = S.aptr(cur); const char* cB = S.bptr(cur);
;     PG8_STAGE(PG8_SB(0, 0), cB, voffB); PG8_STAGE(PG8_SB(0, 1), cB + hB, voffB); PG8_STAGE(PG8_SA(0, 0), cA, voffA); PG8_STAGE(PG8_SA(0, 1), cA + hA, voffA);
;     if (wr == 1) PG8_BAR;
;     PG8_WAIT_V(2); PG8_BAR;
;     PG8_STAGE(PG8_SB(1, 0), cB + kstep, voffB); PG8_STAGE(PG8_SA(1, 0), cA + kstep, voffA); PG8_STAGE(PG8_SB(1, 1), cB + hB + kstep, voffB);
;     PG8_WAIT_V(6); PG8_BAR;
.LBB0_1359:
	v_readlane_b32 s4, v255, 24
	v_readlane_b32 s5, v255, 25
	s_and_b64 vcc, exec, s[4:5]
	s_cbranch_vccnz .LBB0_1397
	v_ashrrev_i32_e32 v1, 31, v8
	v_lshrrev_b32_e32 v1, 26, v1
	v_add_u32_e32 v1, v8, v1
	v_ashrrev_i32_e32 v9, 6, v1
	v_bfe_i32 v1, v8, 27, 1
	v_lshlrev_b32_e32 v0, 4, v8
	v_lshrrev_b32_e32 v1, 22, v1
	v_add_u32_e32 v1, v0, v1
	v_and_b32_e32 v1, 0xfffffc00, v1
	v_sub_u32_e32 v1, v0, v1
	v_lshrrev_b32_e32 v2, 4, v1
	v_bitop3_b32 v1, v2, v1, 32 bitop3:0x6c
	v_ashrrev_i32_e32 v3, 31, v1
	v_lshrrev_b32_e32 v3, 26, v3
	v_add_u32_e32 v3, v1, v3
	v_lshlrev_b32_e32 v2, 3, v9
	v_ashrrev_i32_e32 v10, 6, v3
	v_and_b32_e32 v3, 0xc0, v3
	v_and_b32_e32 v2, -16, v2
	v_sub_u32_e32 v1, v1, v3
	v_mov_b32_e32 v3, 1
	v_add_u32_e32 v2, v10, v2
	v_ashrrev_i16_sdwa v1, v3, sext(v1) dst_sel:DWORD dst_unused:UNUSED_PAD src0_sel:DWORD src1_sel:BYTE_0
	v_lshlrev_b32_e32 v4, 5, v9
	v_bfe_i32 v11, v1, 0, 16
	v_lshlrev_b32_e32 v1, 1, v2
	v_lshrrev_b32_e32 v5, 2, v2
	v_and_b32_e32 v6, 3, v10
	s_mov_b32 s1, 0xfffe0
	v_and_b32_e32 v4, 32, v4
	v_and_b32_e32 v1, 24, v1
	v_and_b32_e32 v5, 4, v5
	v_and_or_b32 v6, v2, s1, v6
	v_or3_b32 v1, v6, v5, v1
	v_add_lshl_u32 v4, v4, v11, 1
	v_add_u32_e32 v0, 0x2000, v0
	v_and_b32_e32 v106, 63, v254
	v_lshrrev_b32_e32 v107, 6, v254
	v_lshrrev_b32_e32 v108, 3, v106
	v_lshl_add_u32 v109, v107, 3, v108
	v_and_b32_e32 v110, 1, v107
	v_bfe_u32 v111, v106, 4, 2
	v_lshl_add_u32 v111, v110, 2, v111
	v_and_b32_e32 v101, 7, v106
	v_xor_b32_e32 v111, v101, v111
	v_lshlrev_b32_e32 v111, 4, v111
	v_lshl_add_u32 v100, v109, 12, v111
	v_add_u32_e32 v101, 0x40000, v100
	v_lshrrev_b32_e32 v109, 5, v106
	v_lshlrev_b32_e32 v109, 3, v109
	v_lshl_add_u32 v109, v110, 4, v109
	v_bfe_u32 v110, v107, 1, 1
	v_lshl_add_u32 v109, v110, 2, v109
	v_and_b32_e32 v110, 3, v108
	v_add_u32_e32 v109, v109, v110
	v_lshrrev_b32_e32 v110, 2, v107
	v_lshl_add_u32 v109, v110, 5, v109
	v_lshl_add_u32 v102, v109, 12, v111
	v_add_u32_e32 v103, 0x40000, v102
	v_and_b32_e32 v106, 15, v254
	v_bfe_u32 v108, v254, 4, 2
	v_bfe_u32 v109, v254, 1, 3
	v_xor_b32_e32 v108, v108, v109
	v_lshlrev_b32_e32 v108, 4, v108
	v_lshl_add_u32 v108, v106, 7, v108
	v_lshrrev_b32_e32 v109, 8, v254
	v_lshl_add_u32 v104, v109, 13, v108
	v_and_b32_e32 v109, 3, v107
	v_lshl_add_u32 v105, v109, 13, v108
	v_and_b32_e32 v106, 63, v254
	v_lshrrev_b32_e32 v107, 6, v254
	v_lshrrev_b32_e32 v108, 3, v106
	v_and_b32_e32 v110, 1, v107
	v_bfe_u32 v111, v106, 4, 2
	v_lshl_add_u32 v111, v110, 2, v111
	v_and_b32_e32 v109, 7, v106
	v_xor_b32_e32 v111, v109, v111
	v_lshlrev_b32_e32 v111, 4, v111
	v_lshlrev_b32_e32 v109, 5, v110
	v_lshl_add_u32 v109, v108, 2, v109
	v_bfe_u32 v110, v107, 1, 2
	v_add_u32_e32 v109, v109, v110
	v_lshl_add_u32 v102, v109, 12, v111
	v_add_u32_e32 v103, 0x40000, v102
	v_mov_b32_e32 v186, v102
	v_ashrrev_i32_e32 v1, 31, v0
	v_lshrrev_b32_e32 v1, 22, v1
	v_add_u32_e32 v1, v0, v1
	v_ashrrev_i32_e32 v12, 10, v1
	v_mul_i32_i24_e32 v1, 0x400, v12
	v_sub_u32_e32 v0, v0, v1
	v_lshrrev_b32_e32 v1, 4, v0
	v_bitop3_b32 v0, v1, v0, 32 bitop3:0x6c
	v_mov_b32_e32 v184, v100
	v_ashrrev_i32_e32 v2, 31, v0
	v_lshrrev_b32_e32 v2, 26, v2
	v_add_u32_e32 v2, v0, v2
	v_lshlrev_b32_e32 v1, 3, v12
	v_ashrrev_i32_e32 v13, 6, v2
	v_and_b32_e32 v2, 0xc0, v2
	v_and_b32_e32 v1, -16, v1
	v_sub_u32_e32 v0, v0, v2
	s_ashr_i32 s8, s0, 6
	v_add_u32_e32 v1, v13, v1
	v_ashrrev_i16_sdwa v0, v3, sext(v0) dst_sel:DWORD dst_unused:UNUSED_PAD src0_sel:DWORD src1_sel:BYTE_0
	v_and_b32_e32 v3, 3, v13
	s_ashr_i32 s51, s50, 31
	s_ashr_i32 s17, s16, 31
	v_and_or_b32 v3, v1, s1, v3
	s_ashr_i32 s9, s0, 8
	s_lshl_b32 s1, s8, 10
	s_lshl_b64 s[4:5], s[50:51], 20
	s_lshl_b64 s[6:7], s[16:17], 20
	s_add_u32 s52, s36, s6
	v_lshlrev_b32_e32 v4, 5, v12
	v_bfe_i32 v14, v0, 0, 16
	v_lshlrev_b32_e32 v0, 1, v1
	v_lshrrev_b32_e32 v2, 2, v1
	s_addc_u32 s53, s37, s7
	s_add_i32 s2, s1, 0
	v_and_b32_e32 v4, 32, v4
	v_and_b32_e32 v0, 24, v0
	v_and_b32_e32 v2, 4, v2
	s_add_i32 m0, s2, 0x10000
	v_or3_b32 v0, v3, v2, v0
	v_add_lshl_u32 v2, v4, v14, 1
	global_load_lds_dwordx4 v186, s[52:53]
	s_add_i32 m0, s2, 0x12000
	v_mov_b32_e32 v190, v103
	s_add_u32 s6, s52, 0x80000
	global_load_lds_dwordx4 v190, s[52:53]
	s_addc_u32 s7, s53, 0
	s_add_i32 m0, s2, 0x14000
	v_mov_b32_e32 v188, v101
	global_load_lds_dwordx4 v186, s[6:7]
	s_add_i32 m0, s2, 0x16000
	s_add_u32 s54, s28, s4
	s_addc_u32 s55, s29, s5
	s_add_i32 s4, s2, 0x2000
	global_load_lds_dwordx4 v190, s[6:7]
	s_mov_b32 m0, s2
	s_add_u32 s10, s54, 0x80000
	global_load_lds_dwordx4 v184, s[54:55]
	s_mov_b32 m0, s4
	s_addc_u32 s11, s55, 0
	s_add_i32 s5, s2, 0x4000
	global_load_lds_dwordx4 v188, s[54:55]
	s_mov_b32 m0, s5
	s_add_i32 s6, s2, 0x6000
	global_load_lds_dwordx4 v184, s[10:11]
	s_mov_b32 m0, s6
	v_mov_b32_e32 v187, 0
	global_load_lds_dwordx4 v188, s[10:11]
	v_mov_b32_e32 v191, v187
	v_mov_b32_e32 v185, v187
	v_mov_b32_e32 v189, v187
	s_cmp_eq_u32 s9, 1
	s_mov_b32 s7, 0
	v_lshl_add_u64 v[6:7], s[52:53], 0, v[186:187]
	v_lshl_add_u64 v[4:5], s[52:53], 0, v[190:191]
	v_lshl_add_u64 v[0:1], s[54:55], 0, v[184:185]
	s_cselect_b64 s[18:19], -1, 0
	s_cmp_lg_u32 s9, 1
	v_lshl_add_u64 v[2:3], s[54:55], 0, v[188:189]
	s_cbranch_scc1 .LBB0_1362
	s_barrier
; #define LAS __attribute__((address_space(3)))
; #define LDS_WAIT() asm volatile("s_waitcnt lgkmcnt(0)" ::: "memory")
; #define PG8_STAGE(bufoff, gbase, voff) do { _Pragma("unroll") for (int _i = 0; _i < 2; ++_i) \
;         __builtin_amdgcn_global_load_lds((const unsigned*)((const char*)(gbase) + (voff)[_i]), (LAS unsigned*)(lds + (bufoff) + ldsw + _i * 8192), 16, 0, 0); } while (0)
; #define PG8_WAIT_V(n) asm volatile("s_waitcnt vmcnt(" #n ")" ::: "memory")
; #define PG8_BAR __builtin_amdgcn_s_barrier()
; template <class Epi, class Sched>
; __device__ __forceinline__ void gemm_phase(LAS unsigned char* lds, const int K, const int lda, const int ldb, const Sched& S, const Epi& E) {
;     ...
;     PG8_STAGE(PG8_SB(0, 0), cB, voffB); PG8_STAGE(PG8_SB(0, 1), cB + hB, voffB); PG8_STAGE(PG8_SA(0, 0), cA, voffA); PG8_STAGE(PG8_SA(0, 1), cA + hA, voffA);
;     if (wr == 1) PG8_BAR;
;     PG8_WAIT_V(2); PG8_BAR;
;     PG8_STAGE(PG8_SB(1, 0), cB + kstep, voffB); PG8_STAGE(PG8_SA(1, 0), cA + kstep, voffA); PG8_STAGE(PG8_SB(1, 1), cB + hB + kstep, voffB);
;     PG8_WAIT_V(6); PG8_BAR;
;     for (;;) {
;     __device__ __forceinline__ void operator()(const f32x4 (&acc)[2][2][4][2], const Unit& u, int wr, int wc, int fr, int fq, LAS unsigned char* xs, int wid, int lane) const {
;     ...
;         if (!LAST) {
;             LDS_WAIT();
;             __builtin_amdgcn_s_barrier();
;             const int tid = wid * 64 + lane;
;             if (tid < 256) { const f32x4 v = *(const LAS f32x4*)(P + tid * 4); rss[(size_t)(u.pm * 256 + tid) * 8 + u.pn] = (v[0] + v[1]) + (v[2] + v[3]); }
;             LDS_WAIT();
.LBB0_1362:
	s_mov_b64 s[20:21], 0x80
	s_and_b32 s8, s8, 3
	s_add_i32 m0, s2, 0x18000
	v_lshl_add_u64 v[6:7], v[6:7], 0, s[20:21]
	s_lshl_b32 s12, s9, 13
	s_lshl_b32 s13, s8, 12
	s_waitcnt vmcnt(2)
	s_barrier
	global_load_lds_dwordx4 v[6:7], off
	v_lshl_add_u64 v[4:5], v[4:5], 0, s[20:21]
	s_add_i32 m0, s2, 0x1a000
	s_add_i32 s14, s2, 0x8000
	s_add_i32 s15, s2, 0xa000
	global_load_lds_dwordx4 v[4:5], off
	v_lshl_add_u64 v[0:1], v[0:1], 0, s[20:21]
	s_mov_b32 m0, s14
	s_add_u32 s10, s52, 0x80080
	global_load_lds_dwordx4 v[0:1], off
	v_lshl_add_u64 v[0:1], v[2:3], 0, s[20:21]
	s_mov_b32 m0, s15
	s_addc_u32 s11, s53, 0
	global_load_lds_dwordx4 v[0:1], off
	s_add_i32 m0, s2, 0x1c000
	v_lshl_add_u64 v[0:1], s[10:11], 0, v[186:187]
	global_load_lds_dwordx4 v[0:1], off
	v_lshl_add_u64 v[0:1], s[10:11], 0, v[190:191]
	s_add_i32 m0, s2, 0x1e000
	v_lshrrev_b32_e32 v2, 1, v8
	global_load_lds_dwordx4 v[0:1], off
	v_and_b32_e32 v1, 15, v8
	v_and_b32_e32 v2, 24, v2
	v_and_b32_e32 v3, 48, v8
	v_lshl_or_b32 v216, s9, 6, v1
	v_lshl_or_b32 v1, v1, 6, v3
	v_lshlrev_b32_e32 v3, 2, v8
	v_lshl_or_b32 v218, s8, 5, v2
	v_lshlrev_b32_e32 v2, 15, v12
	v_and_b32_e32 v3, 32, v3
	v_and_b32_e32 v2, 0xffff0000, v2
	v_bitop3_b32 v4, v1, s12, v3 bitop3:0xde
	v_mov_b32_e32 v217, v105
	v_lshl_add_u32 v2, v13, 12, v2
	v_and_b32_e32 v3, 1, v12
	v_lshl_or_b32 v2, v3, 6, v2
	v_mov_b32_e32 v192, v101
	v_lshlrev_b32_e32 v2, 15, v9
	s_cmpk_lt_u32 s0, 0x100
	s_movk_i32 s11, 0xffc0
	v_mov_b32_e32 v1, s0
	v_and_b32_e32 v2, 0xffff0000, v2
	s_cselect_b64 s[22:23], -1, 0
	s_lshl_b32 s8, s8, 2
	v_bfi_b32 v219, s11, v1, v8
	v_lshl_add_u32 v2, v10, 12, v2
	v_and_b32_e32 v3, 1, v9
	v_and_b32_e32 v0, 63, v8
	s_waitcnt vmcnt(6)
	s_add_i32 s8, s8, 0
	v_lshlrev_b32_e32 v1, 4, v219
	v_lshl_or_b32 v2, v3, 6, v2
	s_movk_i32 s10, 0x100
	s_add_i32 s12, s8, 0x20000
	v_cmp_gt_u32_e64 s[8:9], 16, v0
	v_lshlrev_b32_e32 v0, 4, v216
	v_mov_b32_e32 v194, v100
	s_add_i32 s0, 0, 0x10000
	s_add_i32 s34, 0, 0x14000
	v_mbcnt_lo_u32_b32 v2, -1, 0
	v_add_u32_e32 v1, 0, v1
	v_cmp_gt_i32_e64 s[10:11], s10, v219
	s_ashr_i32 s30, s3, 31
	s_ashr_i32 s31, s33, 31
	v_mov_b32_e32 v193, v187
	v_mov_b32_e32 v195, v187
	v_mov_b64_e32 v[196:197], 0x400
	v_mov_b64_e32 v[198:199], 0x3ff
	v_add_u32_e32 v220, s0, v217
	v_add_u32_e32 v221, 0x11000, v217
	v_mov_b32_e32 v222, v104
	v_xor_b32_e32 v246, 64, v222
	v_xor_b32_e32 v247, 64, v220
	v_xor_b32_e32 v248, 64, v221
	v_xor_b32_e32 v249, 64, v217
	v_mbcnt_hi_u32_b32 v223, -1, v2
	v_add_u32_e32 v224, 0x20000, v1
	v_add_u32_e32 v225, s12, v0
	s_barrier
	s_branch .LBB0_1365

; #define PG8_STAGE(bufoff, gbase, voff) do { _Pragma("unroll") for (int _i = 0; _i < 2; ++_i) \
;         __builtin_amdgcn_global_load_lds((const unsigned*)((const char*)(gbase) + (voff)[_i]), (LAS unsigned*)(lds + (bufoff) + ldsw + _i * 8192), 16, 0, 0); } while (0)
; #define PG8_LDA(dst, b, h) do { _Pragma("unroll") for (int m = 0; m < 4; ++m) _Pragma("unroll") for (int k = 0; k < 2; ++k) dst[m][k] = *(const LAS bf16x8*)(lds + PG8_SA(b, h) + aoff + m * 2048 + k * 1024); } while (0)
; #define PG8_LDB(dst, b, h) do { _Pragma("unroll") for (int n = 0; n < 2; ++n) _Pragma("unroll") for (int k = 0; k < 2; ++k) dst[n][k] = *(const LAS bf16x8*)(lds + PG8_SB(b, h) + boff + n * 2048 + k * 1024); } while (0)
; #define PG8_MMA(ai, bj, At, Bt) do { __builtin_amdgcn_s_setprio(1); _Pragma("unroll") for (int m = 0; m < 4; ++m) _Pragma("unroll") for (int n = 0; n < 2; ++n) _Pragma("unroll") for (int k = 0; k < 2; ++k) \
;         acc[ai][bj][m][n] = __builtin_amdgcn_mfma_f32_16x16x32_bf16(Bt[n][k], At[m][k], acc[ai][bj][m][n], 0, 0, 0); __builtin_amdgcn_s_setprio(0); } while (0)
; #define PG8_WAIT_V(n) asm volatile("s_waitcnt vmcnt(" #n ")" ::: "memory")
; #define PG8_WAIT_L(n) asm volatile("s_waitcnt lgkmcnt(" #n ")" ::: "memory")
; #define PG8_BAR __builtin_amdgcn_s_barrier()
; #define PG8_SCHED __builtin_amdgcn_sched_barrier(0)
; template <class Epi, class Sched>
; __device__ __forceinline__ void gemm_phase(LAS unsigned char* lds, const int K, const int lda, const int ldb, const Sched& S, const Epi& E) {
;     ...
;             PG8_LDB(B0, 0, 0); PG8_LDB(B1, 0, 1); PG8_SCHED; PG8_LDA(At, 0, 0); PG8_STAGE(PG8_SA(1, 1), a1 + hA, voffA);
;             PG8_WAIT_V(8); PG8_WAIT_L(0); PG8_BAR; PG8_MMA(0, 0, At, B0); PG8_MMA(0, 1, At, B1); PG8_BAR; PG8_SCHED;
;             PG8_LDA(At, 0, 1); PG8_STAGE(PG8_SB(0, 0), b2, voffB); PG8_STAGE(PG8_SB(0, 1), b2 + hB, voffB); PG8_STAGE(PG8_SA(0, 0), a2, voffA);
;             PG8_WAIT_V(8); PG8_WAIT_L(0); PG8_BAR; PG8_MMA(1, 0, At, B0); PG8_MMA(1, 1, At, B1); PG8_BAR; PG8_SCHED;
.LBB0_1372:
	ds_read_b128 v[104:107], v220
	ds_read_b128 v[112:115], v247
	ds_read_b128 v[124:127], v220 offset:2048
	ds_read_b128 v[140:143], v247 offset:2048
	ds_read_b128 v[144:147], v221
	ds_read_b128 v[148:151], v248
	ds_read_b128 v[152:155], v221 offset:2048
	ds_read_b128 v[156:159], v248 offset:2048
	s_add_u32 s51, s52, 0xfff80080
	s_addc_u32 s54, s53, -1
	s_cmp_eq_u32 s41, 28
	s_cselect_b32 s57, s17, s54
	s_cselect_b32 s56, s27, s51
	s_cselect_b32 s55, s25, s39
	s_cselect_b32 s54, s35, s38
	v_lshl_add_u64 v[208:209], s[52:53], 0, v[194:195]
	s_add_i32 m0, s2, 0xc000
	ds_read_b128 v[160:163], v222
	ds_read_b128 v[164:167], v246
	ds_read_b128 v[168:171], v222 offset:2048
	ds_read_b128 v[172:175], v246 offset:2048
	ds_read_b128 v[176:179], v222 offset:4096
	ds_read_b128 v[180:183], v246 offset:4096
	ds_read_b128 v[200:203], v222 offset:6144
	ds_read_b128 v[204:207], v246 offset:6144
	global_load_lds_dwordx4 v[208:209], off
	v_lshl_add_u64 v[208:209], s[52:53], 0, v[192:193]
	s_add_i32 m0, s2, 0xe000
	s_nop 0
	global_load_lds_dwordx4 v[208:209], off
	s_waitcnt vmcnt(8)
	s_waitcnt lgkmcnt(0)
	s_barrier
	s_setprio 1
	s_waitcnt lgkmcnt(0)
	v_mfma_f32_16x16x32_bf16 v[136:139], v[160:163], v[104:107], v[136:139]
	v_mfma_f32_16x16x32_bf16 v[132:135], v[160:163], v[124:127], v[132:135]
	v_mfma_f32_16x16x32_bf16 v[116:119], v[168:171], v[104:107], v[116:119]
	v_mfma_f32_16x16x32_bf16 v[108:111], v[168:171], v[124:127], v[108:111]
	v_mfma_f32_16x16x32_bf16 v[92:95], v[176:179], v[104:107], v[92:95]
	v_mfma_f32_16x16x32_bf16 v[88:91], v[176:179], v[124:127], v[88:91]
	v_mfma_f32_16x16x32_bf16 v[76:79], v[200:203], v[104:107], v[76:79]
	v_mfma_f32_16x16x32_bf16 v[72:75], v[200:203], v[124:127], v[72:75]
	v_mfma_f32_16x16x32_bf16 v[136:139], v[164:167], v[112:115], v[136:139]
	v_mfma_f32_16x16x32_bf16 v[132:135], v[164:167], v[140:143], v[132:135]
	v_mfma_f32_16x16x32_bf16 v[116:119], v[172:175], v[112:115], v[116:119]
	v_mfma_f32_16x16x32_bf16 v[108:111], v[172:175], v[140:143], v[108:111]
	v_mfma_f32_16x16x32_bf16 v[92:95], v[180:183], v[112:115], v[92:95]
	v_mfma_f32_16x16x32_bf16 v[88:91], v[180:183], v[140:143], v[88:91]
	v_mfma_f32_16x16x32_bf16 v[76:79], v[204:207], v[112:115], v[76:79]
	v_mfma_f32_16x16x32_bf16 v[72:75], v[204:207], v[140:143], v[72:75]
	s_setprio 0
	s_setprio 1
	v_mfma_f32_16x16x32_bf16 v[128:131], v[160:163], v[144:147], v[128:131]
	v_mfma_f32_16x16x32_bf16 v[120:123], v[160:163], v[152:155], v[120:123]
	v_mfma_f32_16x16x32_bf16 v[100:103], v[168:171], v[144:147], v[100:103]
	v_mfma_f32_16x16x32_bf16 v[96:99], v[168:171], v[152:155], v[96:99]
	v_mfma_f32_16x16x32_bf16 v[84:87], v[176:179], v[144:147], v[84:87]
	v_mfma_f32_16x16x32_bf16 v[80:83], v[176:179], v[152:155], v[80:83]
	v_mfma_f32_16x16x32_bf16 v[68:71], v[200:203], v[144:147], v[68:71]
	v_mfma_f32_16x16x32_bf16 v[64:67], v[200:203], v[152:155], v[64:67]
	v_mfma_f32_16x16x32_bf16 v[128:131], v[164:167], v[148:151], v[128:131]
	v_mfma_f32_16x16x32_bf16 v[120:123], v[164:167], v[156:159], v[120:123]
	v_mfma_f32_16x16x32_bf16 v[100:103], v[172:175], v[148:151], v[100:103]
	v_mfma_f32_16x16x32_bf16 v[96:99], v[172:175], v[156:159], v[96:99]
	v_mfma_f32_16x16x32_bf16 v[84:87], v[180:183], v[148:151], v[84:87]
	v_mfma_f32_16x16x32_bf16 v[80:83], v[180:183], v[156:159], v[80:83]
	v_mfma_f32_16x16x32_bf16 v[68:71], v[204:207], v[148:151], v[68:71]
	v_mfma_f32_16x16x32_bf16 v[64:67], v[204:207], v[156:159], v[64:67]
	s_setprio 0
	s_barrier
	s_add_i32 s51, s0, s1
	v_lshl_add_u64 v[208:209], s[54:55], 0, v[186:187]
	s_mov_b32 m0, s51
	ds_read_b128 v[160:163], v222 offset:16384
	ds_read_b128 v[164:167], v246 offset:16384
	ds_read_b128 v[168:171], v222 offset:18432
	ds_read_b128 v[172:175], v246 offset:18432
	ds_read_b128 v[176:179], v222 offset:20480
	ds_read_b128 v[180:183], v246 offset:20480
	ds_read_b128 v[200:203], v222 offset:22528
	ds_read_b128 v[204:207], v246 offset:22528
	global_load_lds_dwordx4 v[208:209], off
	s_add_i32 m0, s51, 0x2000
	s_add_u32 s58, s54, 0x80000
	v_lshl_add_u64 v[210:211], s[54:55], 0, v[190:191]
	s_addc_u32 s59, s55, 0
	s_add_i32 s51, s34, s1
	global_load_lds_dwordx4 v[210:211], off
	v_lshl_add_u64 v[212:213], s[58:59], 0, v[186:187]
	s_mov_b32 m0, s51
	v_lshl_add_u64 v[214:215], s[56:57], 0, v[188:189]
	global_load_lds_dwordx4 v[212:213], off
	v_lshl_add_u64 v[212:213], s[58:59], 0, v[190:191]
	s_add_i32 m0, s51, 0x2000
	s_nop 0
	global_load_lds_dwordx4 v[212:213], off
	v_lshl_add_u64 v[212:213], s[56:57], 0, v[184:185]
	s_mov_b32 m0, s2
	s_nop 0
	global_load_lds_dwordx4 v[212:213], off
	s_mov_b32 m0, s4
	s_nop 0
	global_load_lds_dwordx4 v[214:215], off
	s_waitcnt vmcnt(8)
	s_waitcnt lgkmcnt(0)
	s_barrier
; #define PG8_STAGE(bufoff, gbase, voff) do { _Pragma("unroll") for (int _i = 0; _i < 2; ++_i) \
;         __builtin_amdgcn_global_load_lds((const unsigned*)((const char*)(gbase) + (voff)[_i]), (LAS unsigned*)(lds + (bufoff) + ldsw + _i * 8192), 16, 0, 0); } while (0)
; #define PG8_LDA(dst, b, h) do { _Pragma("unroll") for (int m = 0; m < 4; ++m) _Pragma("unroll") for (int k = 0; k < 2; ++k) dst[m][k] = *(const LAS bf16x8*)(lds + PG8_SA(b, h) + aoff + m * 2048 + k * 1024); } while (0)
; #define PG8_LDB(dst, b, h) do { _Pragma("unroll") for (int n = 0; n < 2; ++n) _Pragma("unroll") for (int k = 0; k < 2; ++k) dst[n][k] = *(const LAS bf16x8*)(lds + PG8_SB(b, h) + boff + n * 2048 + k * 1024); } while (0)
; #define PG8_MMA(ai, bj, At, Bt) do { __builtin_amdgcn_s_setprio(1); _Pragma("unroll") for (int m = 0; m < 4; ++m) _Pragma("unroll") for (int n = 0; n < 2; ++n) _Pragma("unroll") for (int k = 0; k < 2; ++k) \
;         acc[ai][bj][m][n] = __builtin_amdgcn_mfma_f32_16x16x32_bf16(Bt[n][k], At[m][k], acc[ai][bj][m][n], 0, 0, 0); __builtin_amdgcn_s_setprio(0); } while (0)
; #define PG8_WAIT_V(n) asm volatile("s_waitcnt vmcnt(" #n ")" ::: "memory")
; #define PG8_WAIT_L(n) asm volatile("s_waitcnt lgkmcnt(" #n ")" ::: "memory")
; #define PG8_BAR __builtin_amdgcn_s_barrier()
; #define PG8_SCHED __builtin_amdgcn_sched_barrier(0)
; template <class Epi, class Sched>
; __device__ __forceinline__ void gemm_phase(LAS unsigned char* lds, const int K, const int lda, const int ldb, const Sched& S, const Epi& E) {
;     ...
;             PG8_WAIT_V(8); PG8_WAIT_L(0); PG8_BAR; PG8_MMA(1, 0, At, B0); PG8_MMA(1, 1, At, B1); PG8_BAR; PG8_SCHED;
;             PG8_LDB(B0, 1, 0); PG8_LDB(B1, 1, 1); PG8_SCHED; PG8_LDA(At, 1, 0); PG8_STAGE(PG8_SA(0, 1), a2 + hA, voffA);
;             PG8_WAIT_V(8); PG8_WAIT_L(0); PG8_BAR; PG8_MMA(0, 0, At, B0); PG8_MMA(0, 1, At, B1); PG8_BAR; PG8_SCHED;
;             PG8_LDA(At, 1, 1); PG8_STAGE(PG8_SB(1, 0), b3, voffB); PG8_STAGE(PG8_SB(1, 1), b3 + hB, voffB); PG8_STAGE(PG8_SA(1, 0), a3, voffA);
;             PG8_WAIT_V(8); PG8_WAIT_L(0); PG8_BAR; PG8_MMA(1, 0, At, B0); PG8_MMA(1, 1, At, B1); PG8_BAR; PG8_SCHED;
	s_setprio 1
	s_waitcnt lgkmcnt(0)
	v_mfma_f32_16x16x32_bf16 v[60:63], v[160:163], v[104:107], v[60:63]
	v_mfma_f32_16x16x32_bf16 v[56:59], v[160:163], v[124:127], v[56:59]
	v_mfma_f32_16x16x32_bf16 v[44:47], v[168:171], v[104:107], v[44:47]
	v_mfma_f32_16x16x32_bf16 v[40:43], v[168:171], v[124:127], v[40:43]
	v_mfma_f32_16x16x32_bf16 v[28:31], v[176:179], v[104:107], v[28:31]
	v_mfma_f32_16x16x32_bf16 v[24:27], v[176:179], v[124:127], v[24:27]
	v_mfma_f32_16x16x32_bf16 v[12:15], v[200:203], v[104:107], v[12:15]
	v_mfma_f32_16x16x32_bf16 v[8:11], v[200:203], v[124:127], v[8:11]
	v_mfma_f32_16x16x32_bf16 v[60:63], v[164:167], v[112:115], v[60:63]
	v_mfma_f32_16x16x32_bf16 v[56:59], v[164:167], v[140:143], v[56:59]
	v_mfma_f32_16x16x32_bf16 v[44:47], v[172:175], v[112:115], v[44:47]
	v_mfma_f32_16x16x32_bf16 v[40:43], v[172:175], v[140:143], v[40:43]
	v_mfma_f32_16x16x32_bf16 v[28:31], v[180:183], v[112:115], v[28:31]
	v_mfma_f32_16x16x32_bf16 v[24:27], v[180:183], v[140:143], v[24:27]
	v_mfma_f32_16x16x32_bf16 v[12:15], v[204:207], v[112:115], v[12:15]
	v_mfma_f32_16x16x32_bf16 v[8:11], v[204:207], v[140:143], v[8:11]
	s_setprio 0
	s_setprio 1
	v_mfma_f32_16x16x32_bf16 v[52:55], v[160:163], v[144:147], v[52:55]
	v_mfma_f32_16x16x32_bf16 v[48:51], v[160:163], v[152:155], v[48:51]
	v_mfma_f32_16x16x32_bf16 v[36:39], v[168:171], v[144:147], v[36:39]
	v_mfma_f32_16x16x32_bf16 v[32:35], v[168:171], v[152:155], v[32:35]
	v_mfma_f32_16x16x32_bf16 v[20:23], v[176:179], v[144:147], v[20:23]
	v_mfma_f32_16x16x32_bf16 v[16:19], v[176:179], v[152:155], v[16:19]
	v_mfma_f32_16x16x32_bf16 v[4:7], v[200:203], v[144:147], v[4:7]
	v_mfma_f32_16x16x32_bf16 v[0:3], v[200:203], v[152:155], v[0:3]
	v_mfma_f32_16x16x32_bf16 v[52:55], v[164:167], v[148:151], v[52:55]
	v_mfma_f32_16x16x32_bf16 v[48:51], v[164:167], v[156:159], v[48:51]
	v_mfma_f32_16x16x32_bf16 v[36:39], v[172:175], v[148:151], v[36:39]
	v_mfma_f32_16x16x32_bf16 v[32:35], v[172:175], v[156:159], v[32:35]
	v_mfma_f32_16x16x32_bf16 v[20:23], v[180:183], v[148:151], v[20:23]
	v_mfma_f32_16x16x32_bf16 v[16:19], v[180:183], v[156:159], v[16:19]
	v_mfma_f32_16x16x32_bf16 v[4:7], v[204:207], v[148:151], v[4:7]
	v_mfma_f32_16x16x32_bf16 v[0:3], v[204:207], v[156:159], v[0:3]
	s_setprio 0
	s_barrier
	s_add_i32 s51, 0, 0x18000
	s_add_i32 s58, 0, 0x1c000
	v_add_u32_e32 v140, s51, v217
	v_add_u32_e32 v250, s51, v249
	v_add_u32_e32 v156, 0x19000, v217
	v_add_u32_e32 v251, 0x19000, v249
	ds_read_b128 v[104:107], v140
	ds_read_b128 v[112:115], v250
	ds_read_b128 v[124:127], v140 offset:2048
	ds_read_b128 v[140:143], v250 offset:2048
	ds_read_b128 v[144:147], v156
	ds_read_b128 v[148:151], v251
	ds_read_b128 v[152:155], v156 offset:2048
	ds_read_b128 v[156:159], v251 offset:2048
	s_add_u32 s56, s56, 0x80000
	s_addc_u32 s57, s57, 0
	s_mov_b32 m0, s5
	v_lshl_add_u64 v[226:227], s[56:57], 0, v[184:185]
	ds_read_b128 v[160:163], v222 offset:32768
	ds_read_b128 v[164:167], v246 offset:32768
	ds_read_b128 v[168:171], v222 offset:34816
	ds_read_b128 v[172:175], v246 offset:34816
	ds_read_b128 v[176:179], v222 offset:36864
	ds_read_b128 v[180:183], v246 offset:36864
	ds_read_b128 v[200:203], v222 offset:38912
	ds_read_b128 v[204:207], v246 offset:38912
	global_load_lds_dwordx4 v[226:227], off
	v_lshl_add_u64 v[226:227], s[56:57], 0, v[188:189]
	s_mov_b32 m0, s6
	s_nop 0
	global_load_lds_dwordx4 v[226:227], off
	s_waitcnt vmcnt(8)
	s_waitcnt lgkmcnt(0)
	s_barrier
	s_setprio 1
	s_waitcnt lgkmcnt(0)
	v_mfma_f32_16x16x32_bf16 v[136:139], v[160:163], v[104:107], v[136:139]
	v_mfma_f32_16x16x32_bf16 v[132:135], v[160:163], v[124:127], v[132:135]
	v_mfma_f32_16x16x32_bf16 v[116:119], v[168:171], v[104:107], v[116:119]
	v_mfma_f32_16x16x32_bf16 v[108:111], v[168:171], v[124:127], v[108:111]
	v_mfma_f32_16x16x32_bf16 v[92:95], v[176:179], v[104:107], v[92:95]
	v_mfma_f32_16x16x32_bf16 v[88:91], v[176:179], v[124:127], v[88:91]
	v_mfma_f32_16x16x32_bf16 v[76:79], v[200:203], v[104:107], v[76:79]
	v_mfma_f32_16x16x32_bf16 v[72:75], v[200:203], v[124:127], v[72:75]
	v_mfma_f32_16x16x32_bf16 v[136:139], v[164:167], v[112:115], v[136:139]
	v_mfma_f32_16x16x32_bf16 v[132:135], v[164:167], v[140:143], v[132:135]
	v_mfma_f32_16x16x32_bf16 v[116:119], v[172:175], v[112:115], v[116:119]
	v_mfma_f32_16x16x32_bf16 v[108:111], v[172:175], v[140:143], v[108:111]
	v_mfma_f32_16x16x32_bf16 v[92:95], v[180:183], v[112:115], v[92:95]
	v_mfma_f32_16x16x32_bf16 v[88:91], v[180:183], v[140:143], v[88:91]
	v_mfma_f32_16x16x32_bf16 v[76:79], v[204:207], v[112:115], v[76:79]
	v_mfma_f32_16x16x32_bf16 v[72:75], v[204:207], v[140:143], v[72:75]
	s_setprio 0
	s_setprio 1
	v_mfma_f32_16x16x32_bf16 v[128:131], v[160:163], v[144:147], v[128:131]
	v_mfma_f32_16x16x32_bf16 v[120:123], v[160:163], v[152:155], v[120:123]
	v_mfma_f32_16x16x32_bf16 v[100:103], v[168:171], v[144:147], v[100:103]
	v_mfma_f32_16x16x32_bf16 v[96:99], v[168:171], v[152:155], v[96:99]
	v_mfma_f32_16x16x32_bf16 v[84:87], v[176:179], v[144:147], v[84:87]
	v_mfma_f32_16x16x32_bf16 v[80:83], v[176:179], v[152:155], v[80:83]
	v_mfma_f32_16x16x32_bf16 v[68:71], v[200:203], v[144:147], v[68:71]
	v_mfma_f32_16x16x32_bf16 v[64:67], v[200:203], v[152:155], v[64:67]
	v_mfma_f32_16x16x32_bf16 v[128:131], v[164:167], v[148:151], v[128:131]
	v_mfma_f32_16x16x32_bf16 v[120:123], v[164:167], v[156:159], v[120:123]
	v_mfma_f32_16x16x32_bf16 v[100:103], v[172:175], v[148:151], v[100:103]
	v_mfma_f32_16x16x32_bf16 v[96:99], v[172:175], v[156:159], v[96:99]
	v_mfma_f32_16x16x32_bf16 v[84:87], v[180:183], v[148:151], v[84:87]
	v_mfma_f32_16x16x32_bf16 v[80:83], v[180:183], v[156:159], v[80:83]
	v_mfma_f32_16x16x32_bf16 v[68:71], v[204:207], v[148:151], v[68:71]
	v_mfma_f32_16x16x32_bf16 v[64:67], v[204:207], v[156:159], v[64:67]
	s_setprio 0
	s_barrier
; #define LAS __attribute__((address_space(3)))
; #define PG8_STAGE(bufoff, gbase, voff) do { _Pragma("unroll") for (int _i = 0; _i < 2; ++_i) \
;         __builtin_amdgcn_global_load_lds((const unsigned*)((const char*)(gbase) + (voff)[_i]), (LAS unsigned*)(lds + (bufoff) + ldsw + _i * 8192), 16, 0, 0); } while (0)
; #define PG8_LDA(dst, b, h) do { _Pragma("unroll") for (int m = 0; m < 4; ++m) _Pragma("unroll") for (int k = 0; k < 2; ++k) dst[m][k] = *(const LAS bf16x8*)(lds + PG8_SA(b, h) + aoff + m * 2048 + k * 1024); } while (0)
; #define PG8_MMA(ai, bj, At, Bt) do { __builtin_amdgcn_s_setprio(1); _Pragma("unroll") for (int m = 0; m < 4; ++m) _Pragma("unroll") for (int n = 0; n < 2; ++n) _Pragma("unroll") for (int k = 0; k < 2; ++k) \
;         acc[ai][bj][m][n] = __builtin_amdgcn_mfma_f32_16x16x32_bf16(Bt[n][k], At[m][k], acc[ai][bj][m][n], 0, 0, 0); __builtin_amdgcn_s_setprio(0); } while (0)
; #define PG8_WAIT_V(n) asm volatile("s_waitcnt vmcnt(" #n ")" ::: "memory")
; #define PG8_WAIT_L(n) asm volatile("s_waitcnt lgkmcnt(" #n ")" ::: "memory")
; #define PG8_BAR __builtin_amdgcn_s_barrier()
; #define PG8_SCHED __builtin_amdgcn_sched_barrier(0)
; template <class Epi, class Sched>
; __device__ __forceinline__ void gemm_phase(LAS unsigned char* lds, const int K, const int lda, const int ldb, const Sched& S, const Epi& E) {
;     ...
;             PG8_LDA(At, 1, 1); PG8_STAGE(PG8_SB(1, 0), b3, voffB); PG8_STAGE(PG8_SB(1, 1), b3 + hB, voffB); PG8_STAGE(PG8_SA(1, 0), a3, voffA);
;             PG8_WAIT_V(8); PG8_WAIT_L(0); PG8_BAR; PG8_MMA(1, 0, At, B0); PG8_MMA(1, 1, At, B1); PG8_BAR; PG8_SCHED;
;         }
;         if (wr == 0) PG8_BAR;
;     __device__ __forceinline__ void operator()(const f32x4 (&acc)[2][2][4][2], const Unit& u, int wr, int wc, int fr, int fq, LAS unsigned char* xs, int wid, int lane) const {
;         const int row0 = u.pm * 256 + wr * 64, col0 = u.pn * 256 + wc * 32 + 8 * fq;
;         const float* xo = (row0 < TP) ? xo_p : xo_s - (size_t)TP * D;
;         LAS float* P = (LAS float*)xs;
;         u32x4 raw[2][4][2];
;         if (!SRCF32) {
; #pragma unroll
;             for (int ai = 0; ai < 2; ++ai)
; #pragma unroll
;                 for (int m = 0; m < 4; ++m)
; #pragma unroll
;                     for (int bj = 0; bj < 2; ++bj) raw[ai][m][bj] = *(const u32x4*)(xb + (size_t)(row0 + ai * 128 + m * 16 + fr) * D + col0 + bj * 128);
	s_add_i32 s51, s51, s1
	v_lshl_add_u64 v[208:209], v[208:209], 0, s[20:21]
	s_mov_b32 m0, s51
	ds_read_b128 v[160:163], v222 offset:49152
	ds_read_b128 v[164:167], v246 offset:49152
	ds_read_b128 v[168:171], v222 offset:51200
	ds_read_b128 v[172:175], v246 offset:51200
	ds_read_b128 v[176:179], v222 offset:53248
	ds_read_b128 v[180:183], v246 offset:53248
	ds_read_b128 v[200:203], v222 offset:55296
	ds_read_b128 v[204:207], v246 offset:55296
	global_load_lds_dwordx4 v[208:209], off
	s_add_i32 m0, s51, 0x2000
	s_add_u32 s54, s54, 0x80080
	v_lshl_add_u64 v[208:209], v[210:211], 0, s[20:21]
	s_addc_u32 s55, s55, 0
	s_add_i32 s51, s58, s1
	global_load_lds_dwordx4 v[208:209], off
	v_lshl_add_u64 v[208:209], s[54:55], 0, v[186:187]
	s_mov_b32 m0, s51
	s_nop 0
	global_load_lds_dwordx4 v[208:209], off
	v_lshl_add_u64 v[208:209], s[54:55], 0, v[190:191]
	s_add_i32 m0, s51, 0x2000
	s_nop 0
	global_load_lds_dwordx4 v[208:209], off
	v_lshl_add_u64 v[208:209], v[212:213], 0, s[20:21]
	s_mov_b32 m0, s14
	s_nop 0
	global_load_lds_dwordx4 v[208:209], off
	v_lshl_add_u64 v[208:209], v[214:215], 0, s[20:21]
	s_mov_b32 m0, s15
	s_nop 0
	global_load_lds_dwordx4 v[208:209], off
	s_waitcnt vmcnt(8)
	s_waitcnt lgkmcnt(0)
	s_barrier
	s_setprio 1
	s_waitcnt lgkmcnt(0)
	v_mfma_f32_16x16x32_bf16 v[60:63], v[160:163], v[104:107], v[60:63]
	v_mfma_f32_16x16x32_bf16 v[56:59], v[160:163], v[124:127], v[56:59]
	v_mfma_f32_16x16x32_bf16 v[44:47], v[168:171], v[104:107], v[44:47]
	v_mfma_f32_16x16x32_bf16 v[40:43], v[168:171], v[124:127], v[40:43]
	v_mfma_f32_16x16x32_bf16 v[28:31], v[176:179], v[104:107], v[28:31]
	v_mfma_f32_16x16x32_bf16 v[24:27], v[176:179], v[124:127], v[24:27]
	v_mfma_f32_16x16x32_bf16 v[12:15], v[200:203], v[104:107], v[12:15]
	v_mfma_f32_16x16x32_bf16 v[8:11], v[200:203], v[124:127], v[8:11]
	v_mfma_f32_16x16x32_bf16 v[60:63], v[164:167], v[112:115], v[60:63]
	v_mfma_f32_16x16x32_bf16 v[56:59], v[164:167], v[140:143], v[56:59]
	v_mfma_f32_16x16x32_bf16 v[44:47], v[172:175], v[112:115], v[44:47]
	v_mfma_f32_16x16x32_bf16 v[40:43], v[172:175], v[140:143], v[40:43]
	v_mfma_f32_16x16x32_bf16 v[28:31], v[180:183], v[112:115], v[28:31]
	v_mfma_f32_16x16x32_bf16 v[24:27], v[180:183], v[140:143], v[24:27]
	v_mfma_f32_16x16x32_bf16 v[12:15], v[204:207], v[112:115], v[12:15]
	v_mfma_f32_16x16x32_bf16 v[8:11], v[204:207], v[140:143], v[8:11]
	s_setprio 0
	s_setprio 1
	v_mfma_f32_16x16x32_bf16 v[52:55], v[160:163], v[144:147], v[52:55]
	v_mfma_f32_16x16x32_bf16 v[48:51], v[160:163], v[152:155], v[48:51]
	v_mfma_f32_16x16x32_bf16 v[36:39], v[168:171], v[144:147], v[36:39]
	v_mfma_f32_16x16x32_bf16 v[32:35], v[168:171], v[152:155], v[32:35]
	v_mfma_f32_16x16x32_bf16 v[20:23], v[176:179], v[144:147], v[20:23]
	v_mfma_f32_16x16x32_bf16 v[16:19], v[176:179], v[152:155], v[16:19]
	v_mfma_f32_16x16x32_bf16 v[4:7], v[200:203], v[144:147], v[4:7]
	v_mfma_f32_16x16x32_bf16 v[0:3], v[200:203], v[152:155], v[0:3]
	v_mfma_f32_16x16x32_bf16 v[52:55], v[164:167], v[148:151], v[52:55]
	v_mfma_f32_16x16x32_bf16 v[48:51], v[164:167], v[156:159], v[48:51]
	v_mfma_f32_16x16x32_bf16 v[36:39], v[172:175], v[148:151], v[36:39]
	v_mfma_f32_16x16x32_bf16 v[32:35], v[172:175], v[156:159], v[32:35]
	v_mfma_f32_16x16x32_bf16 v[20:23], v[180:183], v[148:151], v[20:23]
	v_mfma_f32_16x16x32_bf16 v[16:19], v[180:183], v[156:159], v[16:19]
	v_mfma_f32_16x16x32_bf16 v[4:7], v[204:207], v[148:151], v[4:7]
	v_mfma_f32_16x16x32_bf16 v[0:3], v[204:207], v[156:159], v[0:3]
	s_setprio 0
	s_barrier
	s_add_i32 s41, s41, 2
	s_add_u32 s38, s38, 0x100
	s_addc_u32 s39, s39, 0
	s_add_u32 s52, s52, 0x100
	s_addc_u32 s53, s53, 0
	s_cmp_gt_u32 s41, 29
	s_cbranch_scc0 .LBB0_1372
	s_and_b64 vcc, exec, s[22:23]
	s_cbranch_vccz .LBB0_1375
	s_barrier
.LBB0_1375:
	v_readfirstlane_b32 s25, v254
	s_nop 1
	s_lshr_b32 s25, s25, 6
	s_lshr_b32 s27, s25, 2
	s_and_b32 s51, s25, 3
	s_lshl_b32 s41, s50, 8
	s_lshl_b32 s27, s27, 6
	s_add_i32 s32, s41, s27
	s_lshl_b32 s35, s16, 8
	s_lshl_b32 s25, s51, 6
	s_add_i32 s35, s35, s25
	s_lshl_b32 s32, s32, 11
	s_add_i32 s32, s32, s35
	s_lshl_b32 s35, s32, 1
	s_add_u32 s38, s42, s35
	s_addc_u32 s39, s43, 0
	v_and_b32_e32 v209, 15, v254
	v_bfe_u32 v210, v254, 4, 2
	v_lshlrev_b32_e32 v208, 13, v210
	v_lshl_add_u32 v208, v209, 2, v208
	v_lshlrev_b32_e32 v208, 1, v208
	v_lshlrev_b32_e32 v213, 6, v210
	v_add_u32_e32 v213, 0x20000, v213
	s_lshl_b32 s27, s27, 4
	s_lshl_b32 s25, s51, 2
	s_add_i32 s27, s27, s25
	v_add_u32_e32 v213, s27, v213
	s_add_u32 s52, s38, 0x0
	s_addc_u32 s53, s39, 0
	global_load_dwordx2 v[104:105], v208, s[52:53]
	s_add_u32 s54, s38, 0x1000
	s_addc_u32 s55, s39, 0
	global_load_dwordx2 v[106:107], v208, s[54:55]
	s_add_u32 s52, s38, 0x2000
	s_addc_u32 s53, s39, 0
	global_load_dwordx2 v[112:113], v208, s[52:53]
	s_add_u32 s54, s38, 0x3000
	s_addc_u32 s55, s39, 0
	global_load_dwordx2 v[114:115], v208, s[54:55]
	s_add_u32 s52, s38, 0x10000
	s_addc_u32 s53, s39, 0
	global_load_dwordx2 v[124:125], v208, s[52:53]
	s_add_u32 s54, s38, 0x11000
	s_addc_u32 s55, s39, 0
	global_load_dwordx2 v[126:127], v208, s[54:55]
	s_add_u32 s52, s38, 0x12000
	s_addc_u32 s53, s39, 0
	global_load_dwordx2 v[140:141], v208, s[52:53]
	s_add_u32 s54, s38, 0x13000
	s_addc_u32 s55, s39, 0
	global_load_dwordx2 v[142:143], v208, s[54:55]
	s_add_u32 s52, s38, 0x20000
	s_addc_u32 s53, s39, 0
	global_load_dwordx2 v[144:145], v208, s[52:53]
	s_add_u32 s54, s38, 0x21000
	s_addc_u32 s55, s39, 0
	global_load_dwordx2 v[146:147], v208, s[54:55]
	s_add_u32 s52, s38, 0x22000
	s_addc_u32 s53, s39, 0
	global_load_dwordx2 v[148:149], v208, s[52:53]
	s_add_u32 s54, s38, 0x23000
	s_addc_u32 s55, s39, 0
; __device__ __forceinline__ unsigned cvt_pk_bf16(float lo, float hi) { unsigned r; asm("v_cvt_pk_bf16_f32 %0, %1, %2" : "=v"(r) : "v"(lo), "v"(hi)); return r; }
;     __device__ __forceinline__ void operator()(const f32x4 (&acc)[2][2][4][2], const Unit& u, int wr, int wc, int fr, int fq, LAS unsigned char* xs, int wid, int lane) const {
;     ...
; #pragma unroll
;             for (int m = 0; m < 4; ++m) {
;                 const size_t row = (size_t)(row0 + ai * 128 + m * 16 + fr);
;                 float ss = 0.f;
; #pragma unroll
;                 for (int bj = 0; bj < 2; ++bj) {
;                     const size_t o = row * D + col0 + bj * 128;
;                     f32x4 x0, x1;
;                     if (SRCF32) { x0 = xf[m][bj][0]; x1 = xf[m][bj][1]; }
;                     else { const u32x4 r = raw[ai][m][bj]; x0 = (f32x4){bf_lo(r.x), bf_hi(r.x), bf_lo(r.y), bf_hi(r.y)}; x1 = (f32x4){bf_lo(r.z), bf_hi(r.z), bf_lo(r.w), bf_hi(r.w)}; }
;                     const f32x4 v0 = x0 + acc[ai][bj][m][0], v1 = x1 + acc[ai][bj][m][1];
;                     if (LAST) { *(f32x4*)(out + o) = v0; *(f32x4*)(out + o + 4) = v1; }
;                     else {
;                         ss += (v0[0] * v0[0] + v0[1] * v0[1]) + (v0[2] * v0[2] + v0[3] * v0[3]) + (v1[0] * v1[0] + v1[1] * v1[1]) + (v1[2] * v1[2] + v1[3] * v1[3]);
;                         u32x4 w; w.x = cvt_pk_bf16(v0[0], v0[1]); w.y = cvt_pk_bf16(v0[2], v0[3]); w.z = cvt_pk_bf16(v1[0], v1[1]); w.w = cvt_pk_bf16(v1[2], v1[3]); *(u32x4*)(xb + o) = w;
	global_load_dwordx2 v[150:151], v208, s[54:55]
	s_add_u32 s52, s38, 0x30000
	s_addc_u32 s53, s39, 0
	global_load_dwordx2 v[152:153], v208, s[52:53]
	s_add_u32 s54, s38, 0x31000
	s_addc_u32 s55, s39, 0
	global_load_dwordx2 v[154:155], v208, s[54:55]
	s_add_u32 s52, s38, 0x32000
	s_addc_u32 s53, s39, 0
	global_load_dwordx2 v[156:157], v208, s[52:53]
	s_add_u32 s54, s38, 0x33000
	s_addc_u32 s55, s39, 0
	global_load_dwordx2 v[158:159], v208, s[54:55]
	s_add_u32 s52, s38, 0x80000
	s_addc_u32 s53, s39, 0
	global_load_dwordx2 v[160:161], v208, s[52:53]
	s_add_u32 s54, s38, 0x81000
	s_addc_u32 s55, s39, 0
	global_load_dwordx2 v[162:163], v208, s[54:55]
	s_add_u32 s52, s38, 0x82000
	s_addc_u32 s53, s39, 0
	global_load_dwordx2 v[164:165], v208, s[52:53]
	s_add_u32 s54, s38, 0x83000
	s_addc_u32 s55, s39, 0
	global_load_dwordx2 v[166:167], v208, s[54:55]
	s_add_u32 s52, s38, 0x90000
	s_addc_u32 s53, s39, 0
	global_load_dwordx2 v[168:169], v208, s[52:53]
	s_add_u32 s54, s38, 0x91000
	s_addc_u32 s55, s39, 0
	global_load_dwordx2 v[170:171], v208, s[54:55]
	s_add_u32 s52, s38, 0x92000
	s_addc_u32 s53, s39, 0
	global_load_dwordx2 v[172:173], v208, s[52:53]
	s_add_u32 s54, s38, 0x93000
	s_addc_u32 s55, s39, 0
	global_load_dwordx2 v[174:175], v208, s[54:55]
	s_add_u32 s52, s38, 0xa0000
	s_addc_u32 s53, s39, 0
	global_load_dwordx2 v[176:177], v208, s[52:53]
	s_add_u32 s54, s38, 0xa1000
	s_addc_u32 s55, s39, 0
	global_load_dwordx2 v[178:179], v208, s[54:55]
	s_add_u32 s52, s38, 0xa2000
	s_addc_u32 s53, s39, 0
	global_load_dwordx2 v[180:181], v208, s[52:53]
	s_add_u32 s54, s38, 0xa3000
	s_addc_u32 s55, s39, 0
	global_load_dwordx2 v[182:183], v208, s[54:55]
	s_add_u32 s52, s38, 0xb0000
	s_addc_u32 s53, s39, 0
	global_load_dwordx2 v[200:201], v208, s[52:53]
	s_add_u32 s54, s38, 0xb1000
	s_addc_u32 s55, s39, 0
	global_load_dwordx2 v[202:203], v208, s[54:55]
	s_add_u32 s52, s38, 0xb2000
	s_addc_u32 s53, s39, 0
	global_load_dwordx2 v[204:205], v208, s[52:53]
	s_add_u32 s54, s38, 0xb3000
	s_addc_u32 s55, s39, 0
	global_load_dwordx2 v[206:207], v208, s[54:55]
	s_waitcnt vmcnt(31)
	v_lshlrev_b32_e32 v211, 16, v104
	v_and_b32_e32 v212, 0xffff0000, v104
	v_add_f32_e32 v136, v136, v211
	v_add_f32_e32 v132, v132, v212
	v_lshlrev_b32_e32 v211, 16, v105
	v_and_b32_e32 v212, 0xffff0000, v105
	v_add_f32_e32 v128, v128, v211
	v_add_f32_e32 v120, v120, v212
	v_cvt_pk_bf16_f32 v236, v136, v132
	v_cvt_pk_bf16_f32 v237, v128, v120
	v_mul_f32_e32 v136, v136, v136
	v_fmac_f32_e32 v136, v132, v132
	v_fmac_f32_e32 v136, v128, v128
	v_fmac_f32_e32 v136, v120, v120
	s_add_u32 s52, s38, 0x0
	s_addc_u32 s53, s39, 0
	global_store_dwordx2 v208, v[236:237], s[52:53]
	s_waitcnt vmcnt(31)
	v_lshlrev_b32_e32 v211, 16, v106
	v_and_b32_e32 v212, 0xffff0000, v106
	v_add_f32_e32 v137, v137, v211
	v_add_f32_e32 v133, v133, v212
	v_lshlrev_b32_e32 v211, 16, v107
	v_and_b32_e32 v212, 0xffff0000, v107
	v_add_f32_e32 v129, v129, v211
	v_add_f32_e32 v121, v121, v212
	v_cvt_pk_bf16_f32 v238, v137, v133
	v_cvt_pk_bf16_f32 v239, v129, v121
	v_mul_f32_e32 v137, v137, v137
	v_fmac_f32_e32 v137, v133, v133
	v_fmac_f32_e32 v137, v129, v129
	v_fmac_f32_e32 v137, v121, v121
	s_add_u32 s54, s38, 0x1000
	s_addc_u32 s55, s39, 0
	global_store_dwordx2 v208, v[238:239], s[54:55]
	s_waitcnt vmcnt(31)
	v_lshlrev_b32_e32 v211, 16, v112
	v_and_b32_e32 v212, 0xffff0000, v112
	v_add_f32_e32 v138, v138, v211
	v_add_f32_e32 v134, v134, v212
	v_lshlrev_b32_e32 v211, 16, v113
	v_and_b32_e32 v212, 0xffff0000, v113
	v_add_f32_e32 v130, v130, v211
	v_add_f32_e32 v122, v122, v212
	v_cvt_pk_bf16_f32 v240, v138, v134
	v_cvt_pk_bf16_f32 v241, v130, v122
	v_mul_f32_e32 v138, v138, v138
	v_fmac_f32_e32 v138, v134, v134
	v_fmac_f32_e32 v138, v130, v130
	v_fmac_f32_e32 v138, v122, v122
	s_add_u32 s52, s38, 0x2000
	s_addc_u32 s53, s39, 0
	global_store_dwordx2 v208, v[240:241], s[52:53]
	s_waitcnt vmcnt(31)
	v_lshlrev_b32_e32 v211, 16, v114
	v_and_b32_e32 v212, 0xffff0000, v114
	v_add_f32_e32 v139, v139, v211
	v_add_f32_e32 v135, v135, v212
	v_lshlrev_b32_e32 v211, 16, v115
	v_and_b32_e32 v212, 0xffff0000, v115
	v_add_f32_e32 v131, v131, v211
	v_add_f32_e32 v123, v123, v212
	v_cvt_pk_bf16_f32 v242, v139, v135
	v_cvt_pk_bf16_f32 v243, v131, v123
	v_mul_f32_e32 v139, v139, v139
	v_fmac_f32_e32 v139, v135, v135
	v_fmac_f32_e32 v139, v131, v131
	v_fmac_f32_e32 v139, v123, v123
	s_add_u32 s54, s38, 0x3000
	s_addc_u32 s55, s39, 0
	global_store_dwordx2 v208, v[242:243], s[54:55]
	s_waitcnt vmcnt(31)
	v_lshlrev_b32_e32 v211, 16, v124
	v_and_b32_e32 v212, 0xffff0000, v124
	v_add_f32_e32 v116, v116, v211
	v_add_f32_e32 v108, v108, v212
	v_lshlrev_b32_e32 v211, 16, v125
	v_and_b32_e32 v212, 0xffff0000, v125
	v_add_f32_e32 v100, v100, v211
	v_add_f32_e32 v96, v96, v212
	v_cvt_pk_bf16_f32 v236, v116, v108
	v_cvt_pk_bf16_f32 v237, v100, v96
	v_mul_f32_e32 v116, v116, v116
	v_fmac_f32_e32 v116, v108, v108
	v_fmac_f32_e32 v116, v100, v100
	v_fmac_f32_e32 v116, v96, v96
	s_add_u32 s52, s38, 0x10000
	s_addc_u32 s53, s39, 0
	global_store_dwordx2 v208, v[236:237], s[52:53]
	s_waitcnt vmcnt(31)
	v_lshlrev_b32_e32 v211, 16, v126
	v_and_b32_e32 v212, 0xffff0000, v126
	v_add_f32_e32 v117, v117, v211
	v_add_f32_e32 v109, v109, v212
	v_lshlrev_b32_e32 v211, 16, v127
	v_and_b32_e32 v212, 0xffff0000, v127
	v_add_f32_e32 v101, v101, v211
	v_add_f32_e32 v97, v97, v212
	v_cvt_pk_bf16_f32 v238, v117, v109
	v_cvt_pk_bf16_f32 v239, v101, v97
	v_mul_f32_e32 v117, v117, v117
	v_fmac_f32_e32 v117, v109, v109
	v_fmac_f32_e32 v117, v101, v101
	v_fmac_f32_e32 v117, v97, v97
	s_add_u32 s54, s38, 0x11000
	s_addc_u32 s55, s39, 0
	global_store_dwordx2 v208, v[238:239], s[54:55]
	s_waitcnt vmcnt(31)
; __device__ __forceinline__ unsigned cvt_pk_bf16(float lo, float hi) { unsigned r; asm("v_cvt_pk_bf16_f32 %0, %1, %2" : "=v"(r) : "v"(lo), "v"(hi)); return r; }
;     __device__ __forceinline__ void operator()(const f32x4 (&acc)[2][2][4][2], const Unit& u, int wr, int wc, int fr, int fq, LAS unsigned char* xs, int wid, int lane) const {
;     ...
; #pragma unroll
;             for (int m = 0; m < 4; ++m) {
;                 const size_t row = (size_t)(row0 + ai * 128 + m * 16 + fr);
;                 float ss = 0.f;
; #pragma unroll
;                 for (int bj = 0; bj < 2; ++bj) {
;                     const size_t o = row * D + col0 + bj * 128;
;                     f32x4 x0, x1;
;                     if (SRCF32) { x0 = xf[m][bj][0]; x1 = xf[m][bj][1]; }
;                     else { const u32x4 r = raw[ai][m][bj]; x0 = (f32x4){bf_lo(r.x), bf_hi(r.x), bf_lo(r.y), bf_hi(r.y)}; x1 = (f32x4){bf_lo(r.z), bf_hi(r.z), bf_lo(r.w), bf_hi(r.w)}; }
;                     const f32x4 v0 = x0 + acc[ai][bj][m][0], v1 = x1 + acc[ai][bj][m][1];
;                     if (LAST) { *(f32x4*)(out + o) = v0; *(f32x4*)(out + o + 4) = v1; }
;                     else {
;                         ss += (v0[0] * v0[0] + v0[1] * v0[1]) + (v0[2] * v0[2] + v0[3] * v0[3]) + (v1[0] * v1[0] + v1[1] * v1[1]) + (v1[2] * v1[2] + v1[3] * v1[3]);
;                         u32x4 w; w.x = cvt_pk_bf16(v0[0], v0[1]); w.y = cvt_pk_bf16(v0[2], v0[3]); w.z = cvt_pk_bf16(v1[0], v1[1]); w.w = cvt_pk_bf16(v1[2], v1[3]); *(u32x4*)(xb + o) = w;
	v_lshlrev_b32_e32 v211, 16, v140
	v_and_b32_e32 v212, 0xffff0000, v140
	v_add_f32_e32 v118, v118, v211
	v_add_f32_e32 v110, v110, v212
	v_lshlrev_b32_e32 v211, 16, v141
	v_and_b32_e32 v212, 0xffff0000, v141
	v_add_f32_e32 v102, v102, v211
	v_add_f32_e32 v98, v98, v212
	v_cvt_pk_bf16_f32 v240, v118, v110
	v_cvt_pk_bf16_f32 v241, v102, v98
	v_mul_f32_e32 v118, v118, v118
	v_fmac_f32_e32 v118, v110, v110
	v_fmac_f32_e32 v118, v102, v102
	v_fmac_f32_e32 v118, v98, v98
	s_add_u32 s52, s38, 0x12000
	s_addc_u32 s53, s39, 0
	global_store_dwordx2 v208, v[240:241], s[52:53]
	s_waitcnt vmcnt(31)
	v_lshlrev_b32_e32 v211, 16, v142
	v_and_b32_e32 v212, 0xffff0000, v142
	v_add_f32_e32 v119, v119, v211
	v_add_f32_e32 v111, v111, v212
	v_lshlrev_b32_e32 v211, 16, v143
	v_and_b32_e32 v212, 0xffff0000, v143
	v_add_f32_e32 v103, v103, v211
	v_add_f32_e32 v99, v99, v212
	v_cvt_pk_bf16_f32 v242, v119, v111
	v_cvt_pk_bf16_f32 v243, v103, v99
	v_mul_f32_e32 v119, v119, v119
	v_fmac_f32_e32 v119, v111, v111
	v_fmac_f32_e32 v119, v103, v103
	v_fmac_f32_e32 v119, v99, v99
	s_add_u32 s54, s38, 0x13000
	s_addc_u32 s55, s39, 0
	global_store_dwordx2 v208, v[242:243], s[54:55]
	s_waitcnt vmcnt(31)
	v_lshlrev_b32_e32 v211, 16, v144
	v_and_b32_e32 v212, 0xffff0000, v144
	v_add_f32_e32 v92, v92, v211
	v_add_f32_e32 v88, v88, v212
	v_lshlrev_b32_e32 v211, 16, v145
	v_and_b32_e32 v212, 0xffff0000, v145
	v_add_f32_e32 v84, v84, v211
	v_add_f32_e32 v80, v80, v212
	v_cvt_pk_bf16_f32 v236, v92, v88
	v_cvt_pk_bf16_f32 v237, v84, v80
	v_mul_f32_e32 v92, v92, v92
	v_fmac_f32_e32 v92, v88, v88
	v_fmac_f32_e32 v92, v84, v84
	v_fmac_f32_e32 v92, v80, v80
	s_add_u32 s52, s38, 0x20000
	s_addc_u32 s53, s39, 0
	global_store_dwordx2 v208, v[236:237], s[52:53]
	s_waitcnt vmcnt(31)
	v_lshlrev_b32_e32 v211, 16, v146
	v_and_b32_e32 v212, 0xffff0000, v146
	v_add_f32_e32 v93, v93, v211
	v_add_f32_e32 v89, v89, v212
	v_lshlrev_b32_e32 v211, 16, v147
	v_and_b32_e32 v212, 0xffff0000, v147
	v_add_f32_e32 v85, v85, v211
	v_add_f32_e32 v81, v81, v212
	v_cvt_pk_bf16_f32 v238, v93, v89
	v_cvt_pk_bf16_f32 v239, v85, v81
	v_mul_f32_e32 v93, v93, v93
	v_fmac_f32_e32 v93, v89, v89
	v_fmac_f32_e32 v93, v85, v85
	v_fmac_f32_e32 v93, v81, v81
	s_add_u32 s54, s38, 0x21000
	s_addc_u32 s55, s39, 0
	global_store_dwordx2 v208, v[238:239], s[54:55]
	s_waitcnt vmcnt(31)
	v_lshlrev_b32_e32 v211, 16, v148
	v_and_b32_e32 v212, 0xffff0000, v148
	v_add_f32_e32 v94, v94, v211
	v_add_f32_e32 v90, v90, v212
	v_lshlrev_b32_e32 v211, 16, v149
	v_and_b32_e32 v212, 0xffff0000, v149
	v_add_f32_e32 v86, v86, v211
	v_add_f32_e32 v82, v82, v212
	v_cvt_pk_bf16_f32 v240, v94, v90
	v_cvt_pk_bf16_f32 v241, v86, v82
	v_mul_f32_e32 v94, v94, v94
	v_fmac_f32_e32 v94, v90, v90
	v_fmac_f32_e32 v94, v86, v86
	v_fmac_f32_e32 v94, v82, v82
	s_add_u32 s52, s38, 0x22000
	s_addc_u32 s53, s39, 0
	global_store_dwordx2 v208, v[240:241], s[52:53]
	s_waitcnt vmcnt(31)
	v_lshlrev_b32_e32 v211, 16, v150
	v_and_b32_e32 v212, 0xffff0000, v150
	v_add_f32_e32 v95, v95, v211
	v_add_f32_e32 v91, v91, v212
	v_lshlrev_b32_e32 v211, 16, v151
	v_and_b32_e32 v212, 0xffff0000, v151
	v_add_f32_e32 v87, v87, v211
	v_add_f32_e32 v83, v83, v212
	v_cvt_pk_bf16_f32 v242, v95, v91
	v_cvt_pk_bf16_f32 v243, v87, v83
	v_mul_f32_e32 v95, v95, v95
	v_fmac_f32_e32 v95, v91, v91
	v_fmac_f32_e32 v95, v87, v87
	v_fmac_f32_e32 v95, v83, v83
	s_add_u32 s54, s38, 0x23000
	s_addc_u32 s55, s39, 0
	global_store_dwordx2 v208, v[242:243], s[54:55]
	s_waitcnt vmcnt(31)
	v_lshlrev_b32_e32 v211, 16, v152
	v_and_b32_e32 v212, 0xffff0000, v152
	v_add_f32_e32 v76, v76, v211
	v_add_f32_e32 v72, v72, v212
	v_lshlrev_b32_e32 v211, 16, v153
	v_and_b32_e32 v212, 0xffff0000, v153
	v_add_f32_e32 v68, v68, v211
	v_add_f32_e32 v64, v64, v212
	v_cvt_pk_bf16_f32 v236, v76, v72
	v_cvt_pk_bf16_f32 v237, v68, v64
	v_mul_f32_e32 v76, v76, v76
	v_fmac_f32_e32 v76, v72, v72
	v_fmac_f32_e32 v76, v68, v68
	v_fmac_f32_e32 v76, v64, v64
	s_add_u32 s52, s38, 0x30000
	s_addc_u32 s53, s39, 0
	global_store_dwordx2 v208, v[236:237], s[52:53]
	s_waitcnt vmcnt(31)
	v_lshlrev_b32_e32 v211, 16, v154
	v_and_b32_e32 v212, 0xffff0000, v154
	v_add_f32_e32 v77, v77, v211
	v_add_f32_e32 v73, v73, v212
	v_lshlrev_b32_e32 v211, 16, v155
	v_and_b32_e32 v212, 0xffff0000, v155
	v_add_f32_e32 v69, v69, v211
	v_add_f32_e32 v65, v65, v212
	v_cvt_pk_bf16_f32 v238, v77, v73
	v_cvt_pk_bf16_f32 v239, v69, v65
	v_mul_f32_e32 v77, v77, v77
	v_fmac_f32_e32 v77, v73, v73
	v_fmac_f32_e32 v77, v69, v69
	v_fmac_f32_e32 v77, v65, v65
	s_add_u32 s54, s38, 0x31000
	s_addc_u32 s55, s39, 0
	global_store_dwordx2 v208, v[238:239], s[54:55]
	s_waitcnt vmcnt(31)
	v_lshlrev_b32_e32 v211, 16, v156
	v_and_b32_e32 v212, 0xffff0000, v156
	v_add_f32_e32 v78, v78, v211
	v_add_f32_e32 v74, v74, v212
	v_lshlrev_b32_e32 v211, 16, v157
	v_and_b32_e32 v212, 0xffff0000, v157
	v_add_f32_e32 v70, v70, v211
	v_add_f32_e32 v66, v66, v212
	v_cvt_pk_bf16_f32 v240, v78, v74
	v_cvt_pk_bf16_f32 v241, v70, v66
	v_mul_f32_e32 v78, v78, v78
	v_fmac_f32_e32 v78, v74, v74
	v_fmac_f32_e32 v78, v70, v70
	v_fmac_f32_e32 v78, v66, v66
	s_add_u32 s52, s38, 0x32000
	s_addc_u32 s53, s39, 0
	global_store_dwordx2 v208, v[240:241], s[52:53]
	s_waitcnt vmcnt(31)
	v_lshlrev_b32_e32 v211, 16, v158
	v_and_b32_e32 v212, 0xffff0000, v158
	v_add_f32_e32 v79, v79, v211
	v_add_f32_e32 v75, v75, v212
	v_lshlrev_b32_e32 v211, 16, v159
	v_and_b32_e32 v212, 0xffff0000, v159
	v_add_f32_e32 v71, v71, v211
	v_add_f32_e32 v67, v67, v212
	v_cvt_pk_bf16_f32 v242, v79, v75
	v_cvt_pk_bf16_f32 v243, v71, v67
	v_mul_f32_e32 v79, v79, v79
	v_fmac_f32_e32 v79, v75, v75
	v_fmac_f32_e32 v79, v71, v71
	v_fmac_f32_e32 v79, v67, v67
	s_add_u32 s54, s38, 0x33000
	s_addc_u32 s55, s39, 0
	global_store_dwordx2 v208, v[242:243], s[54:55]
	s_waitcnt vmcnt(31)
; __device__ __forceinline__ unsigned cvt_pk_bf16(float lo, float hi) { unsigned r; asm("v_cvt_pk_bf16_f32 %0, %1, %2" : "=v"(r) : "v"(lo), "v"(hi)); return r; }
;     __device__ __forceinline__ void operator()(const f32x4 (&acc)[2][2][4][2], const Unit& u, int wr, int wc, int fr, int fq, LAS unsigned char* xs, int wid, int lane) const {
;     ...
; #pragma unroll
;             for (int m = 0; m < 4; ++m) {
;                 const size_t row = (size_t)(row0 + ai * 128 + m * 16 + fr);
;                 float ss = 0.f;
; #pragma unroll
;                 for (int bj = 0; bj < 2; ++bj) {
;                     const size_t o = row * D + col0 + bj * 128;
;                     f32x4 x0, x1;
;                     if (SRCF32) { x0 = xf[m][bj][0]; x1 = xf[m][bj][1]; }
;                     else { const u32x4 r = raw[ai][m][bj]; x0 = (f32x4){bf_lo(r.x), bf_hi(r.x), bf_lo(r.y), bf_hi(r.y)}; x1 = (f32x4){bf_lo(r.z), bf_hi(r.z), bf_lo(r.w), bf_hi(r.w)}; }
;                     const f32x4 v0 = x0 + acc[ai][bj][m][0], v1 = x1 + acc[ai][bj][m][1];
;                     if (LAST) { *(f32x4*)(out + o) = v0; *(f32x4*)(out + o + 4) = v1; }
;                     else {
;                         ss += (v0[0] * v0[0] + v0[1] * v0[1]) + (v0[2] * v0[2] + v0[3] * v0[3]) + (v1[0] * v1[0] + v1[1] * v1[1]) + (v1[2] * v1[2] + v1[3] * v1[3]);
;                         u32x4 w; w.x = cvt_pk_bf16(v0[0], v0[1]); w.y = cvt_pk_bf16(v0[2], v0[3]); w.z = cvt_pk_bf16(v1[0], v1[1]); w.w = cvt_pk_bf16(v1[2], v1[3]); *(u32x4*)(xb + o) = w;
	v_lshlrev_b32_e32 v211, 16, v160
	v_and_b32_e32 v212, 0xffff0000, v160
	v_add_f32_e32 v60, v60, v211
	v_add_f32_e32 v56, v56, v212
	v_lshlrev_b32_e32 v211, 16, v161
	v_and_b32_e32 v212, 0xffff0000, v161
	v_add_f32_e32 v52, v52, v211
	v_add_f32_e32 v48, v48, v212
	v_cvt_pk_bf16_f32 v236, v60, v56
	v_cvt_pk_bf16_f32 v237, v52, v48
	v_mul_f32_e32 v60, v60, v60
	v_fmac_f32_e32 v60, v56, v56
	v_fmac_f32_e32 v60, v52, v52
	v_fmac_f32_e32 v60, v48, v48
	s_add_u32 s52, s38, 0x80000
	s_addc_u32 s53, s39, 0
	global_store_dwordx2 v208, v[236:237], s[52:53]
	s_waitcnt vmcnt(31)
	v_lshlrev_b32_e32 v211, 16, v162
	v_and_b32_e32 v212, 0xffff0000, v162
	v_add_f32_e32 v61, v61, v211
	v_add_f32_e32 v57, v57, v212
	v_lshlrev_b32_e32 v211, 16, v163
	v_and_b32_e32 v212, 0xffff0000, v163
	v_add_f32_e32 v53, v53, v211
	v_add_f32_e32 v49, v49, v212
	v_cvt_pk_bf16_f32 v238, v61, v57
	v_cvt_pk_bf16_f32 v239, v53, v49
	v_mul_f32_e32 v61, v61, v61
	v_fmac_f32_e32 v61, v57, v57
	v_fmac_f32_e32 v61, v53, v53
	v_fmac_f32_e32 v61, v49, v49
	s_add_u32 s54, s38, 0x81000
	s_addc_u32 s55, s39, 0
	global_store_dwordx2 v208, v[238:239], s[54:55]
	s_waitcnt vmcnt(31)
	v_lshlrev_b32_e32 v211, 16, v164
	v_and_b32_e32 v212, 0xffff0000, v164
	v_add_f32_e32 v62, v62, v211
	v_add_f32_e32 v58, v58, v212
	v_lshlrev_b32_e32 v211, 16, v165
	v_and_b32_e32 v212, 0xffff0000, v165
	v_add_f32_e32 v54, v54, v211
	v_add_f32_e32 v50, v50, v212
	v_cvt_pk_bf16_f32 v240, v62, v58
	v_cvt_pk_bf16_f32 v241, v54, v50
	v_mul_f32_e32 v62, v62, v62
	v_fmac_f32_e32 v62, v58, v58
	v_fmac_f32_e32 v62, v54, v54
	v_fmac_f32_e32 v62, v50, v50
	s_add_u32 s52, s38, 0x82000
	s_addc_u32 s53, s39, 0
	global_store_dwordx2 v208, v[240:241], s[52:53]
	s_waitcnt vmcnt(31)
	v_lshlrev_b32_e32 v211, 16, v166
	v_and_b32_e32 v212, 0xffff0000, v166
	v_add_f32_e32 v63, v63, v211
	v_add_f32_e32 v59, v59, v212
	v_lshlrev_b32_e32 v211, 16, v167
	v_and_b32_e32 v212, 0xffff0000, v167
	v_add_f32_e32 v55, v55, v211
	v_add_f32_e32 v51, v51, v212
	v_cvt_pk_bf16_f32 v242, v63, v59
	v_cvt_pk_bf16_f32 v243, v55, v51
	v_mul_f32_e32 v63, v63, v63
	v_fmac_f32_e32 v63, v59, v59
	v_fmac_f32_e32 v63, v55, v55
	v_fmac_f32_e32 v63, v51, v51
	s_add_u32 s54, s38, 0x83000
	s_addc_u32 s55, s39, 0
	global_store_dwordx2 v208, v[242:243], s[54:55]
	s_waitcnt vmcnt(31)
	v_lshlrev_b32_e32 v211, 16, v168
	v_and_b32_e32 v212, 0xffff0000, v168
	v_add_f32_e32 v44, v44, v211
	v_add_f32_e32 v40, v40, v212
	v_lshlrev_b32_e32 v211, 16, v169
	v_and_b32_e32 v212, 0xffff0000, v169
	v_add_f32_e32 v36, v36, v211
	v_add_f32_e32 v32, v32, v212
	v_cvt_pk_bf16_f32 v236, v44, v40
	v_cvt_pk_bf16_f32 v237, v36, v32
	v_mul_f32_e32 v44, v44, v44
	v_fmac_f32_e32 v44, v40, v40
	v_fmac_f32_e32 v44, v36, v36
	v_fmac_f32_e32 v44, v32, v32
	s_add_u32 s52, s38, 0x90000
	s_addc_u32 s53, s39, 0
	global_store_dwordx2 v208, v[236:237], s[52:53]
	s_waitcnt vmcnt(31)
	v_lshlrev_b32_e32 v211, 16, v170
	v_and_b32_e32 v212, 0xffff0000, v170
	v_add_f32_e32 v45, v45, v211
	v_add_f32_e32 v41, v41, v212
	v_lshlrev_b32_e32 v211, 16, v171
	v_and_b32_e32 v212, 0xffff0000, v171
	v_add_f32_e32 v37, v37, v211
	v_add_f32_e32 v33, v33, v212
	v_cvt_pk_bf16_f32 v238, v45, v41
	v_cvt_pk_bf16_f32 v239, v37, v33
	v_mul_f32_e32 v45, v45, v45
	v_fmac_f32_e32 v45, v41, v41
	v_fmac_f32_e32 v45, v37, v37
	v_fmac_f32_e32 v45, v33, v33
	s_add_u32 s54, s38, 0x91000
	s_addc_u32 s55, s39, 0
	global_store_dwordx2 v208, v[238:239], s[54:55]
	s_waitcnt vmcnt(31)
	v_lshlrev_b32_e32 v211, 16, v172
	v_and_b32_e32 v212, 0xffff0000, v172
	v_add_f32_e32 v46, v46, v211
	v_add_f32_e32 v42, v42, v212
	v_lshlrev_b32_e32 v211, 16, v173
	v_and_b32_e32 v212, 0xffff0000, v173
	v_add_f32_e32 v38, v38, v211
	v_add_f32_e32 v34, v34, v212
	v_cvt_pk_bf16_f32 v240, v46, v42
	v_cvt_pk_bf16_f32 v241, v38, v34
	v_mul_f32_e32 v46, v46, v46
	v_fmac_f32_e32 v46, v42, v42
	v_fmac_f32_e32 v46, v38, v38
	v_fmac_f32_e32 v46, v34, v34
	s_add_u32 s52, s38, 0x92000
	s_addc_u32 s53, s39, 0
	global_store_dwordx2 v208, v[240:241], s[52:53]
	s_waitcnt vmcnt(31)
	v_lshlrev_b32_e32 v211, 16, v174
	v_and_b32_e32 v212, 0xffff0000, v174
	v_add_f32_e32 v47, v47, v211
	v_add_f32_e32 v43, v43, v212
	v_lshlrev_b32_e32 v211, 16, v175
	v_and_b32_e32 v212, 0xffff0000, v175
	v_add_f32_e32 v39, v39, v211
	v_add_f32_e32 v35, v35, v212
	v_cvt_pk_bf16_f32 v242, v47, v43
	v_cvt_pk_bf16_f32 v243, v39, v35
	v_mul_f32_e32 v47, v47, v47
	v_fmac_f32_e32 v47, v43, v43
	v_fmac_f32_e32 v47, v39, v39
	v_fmac_f32_e32 v47, v35, v35
	s_add_u32 s54, s38, 0x93000
	s_addc_u32 s55, s39, 0
	global_store_dwordx2 v208, v[242:243], s[54:55]
	s_waitcnt vmcnt(31)
	v_lshlrev_b32_e32 v211, 16, v176
	v_and_b32_e32 v212, 0xffff0000, v176
	v_add_f32_e32 v28, v28, v211
	v_add_f32_e32 v24, v24, v212
	v_lshlrev_b32_e32 v211, 16, v177
	v_and_b32_e32 v212, 0xffff0000, v177
	v_add_f32_e32 v20, v20, v211
	v_add_f32_e32 v16, v16, v212
	v_cvt_pk_bf16_f32 v236, v28, v24
	v_cvt_pk_bf16_f32 v237, v20, v16
	v_mul_f32_e32 v28, v28, v28
	v_fmac_f32_e32 v28, v24, v24
	v_fmac_f32_e32 v28, v20, v20
	v_fmac_f32_e32 v28, v16, v16
	s_add_u32 s52, s38, 0xa0000
	s_addc_u32 s53, s39, 0
	global_store_dwordx2 v208, v[236:237], s[52:53]
	s_waitcnt vmcnt(31)
	v_lshlrev_b32_e32 v211, 16, v178
	v_and_b32_e32 v212, 0xffff0000, v178
	v_add_f32_e32 v29, v29, v211
	v_add_f32_e32 v25, v25, v212
	v_lshlrev_b32_e32 v211, 16, v179
	v_and_b32_e32 v212, 0xffff0000, v179
	v_add_f32_e32 v21, v21, v211
	v_add_f32_e32 v17, v17, v212
	v_cvt_pk_bf16_f32 v238, v29, v25
	v_cvt_pk_bf16_f32 v239, v21, v17
	v_mul_f32_e32 v29, v29, v29
	v_fmac_f32_e32 v29, v25, v25
	v_fmac_f32_e32 v29, v21, v21
	v_fmac_f32_e32 v29, v17, v17
	s_add_u32 s54, s38, 0xa1000
	s_addc_u32 s55, s39, 0
	global_store_dwordx2 v208, v[238:239], s[54:55]
	s_waitcnt vmcnt(31)
; __device__ __forceinline__ unsigned cvt_pk_bf16(float lo, float hi) { unsigned r; asm("v_cvt_pk_bf16_f32 %0, %1, %2" : "=v"(r) : "v"(lo), "v"(hi)); return r; }
;     __device__ __forceinline__ void operator()(const f32x4 (&acc)[2][2][4][2], const Unit& u, int wr, int wc, int fr, int fq, LAS unsigned char* xs, int wid, int lane) const {
;     ...
; #pragma unroll
;             for (int m = 0; m < 4; ++m) {
;                 const size_t row = (size_t)(row0 + ai * 128 + m * 16 + fr);
;                 float ss = 0.f;
; #pragma unroll
;                 for (int bj = 0; bj < 2; ++bj) {
;                     const size_t o = row * D + col0 + bj * 128;
;                     f32x4 x0, x1;
;                     if (SRCF32) { x0 = xf[m][bj][0]; x1 = xf[m][bj][1]; }
;                     else { const u32x4 r = raw[ai][m][bj]; x0 = (f32x4){bf_lo(r.x), bf_hi(r.x), bf_lo(r.y), bf_hi(r.y)}; x1 = (f32x4){bf_lo(r.z), bf_hi(r.z), bf_lo(r.w), bf_hi(r.w)}; }
;                     const f32x4 v0 = x0 + acc[ai][bj][m][0], v1 = x1 + acc[ai][bj][m][1];
;                     if (LAST) { *(f32x4*)(out + o) = v0; *(f32x4*)(out + o + 4) = v1; }
;                     else {
;                         ss += (v0[0] * v0[0] + v0[1] * v0[1]) + (v0[2] * v0[2] + v0[3] * v0[3]) + (v1[0] * v1[0] + v1[1] * v1[1]) + (v1[2] * v1[2] + v1[3] * v1[3]);
;                         u32x4 w; w.x = cvt_pk_bf16(v0[0], v0[1]); w.y = cvt_pk_bf16(v0[2], v0[3]); w.z = cvt_pk_bf16(v1[0], v1[1]); w.w = cvt_pk_bf16(v1[2], v1[3]); *(u32x4*)(xb + o) = w;
;                     }
;                 }
;                 if (!LAST) { ss += __shfl_xor(ss, 16); ss += __shfl_xor(ss, 32);
;                     if (fq == 0) P[(ai * 128 + wr * 64 + m * 16 + fr) * 4 + wc] = ss; }
	v_lshlrev_b32_e32 v211, 16, v180
	v_and_b32_e32 v212, 0xffff0000, v180
	v_add_f32_e32 v30, v30, v211
	v_add_f32_e32 v26, v26, v212
	v_lshlrev_b32_e32 v211, 16, v181
	v_and_b32_e32 v212, 0xffff0000, v181
	v_add_f32_e32 v22, v22, v211
	v_add_f32_e32 v18, v18, v212
	v_cvt_pk_bf16_f32 v240, v30, v26
	v_cvt_pk_bf16_f32 v241, v22, v18
	v_mul_f32_e32 v30, v30, v30
	v_fmac_f32_e32 v30, v26, v26
	v_fmac_f32_e32 v30, v22, v22
	v_fmac_f32_e32 v30, v18, v18
	s_add_u32 s52, s38, 0xa2000
	s_addc_u32 s53, s39, 0
	global_store_dwordx2 v208, v[240:241], s[52:53]
	s_waitcnt vmcnt(31)
	v_lshlrev_b32_e32 v211, 16, v182
	v_and_b32_e32 v212, 0xffff0000, v182
	v_add_f32_e32 v31, v31, v211
	v_add_f32_e32 v27, v27, v212
	v_lshlrev_b32_e32 v211, 16, v183
	v_and_b32_e32 v212, 0xffff0000, v183
	v_add_f32_e32 v23, v23, v211
	v_add_f32_e32 v19, v19, v212
	v_cvt_pk_bf16_f32 v242, v31, v27
	v_cvt_pk_bf16_f32 v243, v23, v19
	v_mul_f32_e32 v31, v31, v31
	v_fmac_f32_e32 v31, v27, v27
	v_fmac_f32_e32 v31, v23, v23
	v_fmac_f32_e32 v31, v19, v19
	s_add_u32 s54, s38, 0xa3000
	s_addc_u32 s55, s39, 0
	global_store_dwordx2 v208, v[242:243], s[54:55]
	s_waitcnt vmcnt(31)
	v_lshlrev_b32_e32 v211, 16, v200
	v_and_b32_e32 v212, 0xffff0000, v200
	v_add_f32_e32 v12, v12, v211
	v_add_f32_e32 v8, v8, v212
	v_lshlrev_b32_e32 v211, 16, v201
	v_and_b32_e32 v212, 0xffff0000, v201
	v_add_f32_e32 v4, v4, v211
	v_add_f32_e32 v0, v0, v212
	v_cvt_pk_bf16_f32 v236, v12, v8
	v_cvt_pk_bf16_f32 v237, v4, v0
	v_mul_f32_e32 v12, v12, v12
	v_fmac_f32_e32 v12, v8, v8
	v_fmac_f32_e32 v12, v4, v4
	v_fmac_f32_e32 v12, v0, v0
	s_add_u32 s52, s38, 0xb0000
	s_addc_u32 s53, s39, 0
	global_store_dwordx2 v208, v[236:237], s[52:53]
	s_waitcnt vmcnt(31)
	v_lshlrev_b32_e32 v211, 16, v202
	v_and_b32_e32 v212, 0xffff0000, v202
	v_add_f32_e32 v13, v13, v211
	v_add_f32_e32 v9, v9, v212
	v_lshlrev_b32_e32 v211, 16, v203
	v_and_b32_e32 v212, 0xffff0000, v203
	v_add_f32_e32 v5, v5, v211
	v_add_f32_e32 v1, v1, v212
	v_cvt_pk_bf16_f32 v238, v13, v9
	v_cvt_pk_bf16_f32 v239, v5, v1
	v_mul_f32_e32 v13, v13, v13
	v_fmac_f32_e32 v13, v9, v9
	v_fmac_f32_e32 v13, v5, v5
	v_fmac_f32_e32 v13, v1, v1
	s_add_u32 s54, s38, 0xb1000
	s_addc_u32 s55, s39, 0
	global_store_dwordx2 v208, v[238:239], s[54:55]
	s_waitcnt vmcnt(31)
	v_lshlrev_b32_e32 v211, 16, v204
	v_and_b32_e32 v212, 0xffff0000, v204
	v_add_f32_e32 v14, v14, v211
	v_add_f32_e32 v10, v10, v212
	v_lshlrev_b32_e32 v211, 16, v205
	v_and_b32_e32 v212, 0xffff0000, v205
	v_add_f32_e32 v6, v6, v211
	v_add_f32_e32 v2, v2, v212
	v_cvt_pk_bf16_f32 v240, v14, v10
	v_cvt_pk_bf16_f32 v241, v6, v2
	v_mul_f32_e32 v14, v14, v14
	v_fmac_f32_e32 v14, v10, v10
	v_fmac_f32_e32 v14, v6, v6
	v_fmac_f32_e32 v14, v2, v2
	s_add_u32 s52, s38, 0xb2000
	s_addc_u32 s53, s39, 0
	global_store_dwordx2 v208, v[240:241], s[52:53]
	s_waitcnt vmcnt(31)
	v_lshlrev_b32_e32 v211, 16, v206
	v_and_b32_e32 v212, 0xffff0000, v206
	v_add_f32_e32 v15, v15, v211
	v_add_f32_e32 v11, v11, v212
	v_lshlrev_b32_e32 v211, 16, v207
	v_and_b32_e32 v212, 0xffff0000, v207
	v_add_f32_e32 v7, v7, v211
	v_add_f32_e32 v3, v3, v212
	v_cvt_pk_bf16_f32 v242, v15, v11
	v_cvt_pk_bf16_f32 v243, v7, v3
	v_mul_f32_e32 v15, v15, v15
	v_fmac_f32_e32 v15, v11, v11
	v_fmac_f32_e32 v15, v7, v7
	v_fmac_f32_e32 v15, v3, v3
	s_add_u32 s54, s38, 0xb3000
	s_addc_u32 s55, s39, 0
	global_store_dwordx2 v208, v[242:243], s[54:55]
	v_add_f32_dpp v136, v136, v136 quad_perm:[1,0,3,2] row_mask:0xf bank_mask:0xf
	v_add_f32_dpp v137, v137, v137 quad_perm:[1,0,3,2] row_mask:0xf bank_mask:0xf
	v_add_f32_dpp v138, v138, v138 quad_perm:[1,0,3,2] row_mask:0xf bank_mask:0xf
	v_add_f32_dpp v139, v139, v139 quad_perm:[1,0,3,2] row_mask:0xf bank_mask:0xf
	v_add_f32_dpp v136, v136, v136 quad_perm:[2,3,0,1] row_mask:0xf bank_mask:0xf
	v_add_f32_dpp v137, v137, v137 quad_perm:[2,3,0,1] row_mask:0xf bank_mask:0xf
	v_add_f32_dpp v138, v138, v138 quad_perm:[2,3,0,1] row_mask:0xf bank_mask:0xf
	v_add_f32_dpp v139, v139, v139 quad_perm:[2,3,0,1] row_mask:0xf bank_mask:0xf
	v_add_f32_dpp v136, v136, v136 row_half_mirror row_mask:0xf bank_mask:0xf
	v_add_f32_dpp v137, v137, v137 row_half_mirror row_mask:0xf bank_mask:0xf
	v_add_f32_dpp v138, v138, v138 row_half_mirror row_mask:0xf bank_mask:0xf
	v_add_f32_dpp v139, v139, v139 row_half_mirror row_mask:0xf bank_mask:0xf
	v_add_f32_dpp v136, v136, v136 row_mirror row_mask:0xf bank_mask:0xf
	v_add_f32_dpp v137, v137, v137 row_mirror row_mask:0xf bank_mask:0xf
	v_add_f32_dpp v138, v138, v138 row_mirror row_mask:0xf bank_mask:0xf
	v_add_f32_dpp v139, v139, v139 row_mirror row_mask:0xf bank_mask:0xf
	v_add_f32_dpp v116, v116, v116 quad_perm:[1,0,3,2] row_mask:0xf bank_mask:0xf
	v_add_f32_dpp v117, v117, v117 quad_perm:[1,0,3,2] row_mask:0xf bank_mask:0xf
	v_add_f32_dpp v118, v118, v118 quad_perm:[1,0,3,2] row_mask:0xf bank_mask:0xf
	v_add_f32_dpp v119, v119, v119 quad_perm:[1,0,3,2] row_mask:0xf bank_mask:0xf
	v_add_f32_dpp v116, v116, v116 quad_perm:[2,3,0,1] row_mask:0xf bank_mask:0xf
	v_add_f32_dpp v117, v117, v117 quad_perm:[2,3,0,1] row_mask:0xf bank_mask:0xf
	v_add_f32_dpp v118, v118, v118 quad_perm:[2,3,0,1] row_mask:0xf bank_mask:0xf
	v_add_f32_dpp v119, v119, v119 quad_perm:[2,3,0,1] row_mask:0xf bank_mask:0xf
	v_add_f32_dpp v116, v116, v116 row_half_mirror row_mask:0xf bank_mask:0xf
	v_add_f32_dpp v117, v117, v117 row_half_mirror row_mask:0xf bank_mask:0xf
	v_add_f32_dpp v118, v118, v118 row_half_mirror row_mask:0xf bank_mask:0xf
	v_add_f32_dpp v119, v119, v119 row_half_mirror row_mask:0xf bank_mask:0xf
	v_add_f32_dpp v116, v116, v116 row_mirror row_mask:0xf bank_mask:0xf
	v_add_f32_dpp v117, v117, v117 row_mirror row_mask:0xf bank_mask:0xf
;     __device__ __forceinline__ void operator()(const f32x4 (&acc)[2][2][4][2], const Unit& u, int wr, int wc, int fr, int fq, LAS unsigned char* xs, int wid, int lane) const {
;     ...
;                 if (!LAST) { ss += __shfl_xor(ss, 16); ss += __shfl_xor(ss, 32);
;                     if (fq == 0) P[(ai * 128 + wr * 64 + m * 16 + fr) * 4 + wc] = ss; }
	v_add_f32_dpp v118, v118, v118 row_mirror row_mask:0xf bank_mask:0xf
	v_add_f32_dpp v119, v119, v119 row_mirror row_mask:0xf bank_mask:0xf
	v_add_f32_dpp v92, v92, v92 quad_perm:[1,0,3,2] row_mask:0xf bank_mask:0xf
	v_add_f32_dpp v93, v93, v93 quad_perm:[1,0,3,2] row_mask:0xf bank_mask:0xf
	v_add_f32_dpp v94, v94, v94 quad_perm:[1,0,3,2] row_mask:0xf bank_mask:0xf
	v_add_f32_dpp v95, v95, v95 quad_perm:[1,0,3,2] row_mask:0xf bank_mask:0xf
	v_add_f32_dpp v92, v92, v92 quad_perm:[2,3,0,1] row_mask:0xf bank_mask:0xf
	v_add_f32_dpp v93, v93, v93 quad_perm:[2,3,0,1] row_mask:0xf bank_mask:0xf
	v_add_f32_dpp v94, v94, v94 quad_perm:[2,3,0,1] row_mask:0xf bank_mask:0xf
	v_add_f32_dpp v95, v95, v95 quad_perm:[2,3,0,1] row_mask:0xf bank_mask:0xf
	v_add_f32_dpp v92, v92, v92 row_half_mirror row_mask:0xf bank_mask:0xf
	v_add_f32_dpp v93, v93, v93 row_half_mirror row_mask:0xf bank_mask:0xf
	v_add_f32_dpp v94, v94, v94 row_half_mirror row_mask:0xf bank_mask:0xf
	v_add_f32_dpp v95, v95, v95 row_half_mirror row_mask:0xf bank_mask:0xf
	v_add_f32_dpp v92, v92, v92 row_mirror row_mask:0xf bank_mask:0xf
	v_add_f32_dpp v93, v93, v93 row_mirror row_mask:0xf bank_mask:0xf
	v_add_f32_dpp v94, v94, v94 row_mirror row_mask:0xf bank_mask:0xf
	v_add_f32_dpp v95, v95, v95 row_mirror row_mask:0xf bank_mask:0xf
	v_add_f32_dpp v76, v76, v76 quad_perm:[1,0,3,2] row_mask:0xf bank_mask:0xf
	v_add_f32_dpp v77, v77, v77 quad_perm:[1,0,3,2] row_mask:0xf bank_mask:0xf
	v_add_f32_dpp v78, v78, v78 quad_perm:[1,0,3,2] row_mask:0xf bank_mask:0xf
	v_add_f32_dpp v79, v79, v79 quad_perm:[1,0,3,2] row_mask:0xf bank_mask:0xf
	v_add_f32_dpp v76, v76, v76 quad_perm:[2,3,0,1] row_mask:0xf bank_mask:0xf
	v_add_f32_dpp v77, v77, v77 quad_perm:[2,3,0,1] row_mask:0xf bank_mask:0xf
	v_add_f32_dpp v78, v78, v78 quad_perm:[2,3,0,1] row_mask:0xf bank_mask:0xf
	v_add_f32_dpp v79, v79, v79 quad_perm:[2,3,0,1] row_mask:0xf bank_mask:0xf
	v_add_f32_dpp v76, v76, v76 row_half_mirror row_mask:0xf bank_mask:0xf
	v_add_f32_dpp v77, v77, v77 row_half_mirror row_mask:0xf bank_mask:0xf
	v_add_f32_dpp v78, v78, v78 row_half_mirror row_mask:0xf bank_mask:0xf
	v_add_f32_dpp v79, v79, v79 row_half_mirror row_mask:0xf bank_mask:0xf
	v_add_f32_dpp v76, v76, v76 row_mirror row_mask:0xf bank_mask:0xf
	v_add_f32_dpp v77, v77, v77 row_mirror row_mask:0xf bank_mask:0xf
	v_add_f32_dpp v78, v78, v78 row_mirror row_mask:0xf bank_mask:0xf
	v_add_f32_dpp v79, v79, v79 row_mirror row_mask:0xf bank_mask:0xf
	v_add_f32_dpp v60, v60, v60 quad_perm:[1,0,3,2] row_mask:0xf bank_mask:0xf
	v_add_f32_dpp v61, v61, v61 quad_perm:[1,0,3,2] row_mask:0xf bank_mask:0xf
	v_add_f32_dpp v62, v62, v62 quad_perm:[1,0,3,2] row_mask:0xf bank_mask:0xf
	v_add_f32_dpp v63, v63, v63 quad_perm:[1,0,3,2] row_mask:0xf bank_mask:0xf
	v_add_f32_dpp v60, v60, v60 quad_perm:[2,3,0,1] row_mask:0xf bank_mask:0xf
	v_add_f32_dpp v61, v61, v61 quad_perm:[2,3,0,1] row_mask:0xf bank_mask:0xf
	v_add_f32_dpp v62, v62, v62 quad_perm:[2,3,0,1] row_mask:0xf bank_mask:0xf
	v_add_f32_dpp v63, v63, v63 quad_perm:[2,3,0,1] row_mask:0xf bank_mask:0xf
	v_add_f32_dpp v60, v60, v60 row_half_mirror row_mask:0xf bank_mask:0xf
	v_add_f32_dpp v61, v61, v61 row_half_mirror row_mask:0xf bank_mask:0xf
	v_add_f32_dpp v62, v62, v62 row_half_mirror row_mask:0xf bank_mask:0xf
	v_add_f32_dpp v63, v63, v63 row_half_mirror row_mask:0xf bank_mask:0xf
	v_add_f32_dpp v60, v60, v60 row_mirror row_mask:0xf bank_mask:0xf
	v_add_f32_dpp v61, v61, v61 row_mirror row_mask:0xf bank_mask:0xf
	v_add_f32_dpp v62, v62, v62 row_mirror row_mask:0xf bank_mask:0xf
	v_add_f32_dpp v63, v63, v63 row_mirror row_mask:0xf bank_mask:0xf
	v_add_f32_dpp v44, v44, v44 quad_perm:[1,0,3,2] row_mask:0xf bank_mask:0xf
	v_add_f32_dpp v45, v45, v45 quad_perm:[1,0,3,2] row_mask:0xf bank_mask:0xf
	v_add_f32_dpp v46, v46, v46 quad_perm:[1,0,3,2] row_mask:0xf bank_mask:0xf
	v_add_f32_dpp v47, v47, v47 quad_perm:[1,0,3,2] row_mask:0xf bank_mask:0xf
	v_add_f32_dpp v44, v44, v44 quad_perm:[2,3,0,1] row_mask:0xf bank_mask:0xf
	v_add_f32_dpp v45, v45, v45 quad_perm:[2,3,0,1] row_mask:0xf bank_mask:0xf
	v_add_f32_dpp v46, v46, v46 quad_perm:[2,3,0,1] row_mask:0xf bank_mask:0xf
	v_add_f32_dpp v47, v47, v47 quad_perm:[2,3,0,1] row_mask:0xf bank_mask:0xf
	v_add_f32_dpp v44, v44, v44 row_half_mirror row_mask:0xf bank_mask:0xf
	v_add_f32_dpp v45, v45, v45 row_half_mirror row_mask:0xf bank_mask:0xf
	v_add_f32_dpp v46, v46, v46 row_half_mirror row_mask:0xf bank_mask:0xf
	v_add_f32_dpp v47, v47, v47 row_half_mirror row_mask:0xf bank_mask:0xf
; #define LAS __attribute__((address_space(3)))
; #define LDS_WAIT() asm volatile("s_waitcnt lgkmcnt(0)" ::: "memory")
;     __device__ __forceinline__ void operator()(const f32x4 (&acc)[2][2][4][2], const Unit& u, int wr, int wc, int fr, int fq, LAS unsigned char* xs, int wid, int lane) const {
;     ...
;                 if (!LAST) { ss += __shfl_xor(ss, 16); ss += __shfl_xor(ss, 32);
;                     if (fq == 0) P[(ai * 128 + wr * 64 + m * 16 + fr) * 4 + wc] = ss; }
;             }
;             if (SRCF32) __builtin_amdgcn_sched_barrier(0);
;         }
;         if (!LAST) {
;             LDS_WAIT();
;             __builtin_amdgcn_s_barrier();
;             const int tid = wid * 64 + lane;
;             if (tid < 256) { const f32x4 v = *(const LAS f32x4*)(P + tid * 4); rss[(size_t)(u.pm * 256 + tid) * 8 + u.pn] = (v[0] + v[1]) + (v[2] + v[3]); }
;             LDS_WAIT();
	v_add_f32_dpp v44, v44, v44 row_mirror row_mask:0xf bank_mask:0xf
	v_add_f32_dpp v45, v45, v45 row_mirror row_mask:0xf bank_mask:0xf
	v_add_f32_dpp v46, v46, v46 row_mirror row_mask:0xf bank_mask:0xf
	v_add_f32_dpp v47, v47, v47 row_mirror row_mask:0xf bank_mask:0xf
	v_add_f32_dpp v28, v28, v28 quad_perm:[1,0,3,2] row_mask:0xf bank_mask:0xf
	v_add_f32_dpp v29, v29, v29 quad_perm:[1,0,3,2] row_mask:0xf bank_mask:0xf
	v_add_f32_dpp v30, v30, v30 quad_perm:[1,0,3,2] row_mask:0xf bank_mask:0xf
	v_add_f32_dpp v31, v31, v31 quad_perm:[1,0,3,2] row_mask:0xf bank_mask:0xf
	v_add_f32_dpp v28, v28, v28 quad_perm:[2,3,0,1] row_mask:0xf bank_mask:0xf
	v_add_f32_dpp v29, v29, v29 quad_perm:[2,3,0,1] row_mask:0xf bank_mask:0xf
	v_add_f32_dpp v30, v30, v30 quad_perm:[2,3,0,1] row_mask:0xf bank_mask:0xf
	v_add_f32_dpp v31, v31, v31 quad_perm:[2,3,0,1] row_mask:0xf bank_mask:0xf
	v_add_f32_dpp v28, v28, v28 row_half_mirror row_mask:0xf bank_mask:0xf
	v_add_f32_dpp v29, v29, v29 row_half_mirror row_mask:0xf bank_mask:0xf
	v_add_f32_dpp v30, v30, v30 row_half_mirror row_mask:0xf bank_mask:0xf
	v_add_f32_dpp v31, v31, v31 row_half_mirror row_mask:0xf bank_mask:0xf
	v_add_f32_dpp v28, v28, v28 row_mirror row_mask:0xf bank_mask:0xf
	v_add_f32_dpp v29, v29, v29 row_mirror row_mask:0xf bank_mask:0xf
	v_add_f32_dpp v30, v30, v30 row_mirror row_mask:0xf bank_mask:0xf
	v_add_f32_dpp v31, v31, v31 row_mirror row_mask:0xf bank_mask:0xf
	v_add_f32_dpp v12, v12, v12 quad_perm:[1,0,3,2] row_mask:0xf bank_mask:0xf
	v_add_f32_dpp v13, v13, v13 quad_perm:[1,0,3,2] row_mask:0xf bank_mask:0xf
	v_add_f32_dpp v14, v14, v14 quad_perm:[1,0,3,2] row_mask:0xf bank_mask:0xf
	v_add_f32_dpp v15, v15, v15 quad_perm:[1,0,3,2] row_mask:0xf bank_mask:0xf
	v_add_f32_dpp v12, v12, v12 quad_perm:[2,3,0,1] row_mask:0xf bank_mask:0xf
	v_add_f32_dpp v13, v13, v13 quad_perm:[2,3,0,1] row_mask:0xf bank_mask:0xf
	v_add_f32_dpp v14, v14, v14 quad_perm:[2,3,0,1] row_mask:0xf bank_mask:0xf
	v_add_f32_dpp v15, v15, v15 quad_perm:[2,3,0,1] row_mask:0xf bank_mask:0xf
	v_add_f32_dpp v12, v12, v12 row_half_mirror row_mask:0xf bank_mask:0xf
	v_add_f32_dpp v13, v13, v13 row_half_mirror row_mask:0xf bank_mask:0xf
	v_add_f32_dpp v14, v14, v14 row_half_mirror row_mask:0xf bank_mask:0xf
	v_add_f32_dpp v15, v15, v15 row_half_mirror row_mask:0xf bank_mask:0xf
	v_add_f32_dpp v12, v12, v12 row_mirror row_mask:0xf bank_mask:0xf
	v_add_f32_dpp v13, v13, v13 row_mirror row_mask:0xf bank_mask:0xf
	v_add_f32_dpp v14, v14, v14 row_mirror row_mask:0xf bank_mask:0xf
	v_add_f32_dpp v15, v15, v15 row_mirror row_mask:0xf bank_mask:0xf
	s_mov_b32 exec_lo, 0x10001
	s_mov_b32 exec_hi, 0x10001
	ds_write_b32 v213, v136 offset:0
	ds_write_b32 v213, v137 offset:16
	ds_write_b32 v213, v138 offset:32
	ds_write_b32 v213, v139 offset:48
	ds_write_b32 v213, v116 offset:256
	ds_write_b32 v213, v117 offset:272
	ds_write_b32 v213, v118 offset:288
	ds_write_b32 v213, v119 offset:304
	ds_write_b32 v213, v92 offset:512
	ds_write_b32 v213, v93 offset:528
	ds_write_b32 v213, v94 offset:544
	ds_write_b32 v213, v95 offset:560
	ds_write_b32 v213, v76 offset:768
	ds_write_b32 v213, v77 offset:784
	ds_write_b32 v213, v78 offset:800
	ds_write_b32 v213, v79 offset:816
	ds_write_b32 v213, v60 offset:2048
	ds_write_b32 v213, v61 offset:2064
	ds_write_b32 v213, v62 offset:2080
	ds_write_b32 v213, v63 offset:2096
	ds_write_b32 v213, v44 offset:2304
	ds_write_b32 v213, v45 offset:2320
	ds_write_b32 v213, v46 offset:2336
	ds_write_b32 v213, v47 offset:2352
	ds_write_b32 v213, v28 offset:2560
	ds_write_b32 v213, v29 offset:2576
	ds_write_b32 v213, v30 offset:2592
	ds_write_b32 v213, v31 offset:2608
	ds_write_b32 v213, v12 offset:2816
	ds_write_b32 v213, v13 offset:2832
	ds_write_b32 v213, v14 offset:2848
	ds_write_b32 v213, v15 offset:2864
	s_mov_b64 exec, -1
	s_waitcnt lgkmcnt(0)
	s_barrier
	v_cmp_gt_u32_e32 vcc, 0x100, v254
	s_and_saveexec_b64 s[52:53], vcc
	v_lshlrev_b32_e32 v211, 4, v254
	v_add_u32_e32 v211, 0x20000, v211
	ds_read_b128 v[236:239], v211
	v_add_u32_e32 v212, s41, v254
	v_lshlrev_b32_e32 v212, 5, v212
	s_lshl_b32 s25, s16, 2
	v_add_u32_e32 v212, s25, v212
	s_waitcnt lgkmcnt(0)
	v_add_f32_e32 v236, v236, v237
	v_add_f32_e32 v238, v238, v239
	v_add_f32_e32 v236, v236, v238
	global_store_dword v212, v236, s[44:45]
	s_or_b64 exec, exec, s[52:53]
	s_andn2_b64 vcc, exec, s[12:13]
	s_mov_b64 s[12:13], -1
	s_cbranch_vccnz .LBB0_1364
	s_andn2_b64 vcc, exec, s[18:19]
	s_cbranch_vccnz .LBB0_1363
	s_barrier
	s_branch .LBB0_1363
